# static priority raise for waves 4-7 during unit-boundary code (epilogue + unit top), reset before the K-loop
# speedup vs baseline: 1.0175x; 1.0175x over previous
; #define PG8_STAGE(bufoff, gbase, voff) do { _Pragma("unroll") for (int _i = 0; _i < 2; ++_i) \
;         __builtin_amdgcn_global_load_lds((const unsigned*)((const char*)(gbase) + (voff)[_i]), (LAS unsigned*)(lds + (bufoff) + ldsw + _i * 8192), 16, 0, 0); } while (0)
; #define PG8_LDA(dst, b, h) do { _Pragma("unroll") for (int m = 0; m < 4; ++m) _Pragma("unroll") for (int k = 0; k < 2; ++k) dst[m][k] = *(const LAS bf16x8*)(lds + PG8_SA(b, h) + aoff + m * 2048 + k * 1024); } while (0)
; #define PG8_LDB(dst, b, h) do { _Pragma("unroll") for (int n = 0; n < 2; ++n) _Pragma("unroll") for (int k = 0; k < 2; ++k) dst[n][k] = *(const LAS bf16x8*)(lds + PG8_SB(b, h) + boff + n * 2048 + k * 1024); } while (0)
; #define PG8_MMA(ai, bj, At, Bt) do { __builtin_amdgcn_s_setprio(1); _Pragma("unroll") for (int m = 0; m < 4; ++m) _Pragma("unroll") for (int n = 0; n < 2; ++n) _Pragma("unroll") for (int k = 0; k < 2; ++k) \
;         acc[ai][bj][m][n] = __builtin_amdgcn_mfma_f32_16x16x32_bf16(Bt[n][k], At[m][k], acc[ai][bj][m][n], 0, 0, 0); __builtin_amdgcn_s_setprio(0); } while (0)
; #define PG8_WAIT_L(n) asm volatile("s_waitcnt lgkmcnt(" #n ")" ::: "memory")
; #define PG8_BAR __builtin_amdgcn_s_barrier()
; #define PG8_SCHED __builtin_amdgcn_sched_barrier(0)
; template <class Epi>
; __device__ __forceinline__ void gemm_phase(LAS unsigned char* lds, const Gemm g, const Sched& S, const Epi& E) {
;     ...
;         for (int t = 0; t < nt; t += 2) {
;             const bool last = (t == nt - 2);
;             const char* a1 = cA + (size_t)(t + 1) * kstep;
;             const char* a2 = last ? nA : cA + (size_t)(t + 2) * kstep; const char* b2 = last ? nB : cB + (size_t)(t + 2) * kstep;
;             const char* a3 = a2 + kstep; const char* b3 = b2 + kstep;
;             PG8_LDB(B0, 0, 0); PG8_SCHED; PG8_LDA(At, 0, 0); PG8_STAGE(PG8_SA(1, 1), a1 + hstepA, voffA);
;             PG8_WAIT_L(8); PG8_BAR; PG8_WAIT_L(0); PG8_MMA(0, 0, At, B0); PG8_BAR; PG8_SCHED;
;     ...
; #pragma unroll
;         for (int a = 0; a < 2; ++a)
; #pragma unroll
;             for (int b = 0; b < 2; ++b)
; #pragma unroll
;                 for (int m = 0; m < 4; ++m)
; #pragma unroll
;                     for (int n = 0; n < 2; ++n) acc[a][b][m][n] = (f32x4){0.f, 0.f, 0.f, 0.f};
;         cur = nxt; cA = nA; cB = nB; ++ui;
.LBB0_399:
	v_mov_b64_e32 v[2:3], s[26:27]
	v_readlane_b32 s8, v254, 11
	v_cmp_lt_i64_e32 vcc, s[88:89], v[2:3]
	v_readlane_b32 s9, v254, 12
	s_add_u32 s88, s8, s84
	s_addc_u32 s89, s9, s85
	s_and_b64 s[14:15], vcc, exec
	s_cselect_b32 s55, s89, s93
	s_cselect_b32 s57, s88, s92
	s_add_u32 s90, s10, s86
	s_addc_u32 s91, s11, s87
	s_and_b64 s[14:15], vcc, exec
	s_cselect_b32 s59, s91, s95
	s_cselect_b32 s65, s90, s94
	s_add_u32 s92, s92, 0x80
	s_addc_u32 s93, s93, 0
	s_add_u32 s34, s94, 0x100
	v_mov_b32_e32 v2, 0
	s_addc_u32 s35, s95, 0
	s_mov_b32 s66, 0
	v_mov_b32_e32 v3, v2
	v_mov_b32_e32 v4, v2
	v_mov_b32_e32 v5, v2
	v_mov_b32_e32 v6, v2
	v_mov_b32_e32 v7, v2
	v_mov_b32_e32 v8, v2
	v_mov_b32_e32 v9, v2
	v_mov_b32_e32 v14, v2
	v_mov_b32_e32 v15, v2
	v_mov_b32_e32 v16, v2
	v_mov_b32_e32 v17, v2
	v_mov_b32_e32 v22, v2
	v_mov_b32_e32 v23, v2
	v_mov_b32_e32 v24, v2
	v_mov_b32_e32 v25, v2
	v_mov_b32_e32 v30, v2
	v_mov_b32_e32 v31, v2
	v_mov_b32_e32 v32, v2
	v_mov_b32_e32 v33, v2
	v_mov_b32_e32 v38, v2
	v_mov_b32_e32 v39, v2
	v_mov_b32_e32 v40, v2
	v_mov_b32_e32 v41, v2
	v_mov_b32_e32 v46, v2
	s_waitcnt lgkmcnt(0)
	v_mov_b32_e32 v47, v2
	v_mov_b32_e32 v48, v2
	v_mov_b32_e32 v49, v2
	v_mov_b32_e32 v54, v2
	v_mov_b32_e32 v55, v2
	v_mov_b32_e32 v56, v2
	v_mov_b32_e32 v57, v2
	v_mov_b32_e32 v10, v2
	v_mov_b32_e32 v11, v2
	v_mov_b32_e32 v12, v2
	v_mov_b32_e32 v13, v2
	v_mov_b32_e32 v18, v2
	v_mov_b32_e32 v19, v2
	v_mov_b32_e32 v20, v2
	v_mov_b32_e32 v21, v2
	v_mov_b32_e32 v26, v2
	v_mov_b32_e32 v27, v2
	v_mov_b32_e32 v28, v2
	v_mov_b32_e32 v29, v2
	v_mov_b32_e32 v34, v2
	v_mov_b32_e32 v35, v2
	v_mov_b32_e32 v36, v2
	v_mov_b32_e32 v37, v2
	v_mov_b32_e32 v42, v2
	v_mov_b32_e32 v43, v2
	v_mov_b32_e32 v44, v2
	v_mov_b32_e32 v45, v2
	v_mov_b32_e32 v50, v2
	v_mov_b32_e32 v51, v2
	v_mov_b32_e32 v52, v2
	v_mov_b32_e32 v53, v2
	v_mov_b32_e32 v58, v2
	v_mov_b32_e32 v59, v2
	v_mov_b32_e32 v60, v2
	v_mov_b32_e32 v61, v2
	v_mov_b32_e32 v62, v2
	v_mov_b32_e32 v63, v2
	v_mov_b32_e32 v64, v2
	v_mov_b32_e32 v65, v2
	v_mov_b32_e32 v66, v2
	v_mov_b32_e32 v67, v2
	v_mov_b32_e32 v68, v2
	v_mov_b32_e32 v69, v2
	v_mov_b32_e32 v70, v2
	v_mov_b32_e32 v71, v2
	v_mov_b32_e32 v72, v2
	v_mov_b32_e32 v73, v2
	v_mov_b32_e32 v82, v2
	v_mov_b32_e32 v83, v2
	v_mov_b32_e32 v84, v2
	v_mov_b32_e32 v85, v2
	v_mov_b32_e32 v86, v2
	v_mov_b32_e32 v87, v2
	v_mov_b32_e32 v88, v2
	v_mov_b32_e32 v89, v2
	v_mov_b32_e32 v98, v2
	v_mov_b32_e32 v99, v2
	v_mov_b32_e32 v100, v2
	v_mov_b32_e32 v101, v2
	v_mov_b32_e32 v102, v2
	v_mov_b32_e32 v103, v2
	v_mov_b32_e32 v104, v2
	v_mov_b32_e32 v105, v2
	v_mov_b32_e32 v114, v2
	v_mov_b32_e32 v115, v2
	v_mov_b32_e32 v116, v2
	v_mov_b32_e32 v117, v2
	v_mov_b32_e32 v118, v2
	v_mov_b32_e32 v119, v2
	v_mov_b32_e32 v120, v2
	v_mov_b32_e32 v121, v2
	v_mov_b32_e32 v74, v2
	v_mov_b32_e32 v75, v2
	v_mov_b32_e32 v76, v2
	v_mov_b32_e32 v77, v2
	v_mov_b32_e32 v78, v2
	v_mov_b32_e32 v79, v2
	v_mov_b32_e32 v80, v2
	v_mov_b32_e32 v81, v2
	v_mov_b32_e32 v90, v2
	v_mov_b32_e32 v91, v2
	v_mov_b32_e32 v92, v2
	v_mov_b32_e32 v93, v2
	v_mov_b32_e32 v94, v2
	v_mov_b32_e32 v95, v2
	v_mov_b32_e32 v96, v2
	v_mov_b32_e32 v97, v2
	v_mov_b32_e32 v106, v2
	v_mov_b32_e32 v107, v2
	v_mov_b32_e32 v108, v2
	v_mov_b32_e32 v109, v2
	v_mov_b32_e32 v110, v2
	v_mov_b32_e32 v111, v2
	v_mov_b32_e32 v112, v2
	v_mov_b32_e32 v113, v2
	v_mov_b32_e32 v122, v2
	v_mov_b32_e32 v123, v2
	v_mov_b32_e32 v124, v2
	v_mov_b32_e32 v125, v2
	v_mov_b32_e32 v126, v2
	v_mov_b32_e32 v127, v2
	v_mov_b32_e32 v128, v2
	v_mov_b32_e32 v129, v2
	v_readfirstlane_b32 s98, v219
	s_nop 1
	s_bitcmp1_b32 s98, 8
	s_cbranch_scc0 .Lresync_y_400
	s_setprio 0
	s_barrier
.Lresync_y_400:
.LBB0_400:
	s_add_i32 s14, s66, 2
	s_add_u32 s8, s92, 0x80
	s_addc_u32 s9, s93, 0
	s_add_i32 s15, 0, 0x10000
	v_add_u32_e32 v148, s15, v152
	ds_read_b128 v[144:147], v148
	ds_read_b128 v[172:175], v148 offset:1024
	ds_read_b128 v[176:179], v148 offset:2048
	ds_read_b128 v[180:183], v148 offset:3072
	s_cmp_eq_u32 s71, s66
	s_cselect_b32 s95, s55, s9
	s_cselect_b32 s94, s57, s8
	s_cselect_b32 s97, s59, s35
	s_cselect_b32 s96, s65, s34
	v_lshl_add_u64 v[148:149], s[92:93], 0, v[138:139]
	s_add_i32 m0, s42, 0xc000
	ds_read_b128 v[184:187], v171
	ds_read_b128 v[188:191], v171 offset:1024
	ds_read_b128 v[196:199], v171 offset:2048
	ds_read_b128 v[200:203], v171 offset:3072
	ds_read_b128 v[204:207], v171 offset:4096
	ds_read_b128 v[208:211], v171 offset:5120
	ds_read_b128 v[212:215], v171 offset:6144
	ds_read_b128 v[222:225], v171 offset:7168
	global_load_lds_dwordx4 v[148:149], off
	v_lshl_add_u64 v[148:149], s[92:93], 0, v[140:141]
	s_add_i32 m0, s42, 0xe000
	s_nop 0
	global_load_lds_dwordx4 v[148:149], off
	s_add_i32 s8, 0, 0x14000
	v_add_u32_e32 v148, s8, v152
	ds_read_b128 v[226:229], v148
	ds_read_b128 v[230:233], v148 offset:1024
	ds_read_b128 v[234:237], v148 offset:2048
	ds_read_b128 v[238:241], v148 offset:3072
	s_waitcnt vmcnt(8)
	s_waitcnt lgkmcnt(0)
	v_mfma_f32_16x16x32_bf16 v[126:129], v[144:147], v[184:187], v[126:129]
	v_mfma_f32_16x16x32_bf16 v[122:125], v[176:179], v[184:187], v[122:125]
	v_mfma_f32_16x16x32_bf16 v[110:113], v[144:147], v[196:199], v[110:113]
	v_mfma_f32_16x16x32_bf16 v[106:109], v[176:179], v[196:199], v[106:109]
	s_barrier
; #define PG8_STAGE(bufoff, gbase, voff) do { _Pragma("unroll") for (int _i = 0; _i < 2; ++_i) \
;         __builtin_amdgcn_global_load_lds((const unsigned*)((const char*)(gbase) + (voff)[_i]), (LAS unsigned*)(lds + (bufoff) + ldsw + _i * 8192), 16, 0, 0); } while (0)
; #define PG8_LDA(dst, b, h) do { _Pragma("unroll") for (int m = 0; m < 4; ++m) _Pragma("unroll") for (int k = 0; k < 2; ++k) dst[m][k] = *(const LAS bf16x8*)(lds + PG8_SA(b, h) + aoff + m * 2048 + k * 1024); } while (0)
; #define PG8_LDB(dst, b, h) do { _Pragma("unroll") for (int n = 0; n < 2; ++n) _Pragma("unroll") for (int k = 0; k < 2; ++k) dst[n][k] = *(const LAS bf16x8*)(lds + PG8_SB(b, h) + boff + n * 2048 + k * 1024); } while (0)
; #define PG8_MMA(ai, bj, At, Bt) do { __builtin_amdgcn_s_setprio(1); _Pragma("unroll") for (int m = 0; m < 4; ++m) _Pragma("unroll") for (int n = 0; n < 2; ++n) _Pragma("unroll") for (int k = 0; k < 2; ++k) \
;         acc[ai][bj][m][n] = __builtin_amdgcn_mfma_f32_16x16x32_bf16(Bt[n][k], At[m][k], acc[ai][bj][m][n], 0, 0, 0); __builtin_amdgcn_s_setprio(0); } while (0)
; #define PG8_WAIT_V(n) asm volatile("s_waitcnt vmcnt(" #n ")" ::: "memory")
; #define PG8_WAIT_L(n) asm volatile("s_waitcnt lgkmcnt(" #n ")" ::: "memory")
; #define PG8_BAR __builtin_amdgcn_s_barrier()
; #define PG8_SCHED __builtin_amdgcn_sched_barrier(0)
; template <class Epi>
; __device__ __forceinline__ void gemm_phase(LAS unsigned char* lds, const Gemm g, const Sched& S, const Epi& E) {
;     ...
;             PG8_LDB(B0, 0, 0); PG8_SCHED; PG8_LDA(At, 0, 0); PG8_STAGE(PG8_SA(1, 1), a1 + hstepA, voffA);
;             PG8_WAIT_L(8); PG8_BAR; PG8_WAIT_L(0); PG8_MMA(0, 0, At, B0); PG8_BAR; PG8_SCHED;
;             PG8_LDB(B1, 0, 1); PG8_STAGE(PG8_SB(0, 0), b2, voffB);
;             PG8_BAR; PG8_WAIT_L(0); PG8_MMA(0, 1, At, B1); PG8_BAR;
;             PG8_LDA(At, 0, 1); PG8_STAGE(PG8_SA(0, 0), a2, voffA);
;             PG8_BAR; PG8_WAIT_L(0); PG8_MMA(1, 0, At, B0); PG8_BAR; PG8_SCHED;
;             PG8_STAGE(PG8_SB(0, 1), b2 + hstepB, voffB);
;             PG8_WAIT_V(6); PG8_BAR; PG8_MMA(1, 1, At, B1); PG8_BAR;
	s_setprio 1
	v_mfma_f32_16x16x32_bf16 v[94:97], v[144:147], v[204:207], v[94:97]
	v_mfma_f32_16x16x32_bf16 v[90:93], v[176:179], v[204:207], v[90:93]
	v_mfma_f32_16x16x32_bf16 v[78:81], v[144:147], v[212:215], v[78:81]
	v_mfma_f32_16x16x32_bf16 v[74:77], v[176:179], v[212:215], v[74:77]
	v_mfma_f32_16x16x32_bf16 v[126:129], v[172:175], v[188:191], v[126:129]
	v_mfma_f32_16x16x32_bf16 v[122:125], v[180:183], v[188:191], v[122:125]
	v_mfma_f32_16x16x32_bf16 v[110:113], v[172:175], v[200:203], v[110:113]
	v_mfma_f32_16x16x32_bf16 v[106:109], v[180:183], v[200:203], v[106:109]
	v_mfma_f32_16x16x32_bf16 v[94:97], v[172:175], v[208:211], v[94:97]
	v_mfma_f32_16x16x32_bf16 v[90:93], v[180:183], v[208:211], v[90:93]
	v_mfma_f32_16x16x32_bf16 v[78:81], v[172:175], v[222:225], v[78:81]
	v_mfma_f32_16x16x32_bf16 v[74:77], v[180:183], v[222:225], v[74:77]
	v_mfma_f32_16x16x32_bf16 v[118:121], v[226:229], v[184:187], v[118:121]
	v_mfma_f32_16x16x32_bf16 v[114:117], v[234:237], v[184:187], v[114:117]
	v_mfma_f32_16x16x32_bf16 v[102:105], v[226:229], v[196:199], v[102:105]
	v_mfma_f32_16x16x32_bf16 v[98:101], v[234:237], v[196:199], v[98:101]
	v_mfma_f32_16x16x32_bf16 v[86:89], v[226:229], v[204:207], v[86:89]
	v_mfma_f32_16x16x32_bf16 v[82:85], v[234:237], v[204:207], v[82:85]
	v_mfma_f32_16x16x32_bf16 v[70:73], v[226:229], v[212:215], v[70:73]
	v_mfma_f32_16x16x32_bf16 v[66:69], v[234:237], v[212:215], v[66:69]
	v_mfma_f32_16x16x32_bf16 v[118:121], v[230:233], v[188:191], v[118:121]
	v_mfma_f32_16x16x32_bf16 v[114:117], v[238:241], v[188:191], v[114:117]
	v_mfma_f32_16x16x32_bf16 v[102:105], v[230:233], v[200:203], v[102:105]
	v_mfma_f32_16x16x32_bf16 v[98:101], v[238:241], v[200:203], v[98:101]
	v_mfma_f32_16x16x32_bf16 v[86:89], v[230:233], v[208:211], v[86:89]
	v_mfma_f32_16x16x32_bf16 v[82:85], v[238:241], v[208:211], v[82:85]
	v_mfma_f32_16x16x32_bf16 v[70:73], v[230:233], v[222:225], v[70:73]
	v_mfma_f32_16x16x32_bf16 v[66:69], v[238:241], v[222:225], v[66:69]
	s_setprio 0
	s_barrier
	s_add_i32 s9, s15, s39
	v_lshl_add_u64 v[148:149], s[96:97], 0, v[132:133]
	s_mov_b32 m0, s9
	v_lshl_add_u64 v[192:193], s[96:97], 0, v[136:137]
	global_load_lds_dwordx4 v[148:149], off
	s_add_i32 m0, s9, 0x2000
	s_nop 0
	global_load_lds_dwordx4 v[192:193], off
	s_mov_b32 m0, s42
	v_lshl_add_u64 v[194:195], s[94:95], 0, v[130:131]
	ds_read_b128 v[184:187], v171 offset:16384
	ds_read_b128 v[188:191], v171 offset:17408
	ds_read_b128 v[196:199], v171 offset:18432
	ds_read_b128 v[200:203], v171 offset:19456
	ds_read_b128 v[204:207], v171 offset:20480
	ds_read_b128 v[208:211], v171 offset:21504
	ds_read_b128 v[212:215], v171 offset:22528
	ds_read_b128 v[222:225], v171 offset:23552
	global_load_lds_dwordx4 v[194:195], off
	v_lshl_add_u64 v[216:217], s[94:95], 0, v[134:135]
	s_mov_b32 m0, s43
	s_nop 0
	global_load_lds_dwordx4 v[216:217], off
	s_add_u32 s96, s96, s78
	s_addc_u32 s97, s97, s79
	s_add_i32 s8, s8, s39
	v_lshl_add_u64 v[242:243], s[96:97], 0, v[132:133]
	s_mov_b32 m0, s8
	v_lshl_add_u64 v[244:245], s[96:97], 0, v[136:137]
	global_load_lds_dwordx4 v[242:243], off
	s_add_i32 m0, s8, 0x2000
	s_nop 0
	global_load_lds_dwordx4 v[244:245], off
	s_waitcnt vmcnt(8)
	s_waitcnt lgkmcnt(0)
	v_mfma_f32_16x16x32_bf16 v[62:65], v[144:147], v[184:187], v[62:65]
	v_mfma_f32_16x16x32_bf16 v[58:61], v[176:179], v[184:187], v[58:61]
	v_mfma_f32_16x16x32_bf16 v[50:53], v[144:147], v[196:199], v[50:53]
	v_mfma_f32_16x16x32_bf16 v[42:45], v[176:179], v[196:199], v[42:45]
	s_barrier
	s_setprio 1
	v_mfma_f32_16x16x32_bf16 v[34:37], v[144:147], v[204:207], v[34:37]
	v_mfma_f32_16x16x32_bf16 v[26:29], v[176:179], v[204:207], v[26:29]
	v_mfma_f32_16x16x32_bf16 v[18:21], v[144:147], v[212:215], v[18:21]
	v_mfma_f32_16x16x32_bf16 v[10:13], v[176:179], v[212:215], v[10:13]
	v_mfma_f32_16x16x32_bf16 v[62:65], v[172:175], v[188:191], v[62:65]
	v_mfma_f32_16x16x32_bf16 v[58:61], v[180:183], v[188:191], v[58:61]
	v_mfma_f32_16x16x32_bf16 v[50:53], v[172:175], v[200:203], v[50:53]
	v_mfma_f32_16x16x32_bf16 v[42:45], v[180:183], v[200:203], v[42:45]
	v_mfma_f32_16x16x32_bf16 v[34:37], v[172:175], v[208:211], v[34:37]
	v_mfma_f32_16x16x32_bf16 v[26:29], v[180:183], v[208:211], v[26:29]
	v_mfma_f32_16x16x32_bf16 v[18:21], v[172:175], v[222:225], v[18:21]
	v_mfma_f32_16x16x32_bf16 v[10:13], v[180:183], v[222:225], v[10:13]
	v_mfma_f32_16x16x32_bf16 v[54:57], v[226:229], v[184:187], v[54:57]
	v_mfma_f32_16x16x32_bf16 v[46:49], v[234:237], v[184:187], v[46:49]
	v_mfma_f32_16x16x32_bf16 v[38:41], v[226:229], v[196:199], v[38:41]
	v_mfma_f32_16x16x32_bf16 v[30:33], v[234:237], v[196:199], v[30:33]
	v_mfma_f32_16x16x32_bf16 v[22:25], v[226:229], v[204:207], v[22:25]
	v_mfma_f32_16x16x32_bf16 v[14:17], v[234:237], v[204:207], v[14:17]
	v_mfma_f32_16x16x32_bf16 v[6:9], v[226:229], v[212:215], v[6:9]
	v_mfma_f32_16x16x32_bf16 v[2:5], v[234:237], v[212:215], v[2:5]
	v_mfma_f32_16x16x32_bf16 v[54:57], v[230:233], v[188:191], v[54:57]
	v_mfma_f32_16x16x32_bf16 v[46:49], v[238:241], v[188:191], v[46:49]
	v_mfma_f32_16x16x32_bf16 v[38:41], v[230:233], v[200:203], v[38:41]
	v_mfma_f32_16x16x32_bf16 v[30:33], v[238:241], v[200:203], v[30:33]
	v_mfma_f32_16x16x32_bf16 v[22:25], v[230:233], v[208:211], v[22:25]
	v_mfma_f32_16x16x32_bf16 v[14:17], v[238:241], v[208:211], v[14:17]
	v_mfma_f32_16x16x32_bf16 v[6:9], v[230:233], v[222:225], v[6:9]
	v_mfma_f32_16x16x32_bf16 v[2:5], v[238:241], v[222:225], v[2:5]
	s_setprio 0
	s_barrier
; #define PG8_STAGE(bufoff, gbase, voff) do { _Pragma("unroll") for (int _i = 0; _i < 2; ++_i) \
;         __builtin_amdgcn_global_load_lds((const unsigned*)((const char*)(gbase) + (voff)[_i]), (LAS unsigned*)(lds + (bufoff) + ldsw + _i * 8192), 16, 0, 0); } while (0)
; #define PG8_LDA(dst, b, h) do { _Pragma("unroll") for (int m = 0; m < 4; ++m) _Pragma("unroll") for (int k = 0; k < 2; ++k) dst[m][k] = *(const LAS bf16x8*)(lds + PG8_SA(b, h) + aoff + m * 2048 + k * 1024); } while (0)
; #define PG8_LDB(dst, b, h) do { _Pragma("unroll") for (int n = 0; n < 2; ++n) _Pragma("unroll") for (int k = 0; k < 2; ++k) dst[n][k] = *(const LAS bf16x8*)(lds + PG8_SB(b, h) + boff + n * 2048 + k * 1024); } while (0)
; #define PG8_MMA(ai, bj, At, Bt) do { __builtin_amdgcn_s_setprio(1); _Pragma("unroll") for (int m = 0; m < 4; ++m) _Pragma("unroll") for (int n = 0; n < 2; ++n) _Pragma("unroll") for (int k = 0; k < 2; ++k) \
;         acc[ai][bj][m][n] = __builtin_amdgcn_mfma_f32_16x16x32_bf16(Bt[n][k], At[m][k], acc[ai][bj][m][n], 0, 0, 0); __builtin_amdgcn_s_setprio(0); } while (0)
; #define PG8_WAIT_L(n) asm volatile("s_waitcnt lgkmcnt(" #n ")" ::: "memory")
; #define PG8_BAR __builtin_amdgcn_s_barrier()
; #define PG8_SCHED __builtin_amdgcn_sched_barrier(0)
; template <class Epi>
; __device__ __forceinline__ void gemm_phase(LAS unsigned char* lds, const Gemm g, const Sched& S, const Epi& E) {
;     ...
;             PG8_LDB(B0, 1, 0); PG8_SCHED; PG8_LDA(At, 1, 0); PG8_STAGE(PG8_SA(0, 1), a2 + hstepA, voffA);
;             PG8_WAIT_L(8); PG8_BAR; PG8_WAIT_L(0); PG8_MMA(0, 0, At, B0); PG8_BAR; PG8_SCHED;
;             PG8_LDB(B1, 1, 1); PG8_STAGE(PG8_SB(1, 0), b3, voffB);
;             PG8_BAR; PG8_WAIT_L(0); PG8_MMA(0, 1, At, B1); PG8_BAR;
;             PG8_LDA(At, 1, 1); PG8_STAGE(PG8_SA(1, 0), a3, voffA);
;             PG8_BAR; PG8_WAIT_L(0); PG8_MMA(1, 0, At, B0); PG8_BAR; PG8_SCHED;
	s_add_i32 s8, 0, 0x18000
	v_add_u32_e32 v180, s8, v152
	ds_read_b128 v[144:147], v180
	ds_read_b128 v[172:175], v180 offset:1024
	ds_read_b128 v[176:179], v180 offset:2048
	ds_read_b128 v[180:183], v180 offset:3072
	s_add_u32 s94, s94, s4
	s_addc_u32 s95, s95, s5
	s_mov_b32 m0, s52
	v_lshl_add_u64 v[226:227], s[94:95], 0, v[130:131]
	ds_read_b128 v[184:187], v171 offset:32768
	ds_read_b128 v[188:191], v171 offset:33792
	ds_read_b128 v[196:199], v171 offset:34816
	ds_read_b128 v[200:203], v171 offset:35840
	ds_read_b128 v[204:207], v171 offset:36864
	ds_read_b128 v[208:211], v171 offset:37888
	ds_read_b128 v[212:215], v171 offset:38912
	ds_read_b128 v[222:225], v171 offset:39936
	global_load_lds_dwordx4 v[226:227], off
	v_lshl_add_u64 v[226:227], s[94:95], 0, v[134:135]
	s_mov_b32 m0, s53
	s_nop 0
	global_load_lds_dwordx4 v[226:227], off
	s_add_i32 s9, 0, 0x1c000
	v_add_u32_e32 v218, s9, v152
	ds_read_b128 v[226:229], v218
	ds_read_b128 v[230:233], v218 offset:1024
	ds_read_b128 v[234:237], v218 offset:2048
	ds_read_b128 v[238:241], v218 offset:3072
	s_waitcnt vmcnt(8)
	s_waitcnt lgkmcnt(0)
	v_mfma_f32_16x16x32_bf16 v[126:129], v[144:147], v[184:187], v[126:129]
	v_mfma_f32_16x16x32_bf16 v[122:125], v[176:179], v[184:187], v[122:125]
	v_mfma_f32_16x16x32_bf16 v[110:113], v[144:147], v[196:199], v[110:113]
	v_mfma_f32_16x16x32_bf16 v[106:109], v[176:179], v[196:199], v[106:109]
	s_barrier
	s_setprio 1
	v_mfma_f32_16x16x32_bf16 v[94:97], v[144:147], v[204:207], v[94:97]
	v_mfma_f32_16x16x32_bf16 v[90:93], v[176:179], v[204:207], v[90:93]
	v_mfma_f32_16x16x32_bf16 v[78:81], v[144:147], v[212:215], v[78:81]
	v_mfma_f32_16x16x32_bf16 v[74:77], v[176:179], v[212:215], v[74:77]
	v_mfma_f32_16x16x32_bf16 v[126:129], v[172:175], v[188:191], v[126:129]
	v_mfma_f32_16x16x32_bf16 v[122:125], v[180:183], v[188:191], v[122:125]
	v_mfma_f32_16x16x32_bf16 v[110:113], v[172:175], v[200:203], v[110:113]
	v_mfma_f32_16x16x32_bf16 v[106:109], v[180:183], v[200:203], v[106:109]
	v_mfma_f32_16x16x32_bf16 v[94:97], v[172:175], v[208:211], v[94:97]
	v_mfma_f32_16x16x32_bf16 v[90:93], v[180:183], v[208:211], v[90:93]
	v_mfma_f32_16x16x32_bf16 v[78:81], v[172:175], v[222:225], v[78:81]
	v_mfma_f32_16x16x32_bf16 v[74:77], v[180:183], v[222:225], v[74:77]
	v_mfma_f32_16x16x32_bf16 v[118:121], v[226:229], v[184:187], v[118:121]
	v_mfma_f32_16x16x32_bf16 v[114:117], v[234:237], v[184:187], v[114:117]
	v_mfma_f32_16x16x32_bf16 v[102:105], v[226:229], v[196:199], v[102:105]
	v_mfma_f32_16x16x32_bf16 v[98:101], v[234:237], v[196:199], v[98:101]
	v_mfma_f32_16x16x32_bf16 v[86:89], v[226:229], v[204:207], v[86:89]
	v_mfma_f32_16x16x32_bf16 v[82:85], v[234:237], v[204:207], v[82:85]
	v_mfma_f32_16x16x32_bf16 v[70:73], v[226:229], v[212:215], v[70:73]
	v_mfma_f32_16x16x32_bf16 v[66:69], v[234:237], v[212:215], v[66:69]
	v_mfma_f32_16x16x32_bf16 v[118:121], v[230:233], v[188:191], v[118:121]
	v_mfma_f32_16x16x32_bf16 v[114:117], v[238:241], v[188:191], v[114:117]
	v_mfma_f32_16x16x32_bf16 v[102:105], v[230:233], v[200:203], v[102:105]
	v_mfma_f32_16x16x32_bf16 v[98:101], v[238:241], v[200:203], v[98:101]
	v_mfma_f32_16x16x32_bf16 v[86:89], v[230:233], v[208:211], v[86:89]
	v_mfma_f32_16x16x32_bf16 v[82:85], v[238:241], v[208:211], v[82:85]
	v_mfma_f32_16x16x32_bf16 v[70:73], v[230:233], v[222:225], v[70:73]
	v_mfma_f32_16x16x32_bf16 v[66:69], v[238:241], v[222:225], v[66:69]
	s_setprio 0
	s_barrier
; #define PG8_STAGE(bufoff, gbase, voff) do { _Pragma("unroll") for (int _i = 0; _i < 2; ++_i) \
;         __builtin_amdgcn_global_load_lds((const unsigned*)((const char*)(gbase) + (voff)[_i]), (LAS unsigned*)(lds + (bufoff) + ldsw + _i * 8192), 16, 0, 0); } while (0)
; #define PG8_LDA(dst, b, h) do { _Pragma("unroll") for (int m = 0; m < 4; ++m) _Pragma("unroll") for (int k = 0; k < 2; ++k) dst[m][k] = *(const LAS bf16x8*)(lds + PG8_SA(b, h) + aoff + m * 2048 + k * 1024); } while (0)
; #define PG8_MMA(ai, bj, At, Bt) do { __builtin_amdgcn_s_setprio(1); _Pragma("unroll") for (int m = 0; m < 4; ++m) _Pragma("unroll") for (int n = 0; n < 2; ++n) _Pragma("unroll") for (int k = 0; k < 2; ++k) \
;         acc[ai][bj][m][n] = __builtin_amdgcn_mfma_f32_16x16x32_bf16(Bt[n][k], At[m][k], acc[ai][bj][m][n], 0, 0, 0); __builtin_amdgcn_s_setprio(0); } while (0)
; #define PG8_WAIT_V(n) asm volatile("s_waitcnt vmcnt(" #n ")" ::: "memory")
; #define PG8_WAIT_L(n) asm volatile("s_waitcnt lgkmcnt(" #n ")" ::: "memory")
; #define PG8_BAR __builtin_amdgcn_s_barrier()
; #define PG8_SCHED __builtin_amdgcn_sched_barrier(0)
; template <class Epi>
; __device__ __forceinline__ void gemm_phase(LAS unsigned char* lds, const Gemm g, const Sched& S, const Epi& E) {
;     ...
;             PG8_LDA(At, 1, 1); PG8_STAGE(PG8_SA(1, 0), a3, voffA);
;             PG8_BAR; PG8_WAIT_L(0); PG8_MMA(1, 0, At, B0); PG8_BAR; PG8_SCHED;
;             PG8_STAGE(PG8_SB(1, 1), b3 + hstepB, voffB);
;             PG8_WAIT_V(6); PG8_BAR; PG8_MMA(1, 1, At, B1); PG8_BAR;
;         }
;         E(acc, cur, wr, wc, fr, fq, pre);
;         if (!has_next) break;
	s_add_i32 s8, s8, s39
	v_lshl_add_u64 v[148:149], v[148:149], 0, s[60:61]
	s_mov_b32 m0, s8
	s_nop 0
	global_load_lds_dwordx4 v[148:149], off
	v_lshl_add_u64 v[148:149], v[192:193], 0, s[60:61]
	s_add_i32 m0, s8, 0x2000
	s_nop 0
	global_load_lds_dwordx4 v[148:149], off
	s_mov_b32 m0, s67
	v_lshl_add_u64 v[148:149], v[194:195], 0, s[60:61]
	ds_read_b128 v[184:187], v171 offset:49152
	ds_read_b128 v[188:191], v171 offset:50176
	ds_read_b128 v[196:199], v171 offset:51200
	ds_read_b128 v[200:203], v171 offset:52224
	ds_read_b128 v[204:207], v171 offset:53248
	ds_read_b128 v[208:211], v171 offset:54272
	ds_read_b128 v[212:215], v171 offset:55296
	ds_read_b128 v[222:225], v171 offset:56320
	global_load_lds_dwordx4 v[148:149], off
	v_lshl_add_u64 v[148:149], v[216:217], 0, s[60:61]
	s_mov_b32 m0, s2
	s_nop 0
	global_load_lds_dwordx4 v[148:149], off
	s_add_i32 s8, s9, s39
	v_lshl_add_u64 v[148:149], v[242:243], 0, s[60:61]
	s_mov_b32 m0, s8
	s_nop 0
	global_load_lds_dwordx4 v[148:149], off
	v_lshl_add_u64 v[148:149], v[244:245], 0, s[60:61]
	s_add_i32 m0, s8, 0x2000
	s_nop 0
	global_load_lds_dwordx4 v[148:149], off
	s_waitcnt vmcnt(8)
	s_waitcnt lgkmcnt(0)
	v_mfma_f32_16x16x32_bf16 v[62:65], v[144:147], v[184:187], v[62:65]
	v_mfma_f32_16x16x32_bf16 v[58:61], v[176:179], v[184:187], v[58:61]
	v_mfma_f32_16x16x32_bf16 v[50:53], v[144:147], v[196:199], v[50:53]
	v_mfma_f32_16x16x32_bf16 v[42:45], v[176:179], v[196:199], v[42:45]
	s_barrier
	s_setprio 1
	v_mfma_f32_16x16x32_bf16 v[34:37], v[144:147], v[204:207], v[34:37]
	v_mfma_f32_16x16x32_bf16 v[26:29], v[176:179], v[204:207], v[26:29]
	v_mfma_f32_16x16x32_bf16 v[18:21], v[144:147], v[212:215], v[18:21]
	v_mfma_f32_16x16x32_bf16 v[10:13], v[176:179], v[212:215], v[10:13]
	v_mfma_f32_16x16x32_bf16 v[62:65], v[172:175], v[188:191], v[62:65]
	v_mfma_f32_16x16x32_bf16 v[58:61], v[180:183], v[188:191], v[58:61]
	v_mfma_f32_16x16x32_bf16 v[50:53], v[172:175], v[200:203], v[50:53]
	v_mfma_f32_16x16x32_bf16 v[42:45], v[180:183], v[200:203], v[42:45]
	v_mfma_f32_16x16x32_bf16 v[34:37], v[172:175], v[208:211], v[34:37]
	v_mfma_f32_16x16x32_bf16 v[26:29], v[180:183], v[208:211], v[26:29]
	v_mfma_f32_16x16x32_bf16 v[18:21], v[172:175], v[222:225], v[18:21]
	v_mfma_f32_16x16x32_bf16 v[10:13], v[180:183], v[222:225], v[10:13]
	v_mfma_f32_16x16x32_bf16 v[54:57], v[226:229], v[184:187], v[54:57]
	v_mfma_f32_16x16x32_bf16 v[46:49], v[234:237], v[184:187], v[46:49]
	v_mfma_f32_16x16x32_bf16 v[38:41], v[226:229], v[196:199], v[38:41]
	v_mfma_f32_16x16x32_bf16 v[30:33], v[234:237], v[196:199], v[30:33]
	v_mfma_f32_16x16x32_bf16 v[22:25], v[226:229], v[204:207], v[22:25]
	v_mfma_f32_16x16x32_bf16 v[14:17], v[234:237], v[204:207], v[14:17]
	v_mfma_f32_16x16x32_bf16 v[6:9], v[226:229], v[212:215], v[6:9]
	v_mfma_f32_16x16x32_bf16 v[2:5], v[234:237], v[212:215], v[2:5]
	v_mfma_f32_16x16x32_bf16 v[54:57], v[230:233], v[188:191], v[54:57]
	v_mfma_f32_16x16x32_bf16 v[46:49], v[238:241], v[188:191], v[46:49]
	v_mfma_f32_16x16x32_bf16 v[38:41], v[230:233], v[200:203], v[38:41]
	v_mfma_f32_16x16x32_bf16 v[30:33], v[238:241], v[200:203], v[30:33]
	v_mfma_f32_16x16x32_bf16 v[22:25], v[230:233], v[208:211], v[22:25]
	v_mfma_f32_16x16x32_bf16 v[14:17], v[238:241], v[208:211], v[14:17]
	v_mfma_f32_16x16x32_bf16 v[6:9], v[230:233], v[222:225], v[6:9]
	v_mfma_f32_16x16x32_bf16 v[2:5], v[238:241], v[222:225], v[2:5]
	s_setprio 0
	s_add_u32 s92, s92, 0x100
	s_addc_u32 s93, s93, 0
	s_add_u32 s34, s34, 0x100
	s_addc_u32 s35, s35, 0
	s_cmp_ge_u32 s14, s73
	s_mov_b32 s66, s14
	s_barrier
	s_cbranch_scc0 .LBB0_400
	v_readfirstlane_b32 s98, v219
	s_nop 1
	s_bitcmp1_b32 s98, 8
	s_cbranch_scc1 .Lresync_x_400_p
	s_barrier
	s_branch .Lresync_x_400
.Lresync_x_400_p:
	s_setprio 1

; #define PG8_WAIT_V(n) asm volatile("s_waitcnt vmcnt(" #n ")" ::: "memory")
; #define PG8_BAR __builtin_amdgcn_s_barrier()
; template <class Epi>
; __device__ __forceinline__ void gemm_phase(LAS unsigned char* lds, const Gemm g, const Sched& S, const Epi& E) {
;     ...
;     PG8_WAIT_V(0);
;     if (wr == 0) PG8_BAR;
;     PG8_BAR;
.LBB0_434:
	s_waitcnt vmcnt(0)
	v_readlane_b32 s0, v254, 51
	v_readlane_b32 s84, v254, 49
	s_setprio 0
	s_cmpk_gt_u32 s0, 0xff
	v_readlane_b32 s85, v254, 50
	v_readlane_b32 s48, v254, 53
	v_readlane_b32 s51, v254, 55
	v_readlane_b32 s53, v254, 57
	s_cbranch_scc1 .LBB0_436

; #define PG8_STAGE(bufoff, gbase, voff) do { _Pragma("unroll") for (int _i = 0; _i < 2; ++_i) \
;         __builtin_amdgcn_global_load_lds((const unsigned*)((const char*)(gbase) + (voff)[_i]), (LAS unsigned*)(lds + (bufoff) + ldsw + _i * 8192), 16, 0, 0); } while (0)
; #define PG8_LDA(dst, b, h) do { _Pragma("unroll") for (int m = 0; m < 4; ++m) _Pragma("unroll") for (int k = 0; k < 2; ++k) dst[m][k] = *(const LAS bf16x8*)(lds + PG8_SA(b, h) + aoff + m * 2048 + k * 1024); } while (0)
; #define PG8_LDB(dst, b, h) do { _Pragma("unroll") for (int n = 0; n < 2; ++n) _Pragma("unroll") for (int k = 0; k < 2; ++k) dst[n][k] = *(const LAS bf16x8*)(lds + PG8_SB(b, h) + boff + n * 2048 + k * 1024); } while (0)
; #define PG8_MMA(ai, bj, At, Bt) do { __builtin_amdgcn_s_setprio(1); _Pragma("unroll") for (int m = 0; m < 4; ++m) _Pragma("unroll") for (int n = 0; n < 2; ++n) _Pragma("unroll") for (int k = 0; k < 2; ++k) \
;         acc[ai][bj][m][n] = __builtin_amdgcn_mfma_f32_16x16x32_bf16(Bt[n][k], At[m][k], acc[ai][bj][m][n], 0, 0, 0); __builtin_amdgcn_s_setprio(0); } while (0)
; #define PG8_WAIT_L(n) asm volatile("s_waitcnt lgkmcnt(" #n ")" ::: "memory")
; #define PG8_BAR __builtin_amdgcn_s_barrier()
; #define PG8_SCHED __builtin_amdgcn_sched_barrier(0)
; template <class Epi>
; __device__ __forceinline__ void gemm_phase(LAS unsigned char* lds, const Gemm g, const Sched& S, const Epi& E) {
;     ...
;         for (int t = 0; t < nt; t += 2) {
;             const bool last = (t == nt - 2);
;             const char* a1 = cA + (size_t)(t + 1) * kstep;
;             const char* a2 = last ? nA : cA + (size_t)(t + 2) * kstep; const char* b2 = last ? nB : cB + (size_t)(t + 2) * kstep;
;             const char* a3 = a2 + kstep; const char* b3 = b2 + kstep;
;             PG8_LDB(B0, 0, 0); PG8_SCHED; PG8_LDA(At, 0, 0); PG8_STAGE(PG8_SA(1, 1), a1 + hstepA, voffA);
;             PG8_WAIT_L(8); PG8_BAR; PG8_WAIT_L(0); PG8_MMA(0, 0, At, B0); PG8_BAR; PG8_SCHED;
;     ...
; #pragma unroll
;         for (int a = 0; a < 2; ++a)
; #pragma unroll
;             for (int b = 0; b < 2; ++b)
; #pragma unroll
;                 for (int m = 0; m < 4; ++m)
; #pragma unroll
;                     for (int n = 0; n < 2; ++n) acc[a][b][m][n] = (f32x4){0.f, 0.f, 0.f, 0.f};
;         cur = nxt; cA = nA; cB = nB; ++ui;
.LBB0_460:
	v_mov_b64_e32 v[2:3], s[26:27]
	v_readlane_b32 s8, v254, 11
	v_cmp_lt_i64_e32 vcc, s[84:85], v[2:3]
	v_readlane_b32 s9, v254, 12
	s_add_u32 s84, s8, s80
	s_addc_u32 s85, s9, s81
	s_and_b64 s[14:15], vcc, exec
	s_cselect_b32 s71, s85, s5
	s_cselect_b32 s57, s84, s4
	s_add_u32 s86, s10, s82
	s_addc_u32 s87, s11, s83
	s_and_b64 s[14:15], vcc, exec
	s_cselect_b32 s59, s87, s89
	s_cselect_b32 s72, s86, s88
	s_add_u32 s4, s4, 0x80
	s_addc_u32 s5, s5, 0
	s_add_u32 s34, s88, 0x100
	v_mov_b32_e32 v2, 0
	s_addc_u32 s35, s89, 0
	s_mov_b32 s88, 0
	v_mov_b32_e32 v3, v2
	v_mov_b32_e32 v4, v2
	v_mov_b32_e32 v5, v2
	v_mov_b32_e32 v6, v2
	v_mov_b32_e32 v7, v2
	v_mov_b32_e32 v8, v2
	v_mov_b32_e32 v9, v2
	v_mov_b32_e32 v18, v2
	v_mov_b32_e32 v19, v2
	v_mov_b32_e32 v20, v2
	v_mov_b32_e32 v21, v2
	v_mov_b32_e32 v22, v2
	v_mov_b32_e32 v23, v2
	v_mov_b32_e32 v24, v2
	v_mov_b32_e32 v25, v2
	v_mov_b32_e32 v34, v2
	v_mov_b32_e32 v35, v2
	v_mov_b32_e32 v36, v2
	v_mov_b32_e32 v37, v2
	v_mov_b32_e32 v38, v2
	v_mov_b32_e32 v39, v2
	v_mov_b32_e32 v40, v2
	v_mov_b32_e32 v41, v2
	v_mov_b32_e32 v50, v2
	v_mov_b32_e32 v51, v2
	v_mov_b32_e32 v52, v2
	v_mov_b32_e32 v53, v2
	v_mov_b32_e32 v54, v2
	v_mov_b32_e32 v55, v2
	v_mov_b32_e32 v56, v2
	v_mov_b32_e32 v57, v2
	v_mov_b32_e32 v10, v2
	v_mov_b32_e32 v11, v2
	v_mov_b32_e32 v12, v2
	v_mov_b32_e32 v13, v2
	v_mov_b32_e32 v14, v2
	v_mov_b32_e32 v15, v2
	v_mov_b32_e32 v16, v2
	v_mov_b32_e32 v17, v2
	v_mov_b32_e32 v26, v2
	v_mov_b32_e32 v27, v2
	v_mov_b32_e32 v28, v2
	v_mov_b32_e32 v29, v2
	v_mov_b32_e32 v30, v2
	v_mov_b32_e32 v31, v2
	v_mov_b32_e32 v32, v2
	v_mov_b32_e32 v33, v2
	v_mov_b32_e32 v42, v2
	v_mov_b32_e32 v43, v2
	v_mov_b32_e32 v44, v2
	v_mov_b32_e32 v45, v2
	v_mov_b32_e32 v46, v2
	s_waitcnt lgkmcnt(0)
	v_mov_b32_e32 v47, v2
	v_mov_b32_e32 v48, v2
	v_mov_b32_e32 v49, v2
	v_mov_b32_e32 v58, v2
	v_mov_b32_e32 v59, v2
	v_mov_b32_e32 v60, v2
	v_mov_b32_e32 v61, v2
	v_mov_b32_e32 v62, v2
	v_mov_b32_e32 v63, v2
	v_mov_b32_e32 v64, v2
	v_mov_b32_e32 v65, v2
	v_mov_b32_e32 v66, v2
	v_mov_b32_e32 v67, v2
	v_mov_b32_e32 v68, v2
	v_mov_b32_e32 v69, v2
	v_mov_b32_e32 v70, v2
	v_mov_b32_e32 v71, v2
	v_mov_b32_e32 v72, v2
	v_mov_b32_e32 v73, v2
	v_mov_b32_e32 v86, v2
	v_mov_b32_e32 v87, v2
	v_mov_b32_e32 v88, v2
	v_mov_b32_e32 v89, v2
	v_mov_b32_e32 v90, v2
	v_mov_b32_e32 v91, v2
	v_mov_b32_e32 v92, v2
	v_mov_b32_e32 v93, v2
	v_mov_b32_e32 v110, v2
	v_mov_b32_e32 v111, v2
	v_mov_b32_e32 v112, v2
	v_mov_b32_e32 v113, v2
	v_mov_b32_e32 v118, v2
	v_mov_b32_e32 v119, v2
	v_mov_b32_e32 v120, v2
	v_mov_b32_e32 v121, v2
	v_mov_b32_e32 v138, v2
	v_mov_b32_e32 v139, v2
	v_mov_b32_e32 v140, v2
	v_mov_b32_e32 v141, v2
	v_mov_b32_e32 v142, v2
	v_mov_b32_e32 v143, v2
	v_mov_b32_e32 v144, v2
	v_mov_b32_e32 v145, v2
	v_mov_b32_e32 v74, v2
	v_mov_b32_e32 v75, v2
	v_mov_b32_e32 v76, v2
	v_mov_b32_e32 v77, v2
	v_mov_b32_e32 v78, v2
	v_mov_b32_e32 v79, v2
	v_mov_b32_e32 v80, v2
	v_mov_b32_e32 v81, v2
	v_mov_b32_e32 v102, v2
	v_mov_b32_e32 v103, v2
	v_mov_b32_e32 v104, v2
	v_mov_b32_e32 v105, v2
	v_mov_b32_e32 v106, v2
	v_mov_b32_e32 v107, v2
	v_mov_b32_e32 v108, v2
	v_mov_b32_e32 v109, v2
	v_mov_b32_e32 v126, v2
	v_mov_b32_e32 v127, v2
	v_mov_b32_e32 v128, v2
	v_mov_b32_e32 v129, v2
	v_mov_b32_e32 v134, v2
	v_mov_b32_e32 v135, v2
	v_mov_b32_e32 v136, v2
	v_mov_b32_e32 v137, v2
	v_mov_b32_e32 v154, v2
	v_mov_b32_e32 v155, v2
	v_mov_b32_e32 v156, v2
	v_mov_b32_e32 v157, v2
	v_mov_b32_e32 v158, v2
	v_mov_b32_e32 v159, v2
	v_mov_b32_e32 v160, v2
	v_mov_b32_e32 v161, v2
	v_readfirstlane_b32 s98, v219
	s_nop 1
	s_bitcmp1_b32 s98, 8
	s_cbranch_scc0 .Lresync_y_461
	s_setprio 0
	s_barrier
.Lresync_y_461:
.LBB0_461:
	s_add_i32 s14, s88, 2
	s_add_u32 s8, s4, 0x80
	s_addc_u32 s9, s5, 0
	s_add_i32 s15, 0, 0x10000
	v_add_u32_e32 v114, s15, v211
	ds_read_b128 v[82:85], v114
	ds_read_b128 v[94:97], v114 offset:1024
	ds_read_b128 v[98:101], v114 offset:2048
	ds_read_b128 v[114:117], v114 offset:3072
	s_cmp_eq_u32 s42, s88
	s_cselect_b32 s88, s57, s8
	s_cselect_b32 s89, s71, s9
	s_cselect_b32 s91, s59, s35
	s_cselect_b32 s90, s72, s34
	v_lshl_add_u64 v[178:179], s[4:5], 0, v[202:203]
	s_add_i32 m0, s24, 0xc000
	ds_read_b128 v[122:125], v213
	ds_read_b128 v[130:133], v213 offset:1024
	ds_read_b128 v[146:149], v213 offset:2048
	ds_read_b128 v[150:153], v213 offset:3072
	ds_read_b128 v[162:165], v213 offset:4096
	ds_read_b128 v[166:169], v213 offset:5120
	ds_read_b128 v[170:173], v213 offset:6144
	ds_read_b128 v[174:177], v213 offset:7168
	global_load_lds_dwordx4 v[178:179], off
	v_lshl_add_u64 v[178:179], s[4:5], 0, v[204:205]
	s_add_i32 m0, s24, 0xe000
	s_nop 0
	global_load_lds_dwordx4 v[178:179], off
	s_add_i32 s8, 0, 0x14000
	v_add_u32_e32 v190, s8, v211
	ds_read_b128 v[178:181], v190
	ds_read_b128 v[182:185], v190 offset:1024
	ds_read_b128 v[186:189], v190 offset:2048
	ds_read_b128 v[190:193], v190 offset:3072
	s_waitcnt vmcnt(8)
	s_waitcnt lgkmcnt(0)
	v_mfma_f32_16x16x32_bf16 v[158:161], v[82:85], v[122:125], v[158:161]
	v_mfma_f32_16x16x32_bf16 v[154:157], v[98:101], v[122:125], v[154:157]
	v_mfma_f32_16x16x32_bf16 v[134:137], v[82:85], v[146:149], v[134:137]
	v_mfma_f32_16x16x32_bf16 v[126:129], v[98:101], v[146:149], v[126:129]
	s_barrier
; #define PG8_STAGE(bufoff, gbase, voff) do { _Pragma("unroll") for (int _i = 0; _i < 2; ++_i) \
;         __builtin_amdgcn_global_load_lds((const unsigned*)((const char*)(gbase) + (voff)[_i]), (LAS unsigned*)(lds + (bufoff) + ldsw + _i * 8192), 16, 0, 0); } while (0)
; #define PG8_LDA(dst, b, h) do { _Pragma("unroll") for (int m = 0; m < 4; ++m) _Pragma("unroll") for (int k = 0; k < 2; ++k) dst[m][k] = *(const LAS bf16x8*)(lds + PG8_SA(b, h) + aoff + m * 2048 + k * 1024); } while (0)
; #define PG8_LDB(dst, b, h) do { _Pragma("unroll") for (int n = 0; n < 2; ++n) _Pragma("unroll") for (int k = 0; k < 2; ++k) dst[n][k] = *(const LAS bf16x8*)(lds + PG8_SB(b, h) + boff + n * 2048 + k * 1024); } while (0)
; #define PG8_MMA(ai, bj, At, Bt) do { __builtin_amdgcn_s_setprio(1); _Pragma("unroll") for (int m = 0; m < 4; ++m) _Pragma("unroll") for (int n = 0; n < 2; ++n) _Pragma("unroll") for (int k = 0; k < 2; ++k) \
;         acc[ai][bj][m][n] = __builtin_amdgcn_mfma_f32_16x16x32_bf16(Bt[n][k], At[m][k], acc[ai][bj][m][n], 0, 0, 0); __builtin_amdgcn_s_setprio(0); } while (0)
; #define PG8_WAIT_V(n) asm volatile("s_waitcnt vmcnt(" #n ")" ::: "memory")
; #define PG8_WAIT_L(n) asm volatile("s_waitcnt lgkmcnt(" #n ")" ::: "memory")
; #define PG8_BAR __builtin_amdgcn_s_barrier()
; #define PG8_SCHED __builtin_amdgcn_sched_barrier(0)
; template <class Epi>
; __device__ __forceinline__ void gemm_phase(LAS unsigned char* lds, const Gemm g, const Sched& S, const Epi& E) {
;     ...
;             PG8_LDB(B0, 0, 0); PG8_SCHED; PG8_LDA(At, 0, 0); PG8_STAGE(PG8_SA(1, 1), a1 + hstepA, voffA);
;             PG8_WAIT_L(8); PG8_BAR; PG8_WAIT_L(0); PG8_MMA(0, 0, At, B0); PG8_BAR; PG8_SCHED;
;             PG8_LDB(B1, 0, 1); PG8_STAGE(PG8_SB(0, 0), b2, voffB);
;             PG8_BAR; PG8_WAIT_L(0); PG8_MMA(0, 1, At, B1); PG8_BAR;
;             PG8_LDA(At, 0, 1); PG8_STAGE(PG8_SA(0, 0), a2, voffA);
;             PG8_BAR; PG8_WAIT_L(0); PG8_MMA(1, 0, At, B0); PG8_BAR; PG8_SCHED;
;             PG8_STAGE(PG8_SB(0, 1), b2 + hstepB, voffB);
;             PG8_WAIT_V(6); PG8_BAR; PG8_MMA(1, 1, At, B1); PG8_BAR;
	s_setprio 1
	v_mfma_f32_16x16x32_bf16 v[106:109], v[82:85], v[162:165], v[106:109]
	v_mfma_f32_16x16x32_bf16 v[102:105], v[98:101], v[162:165], v[102:105]
	v_mfma_f32_16x16x32_bf16 v[78:81], v[82:85], v[170:173], v[78:81]
	v_mfma_f32_16x16x32_bf16 v[74:77], v[98:101], v[170:173], v[74:77]
	v_mfma_f32_16x16x32_bf16 v[158:161], v[94:97], v[130:133], v[158:161]
	v_mfma_f32_16x16x32_bf16 v[154:157], v[114:117], v[130:133], v[154:157]
	v_mfma_f32_16x16x32_bf16 v[134:137], v[94:97], v[150:153], v[134:137]
	v_mfma_f32_16x16x32_bf16 v[126:129], v[114:117], v[150:153], v[126:129]
	v_mfma_f32_16x16x32_bf16 v[106:109], v[94:97], v[166:169], v[106:109]
	v_mfma_f32_16x16x32_bf16 v[102:105], v[114:117], v[166:169], v[102:105]
	v_mfma_f32_16x16x32_bf16 v[78:81], v[94:97], v[174:177], v[78:81]
	v_mfma_f32_16x16x32_bf16 v[74:77], v[114:117], v[174:177], v[74:77]
	v_mfma_f32_16x16x32_bf16 v[142:145], v[178:181], v[122:125], v[142:145]
	v_mfma_f32_16x16x32_bf16 v[118:121], v[178:181], v[146:149], v[118:121]
	v_mfma_f32_16x16x32_bf16 v[110:113], v[186:189], v[146:149], v[110:113]
	v_mfma_f32_16x16x32_bf16 v[90:93], v[178:181], v[162:165], v[90:93]
	v_mfma_f32_16x16x32_bf16 v[86:89], v[186:189], v[162:165], v[86:89]
	v_mfma_f32_16x16x32_bf16 v[70:73], v[178:181], v[170:173], v[70:73]
	v_mfma_f32_16x16x32_bf16 v[66:69], v[186:189], v[170:173], v[66:69]
	v_mfma_f32_16x16x32_bf16 v[142:145], v[182:185], v[130:133], v[142:145]
	v_mfma_f32_16x16x32_bf16 v[122:125], v[186:189], v[122:125], v[138:141]
	v_mfma_f32_16x16x32_bf16 v[118:121], v[182:185], v[150:153], v[118:121]
	v_mfma_f32_16x16x32_bf16 v[110:113], v[190:193], v[150:153], v[110:113]
	v_mfma_f32_16x16x32_bf16 v[90:93], v[182:185], v[166:169], v[90:93]
	v_mfma_f32_16x16x32_bf16 v[86:89], v[190:193], v[166:169], v[86:89]
	v_mfma_f32_16x16x32_bf16 v[70:73], v[182:185], v[174:177], v[70:73]
	v_mfma_f32_16x16x32_bf16 v[66:69], v[190:193], v[174:177], v[66:69]
	v_mfma_f32_16x16x32_bf16 v[122:125], v[190:193], v[130:133], v[122:125]
	s_setprio 0
	s_barrier
	s_add_i32 s9, s15, s3
	v_lshl_add_u64 v[194:195], s[90:91], 0, v[0:1]
	s_mov_b32 m0, s9
	s_nop 0
	global_load_lds_dwordx4 v[194:195], off
	v_lshl_add_u64 v[206:207], s[90:91], 0, v[200:201]
	s_add_i32 m0, s9, 0x2000
	s_nop 0
	global_load_lds_dwordx4 v[206:207], off
	s_mov_b32 m0, s24
	v_lshl_add_u64 v[208:209], s[88:89], 0, v[196:197]
	ds_read_b128 v[130:133], v213 offset:16384
	ds_read_b128 v[138:141], v213 offset:17408
	ds_read_b128 v[146:149], v213 offset:18432
	ds_read_b128 v[150:153], v213 offset:19456
	ds_read_b128 v[162:165], v213 offset:20480
	ds_read_b128 v[166:169], v213 offset:21504
	ds_read_b128 v[170:173], v213 offset:22528
	ds_read_b128 v[174:177], v213 offset:23552
	global_load_lds_dwordx4 v[208:209], off
	v_lshl_add_u64 v[214:215], s[88:89], 0, v[198:199]
	s_mov_b32 m0, s33
	s_nop 0
	global_load_lds_dwordx4 v[214:215], off
	s_add_u32 s90, s90, s78
	s_addc_u32 s91, s91, s79
	s_add_i32 s8, s8, s3
	v_lshl_add_u64 v[216:217], s[90:91], 0, v[0:1]
	s_mov_b32 m0, s8
	v_lshl_add_u64 v[222:223], s[90:91], 0, v[200:201]
	global_load_lds_dwordx4 v[216:217], off
	s_add_i32 m0, s8, 0x2000
	s_nop 0
	global_load_lds_dwordx4 v[222:223], off
	s_waitcnt vmcnt(8)
	s_waitcnt lgkmcnt(0)
	v_mfma_f32_16x16x32_bf16 v[62:65], v[82:85], v[130:133], v[62:65]
	v_mfma_f32_16x16x32_bf16 v[58:61], v[98:101], v[130:133], v[58:61]
	v_mfma_f32_16x16x32_bf16 v[46:49], v[82:85], v[146:149], v[46:49]
	v_mfma_f32_16x16x32_bf16 v[42:45], v[98:101], v[146:149], v[42:45]
	s_barrier
	s_setprio 1
	v_mfma_f32_16x16x32_bf16 v[30:33], v[82:85], v[162:165], v[30:33]
	v_mfma_f32_16x16x32_bf16 v[26:29], v[98:101], v[162:165], v[26:29]
	v_mfma_f32_16x16x32_bf16 v[14:17], v[82:85], v[170:173], v[14:17]
	v_mfma_f32_16x16x32_bf16 v[10:13], v[98:101], v[170:173], v[10:13]
	v_mfma_f32_16x16x32_bf16 v[62:65], v[94:97], v[138:141], v[62:65]
	v_mfma_f32_16x16x32_bf16 v[58:61], v[114:117], v[138:141], v[58:61]
	v_mfma_f32_16x16x32_bf16 v[46:49], v[94:97], v[150:153], v[46:49]
	v_mfma_f32_16x16x32_bf16 v[42:45], v[114:117], v[150:153], v[42:45]
	v_mfma_f32_16x16x32_bf16 v[30:33], v[94:97], v[166:169], v[30:33]
	v_mfma_f32_16x16x32_bf16 v[26:29], v[114:117], v[166:169], v[26:29]
	v_mfma_f32_16x16x32_bf16 v[14:17], v[94:97], v[174:177], v[14:17]
	v_mfma_f32_16x16x32_bf16 v[10:13], v[114:117], v[174:177], v[10:13]
	v_mfma_f32_16x16x32_bf16 v[54:57], v[178:181], v[130:133], v[54:57]
	v_mfma_f32_16x16x32_bf16 v[50:53], v[186:189], v[130:133], v[50:53]
	v_mfma_f32_16x16x32_bf16 v[38:41], v[178:181], v[146:149], v[38:41]
	v_mfma_f32_16x16x32_bf16 v[34:37], v[186:189], v[146:149], v[34:37]
	v_mfma_f32_16x16x32_bf16 v[22:25], v[178:181], v[162:165], v[22:25]
	v_mfma_f32_16x16x32_bf16 v[18:21], v[186:189], v[162:165], v[18:21]
	v_mfma_f32_16x16x32_bf16 v[6:9], v[178:181], v[170:173], v[6:9]
	v_mfma_f32_16x16x32_bf16 v[2:5], v[186:189], v[170:173], v[2:5]
	v_mfma_f32_16x16x32_bf16 v[54:57], v[182:185], v[138:141], v[54:57]
	v_mfma_f32_16x16x32_bf16 v[50:53], v[190:193], v[138:141], v[50:53]
	v_mfma_f32_16x16x32_bf16 v[38:41], v[182:185], v[150:153], v[38:41]
	v_mfma_f32_16x16x32_bf16 v[34:37], v[190:193], v[150:153], v[34:37]
	v_mfma_f32_16x16x32_bf16 v[22:25], v[182:185], v[166:169], v[22:25]
	v_mfma_f32_16x16x32_bf16 v[18:21], v[190:193], v[166:169], v[18:21]
	v_mfma_f32_16x16x32_bf16 v[6:9], v[182:185], v[174:177], v[6:9]
	v_mfma_f32_16x16x32_bf16 v[2:5], v[190:193], v[174:177], v[2:5]
	s_setprio 0
	s_barrier
; #define PG8_STAGE(bufoff, gbase, voff) do { _Pragma("unroll") for (int _i = 0; _i < 2; ++_i) \
;         __builtin_amdgcn_global_load_lds((const unsigned*)((const char*)(gbase) + (voff)[_i]), (LAS unsigned*)(lds + (bufoff) + ldsw + _i * 8192), 16, 0, 0); } while (0)
; #define PG8_LDA(dst, b, h) do { _Pragma("unroll") for (int m = 0; m < 4; ++m) _Pragma("unroll") for (int k = 0; k < 2; ++k) dst[m][k] = *(const LAS bf16x8*)(lds + PG8_SA(b, h) + aoff + m * 2048 + k * 1024); } while (0)
; #define PG8_LDB(dst, b, h) do { _Pragma("unroll") for (int n = 0; n < 2; ++n) _Pragma("unroll") for (int k = 0; k < 2; ++k) dst[n][k] = *(const LAS bf16x8*)(lds + PG8_SB(b, h) + boff + n * 2048 + k * 1024); } while (0)
; #define PG8_MMA(ai, bj, At, Bt) do { __builtin_amdgcn_s_setprio(1); _Pragma("unroll") for (int m = 0; m < 4; ++m) _Pragma("unroll") for (int n = 0; n < 2; ++n) _Pragma("unroll") for (int k = 0; k < 2; ++k) \
;         acc[ai][bj][m][n] = __builtin_amdgcn_mfma_f32_16x16x32_bf16(Bt[n][k], At[m][k], acc[ai][bj][m][n], 0, 0, 0); __builtin_amdgcn_s_setprio(0); } while (0)
; #define PG8_WAIT_L(n) asm volatile("s_waitcnt lgkmcnt(" #n ")" ::: "memory")
; #define PG8_BAR __builtin_amdgcn_s_barrier()
; #define PG8_SCHED __builtin_amdgcn_sched_barrier(0)
; template <class Epi>
; __device__ __forceinline__ void gemm_phase(LAS unsigned char* lds, const Gemm g, const Sched& S, const Epi& E) {
;     ...
;             PG8_LDB(B0, 1, 0); PG8_SCHED; PG8_LDA(At, 1, 0); PG8_STAGE(PG8_SA(0, 1), a2 + hstepA, voffA);
;             PG8_WAIT_L(8); PG8_BAR; PG8_WAIT_L(0); PG8_MMA(0, 0, At, B0); PG8_BAR; PG8_SCHED;
;             PG8_LDB(B1, 1, 1); PG8_STAGE(PG8_SB(1, 0), b3, voffB);
;             PG8_BAR; PG8_WAIT_L(0); PG8_MMA(0, 1, At, B1); PG8_BAR;
;             PG8_LDA(At, 1, 1); PG8_STAGE(PG8_SA(1, 0), a3, voffA);
;             PG8_BAR; PG8_WAIT_L(0); PG8_MMA(1, 0, At, B0); PG8_BAR; PG8_SCHED;
	s_add_i32 s8, 0, 0x18000
	v_add_u32_e32 v114, s8, v211
	ds_read_b128 v[82:85], v114
	ds_read_b128 v[94:97], v114 offset:1024
	ds_read_b128 v[98:101], v114 offset:2048
	ds_read_b128 v[114:117], v114 offset:3072
	s_add_u32 s88, s88, s36
	s_addc_u32 s89, s89, s37
	s_mov_b32 m0, s38
	v_lshl_add_u64 v[178:179], s[88:89], 0, v[196:197]
	ds_read_b128 v[130:133], v213 offset:32768
	ds_read_b128 v[138:141], v213 offset:33792
	ds_read_b128 v[146:149], v213 offset:34816
	ds_read_b128 v[150:153], v213 offset:35840
	ds_read_b128 v[162:165], v213 offset:36864
	ds_read_b128 v[166:169], v213 offset:37888
	ds_read_b128 v[170:173], v213 offset:38912
	ds_read_b128 v[174:177], v213 offset:39936
	global_load_lds_dwordx4 v[178:179], off
	v_lshl_add_u64 v[178:179], s[88:89], 0, v[198:199]
	s_mov_b32 m0, s39
	s_nop 0
	global_load_lds_dwordx4 v[178:179], off
	s_add_i32 s9, 0, 0x1c000
	v_add_u32_e32 v190, s9, v211
	ds_read_b128 v[178:181], v190
	ds_read_b128 v[182:185], v190 offset:1024
	ds_read_b128 v[186:189], v190 offset:2048
	ds_read_b128 v[190:193], v190 offset:3072
	s_waitcnt vmcnt(8)
	s_waitcnt lgkmcnt(0)
	v_mfma_f32_16x16x32_bf16 v[158:161], v[82:85], v[130:133], v[158:161]
	v_mfma_f32_16x16x32_bf16 v[154:157], v[98:101], v[130:133], v[154:157]
	v_mfma_f32_16x16x32_bf16 v[134:137], v[82:85], v[146:149], v[134:137]
	v_mfma_f32_16x16x32_bf16 v[126:129], v[98:101], v[146:149], v[126:129]
	s_barrier
	s_setprio 1
	v_mfma_f32_16x16x32_bf16 v[106:109], v[82:85], v[162:165], v[106:109]
	v_mfma_f32_16x16x32_bf16 v[102:105], v[98:101], v[162:165], v[102:105]
	v_mfma_f32_16x16x32_bf16 v[78:81], v[82:85], v[170:173], v[78:81]
	v_mfma_f32_16x16x32_bf16 v[74:77], v[98:101], v[170:173], v[74:77]
	v_mfma_f32_16x16x32_bf16 v[158:161], v[94:97], v[138:141], v[158:161]
	v_mfma_f32_16x16x32_bf16 v[154:157], v[114:117], v[138:141], v[154:157]
	v_mfma_f32_16x16x32_bf16 v[134:137], v[94:97], v[150:153], v[134:137]
	v_mfma_f32_16x16x32_bf16 v[126:129], v[114:117], v[150:153], v[126:129]
	v_mfma_f32_16x16x32_bf16 v[106:109], v[94:97], v[166:169], v[106:109]
	v_mfma_f32_16x16x32_bf16 v[102:105], v[114:117], v[166:169], v[102:105]
	v_mfma_f32_16x16x32_bf16 v[78:81], v[94:97], v[174:177], v[78:81]
	v_mfma_f32_16x16x32_bf16 v[74:77], v[114:117], v[174:177], v[74:77]
	v_mfma_f32_16x16x32_bf16 v[142:145], v[178:181], v[130:133], v[142:145]
	v_mfma_f32_16x16x32_bf16 v[122:125], v[186:189], v[130:133], v[122:125]
	v_mfma_f32_16x16x32_bf16 v[118:121], v[178:181], v[146:149], v[118:121]
	v_mfma_f32_16x16x32_bf16 v[110:113], v[186:189], v[146:149], v[110:113]
	v_mfma_f32_16x16x32_bf16 v[90:93], v[178:181], v[162:165], v[90:93]
	v_mfma_f32_16x16x32_bf16 v[86:89], v[186:189], v[162:165], v[86:89]
	v_mfma_f32_16x16x32_bf16 v[70:73], v[178:181], v[170:173], v[70:73]
	v_mfma_f32_16x16x32_bf16 v[66:69], v[186:189], v[170:173], v[66:69]
	v_mfma_f32_16x16x32_bf16 v[142:145], v[182:185], v[138:141], v[142:145]
	v_mfma_f32_16x16x32_bf16 v[138:141], v[190:193], v[138:141], v[122:125]
	v_mfma_f32_16x16x32_bf16 v[118:121], v[182:185], v[150:153], v[118:121]
	v_mfma_f32_16x16x32_bf16 v[110:113], v[190:193], v[150:153], v[110:113]
	v_mfma_f32_16x16x32_bf16 v[90:93], v[182:185], v[166:169], v[90:93]
	v_mfma_f32_16x16x32_bf16 v[86:89], v[190:193], v[166:169], v[86:89]
	v_mfma_f32_16x16x32_bf16 v[70:73], v[182:185], v[174:177], v[70:73]
	v_mfma_f32_16x16x32_bf16 v[66:69], v[190:193], v[174:177], v[66:69]
	s_setprio 0
	s_barrier
; #define PG8_STAGE(bufoff, gbase, voff) do { _Pragma("unroll") for (int _i = 0; _i < 2; ++_i) \
;         __builtin_amdgcn_global_load_lds((const unsigned*)((const char*)(gbase) + (voff)[_i]), (LAS unsigned*)(lds + (bufoff) + ldsw + _i * 8192), 16, 0, 0); } while (0)
; #define PG8_LDA(dst, b, h) do { _Pragma("unroll") for (int m = 0; m < 4; ++m) _Pragma("unroll") for (int k = 0; k < 2; ++k) dst[m][k] = *(const LAS bf16x8*)(lds + PG8_SA(b, h) + aoff + m * 2048 + k * 1024); } while (0)
; #define PG8_MMA(ai, bj, At, Bt) do { __builtin_amdgcn_s_setprio(1); _Pragma("unroll") for (int m = 0; m < 4; ++m) _Pragma("unroll") for (int n = 0; n < 2; ++n) _Pragma("unroll") for (int k = 0; k < 2; ++k) \
;         acc[ai][bj][m][n] = __builtin_amdgcn_mfma_f32_16x16x32_bf16(Bt[n][k], At[m][k], acc[ai][bj][m][n], 0, 0, 0); __builtin_amdgcn_s_setprio(0); } while (0)
; #define PG8_WAIT_V(n) asm volatile("s_waitcnt vmcnt(" #n ")" ::: "memory")
; #define PG8_WAIT_L(n) asm volatile("s_waitcnt lgkmcnt(" #n ")" ::: "memory")
; #define PG8_BAR __builtin_amdgcn_s_barrier()
; #define PG8_SCHED __builtin_amdgcn_sched_barrier(0)
; template <class Epi>
; __device__ __forceinline__ void gemm_phase(LAS unsigned char* lds, const Gemm g, const Sched& S, const Epi& E) {
;     ...
;             PG8_LDA(At, 1, 1); PG8_STAGE(PG8_SA(1, 0), a3, voffA);
;             PG8_BAR; PG8_WAIT_L(0); PG8_MMA(1, 0, At, B0); PG8_BAR; PG8_SCHED;
;             PG8_STAGE(PG8_SB(1, 1), b3 + hstepB, voffB);
;             PG8_WAIT_V(6); PG8_BAR; PG8_MMA(1, 1, At, B1); PG8_BAR;
;         }
;         E(acc, cur, wr, wc, fr, fq, pre);
;         if (!has_next) break;
	s_add_i32 s8, s8, s3
	v_lshl_add_u64 v[194:195], v[194:195], 0, s[60:61]
	s_mov_b32 m0, s8
	s_nop 0
	global_load_lds_dwordx4 v[194:195], off
	v_lshl_add_u64 v[194:195], v[206:207], 0, s[60:61]
	s_add_i32 m0, s8, 0x2000
	s_nop 0
	global_load_lds_dwordx4 v[194:195], off
	s_mov_b32 m0, s40
	v_lshl_add_u64 v[194:195], v[208:209], 0, s[60:61]
	ds_read_b128 v[122:125], v213 offset:49152
	ds_read_b128 v[130:133], v213 offset:50176
	ds_read_b128 v[146:149], v213 offset:51200
	ds_read_b128 v[150:153], v213 offset:52224
	ds_read_b128 v[162:165], v213 offset:53248
	ds_read_b128 v[166:169], v213 offset:54272
	ds_read_b128 v[170:173], v213 offset:55296
	ds_read_b128 v[174:177], v213 offset:56320
	global_load_lds_dwordx4 v[194:195], off
	v_lshl_add_u64 v[194:195], v[214:215], 0, s[60:61]
	s_mov_b32 m0, s41
	s_nop 0
	global_load_lds_dwordx4 v[194:195], off
	s_add_i32 s8, s9, s3
	v_lshl_add_u64 v[194:195], v[216:217], 0, s[60:61]
	s_mov_b32 m0, s8
	s_nop 0
	global_load_lds_dwordx4 v[194:195], off
	v_lshl_add_u64 v[194:195], v[222:223], 0, s[60:61]
	s_add_i32 m0, s8, 0x2000
	s_nop 0
	global_load_lds_dwordx4 v[194:195], off
	s_waitcnt vmcnt(8)
	s_waitcnt lgkmcnt(0)
	v_mfma_f32_16x16x32_bf16 v[62:65], v[82:85], v[122:125], v[62:65]
	v_mfma_f32_16x16x32_bf16 v[58:61], v[98:101], v[122:125], v[58:61]
	v_mfma_f32_16x16x32_bf16 v[46:49], v[82:85], v[146:149], v[46:49]
	v_mfma_f32_16x16x32_bf16 v[42:45], v[98:101], v[146:149], v[42:45]
	s_barrier
	s_setprio 1
	v_mfma_f32_16x16x32_bf16 v[30:33], v[82:85], v[162:165], v[30:33]
	v_mfma_f32_16x16x32_bf16 v[26:29], v[98:101], v[162:165], v[26:29]
	v_mfma_f32_16x16x32_bf16 v[14:17], v[82:85], v[170:173], v[14:17]
	v_mfma_f32_16x16x32_bf16 v[10:13], v[98:101], v[170:173], v[10:13]
	v_mfma_f32_16x16x32_bf16 v[62:65], v[94:97], v[130:133], v[62:65]
	v_mfma_f32_16x16x32_bf16 v[58:61], v[114:117], v[130:133], v[58:61]
	v_mfma_f32_16x16x32_bf16 v[46:49], v[94:97], v[150:153], v[46:49]
	v_mfma_f32_16x16x32_bf16 v[42:45], v[114:117], v[150:153], v[42:45]
	v_mfma_f32_16x16x32_bf16 v[30:33], v[94:97], v[166:169], v[30:33]
	v_mfma_f32_16x16x32_bf16 v[26:29], v[114:117], v[166:169], v[26:29]
	v_mfma_f32_16x16x32_bf16 v[14:17], v[94:97], v[174:177], v[14:17]
	v_mfma_f32_16x16x32_bf16 v[10:13], v[114:117], v[174:177], v[10:13]
	v_mfma_f32_16x16x32_bf16 v[54:57], v[178:181], v[122:125], v[54:57]
	v_mfma_f32_16x16x32_bf16 v[50:53], v[186:189], v[122:125], v[50:53]
	v_mfma_f32_16x16x32_bf16 v[38:41], v[178:181], v[146:149], v[38:41]
	v_mfma_f32_16x16x32_bf16 v[34:37], v[186:189], v[146:149], v[34:37]
	v_mfma_f32_16x16x32_bf16 v[22:25], v[178:181], v[162:165], v[22:25]
	v_mfma_f32_16x16x32_bf16 v[18:21], v[186:189], v[162:165], v[18:21]
	v_mfma_f32_16x16x32_bf16 v[6:9], v[178:181], v[170:173], v[6:9]
	v_mfma_f32_16x16x32_bf16 v[2:5], v[186:189], v[170:173], v[2:5]
	v_mfma_f32_16x16x32_bf16 v[54:57], v[182:185], v[130:133], v[54:57]
	v_mfma_f32_16x16x32_bf16 v[50:53], v[190:193], v[130:133], v[50:53]
	v_mfma_f32_16x16x32_bf16 v[38:41], v[182:185], v[150:153], v[38:41]
	v_mfma_f32_16x16x32_bf16 v[34:37], v[190:193], v[150:153], v[34:37]
	v_mfma_f32_16x16x32_bf16 v[22:25], v[182:185], v[166:169], v[22:25]
	v_mfma_f32_16x16x32_bf16 v[18:21], v[190:193], v[166:169], v[18:21]
	v_mfma_f32_16x16x32_bf16 v[6:9], v[182:185], v[174:177], v[6:9]
	v_mfma_f32_16x16x32_bf16 v[2:5], v[190:193], v[174:177], v[2:5]
	s_setprio 0
	s_add_u32 s4, s4, 0x100
	s_addc_u32 s5, s5, 0
	s_add_u32 s34, s34, 0x100
	s_addc_u32 s35, s35, 0
	s_cmp_ge_u32 s14, s73
	s_mov_b32 s88, s14
	s_barrier
	s_cbranch_scc0 .LBB0_461
	v_readfirstlane_b32 s98, v219
	s_nop 1
	s_bitcmp1_b32 s98, 8
	s_cbranch_scc1 .Lresync_x_461_p
	s_barrier
	s_branch .Lresync_x_461

; #define PG8_WAIT_V(n) asm volatile("s_waitcnt vmcnt(" #n ")" ::: "memory")
; #define PG8_BAR __builtin_amdgcn_s_barrier()
; template <class Epi>
; __device__ __forceinline__ void gemm_phase(LAS unsigned char* lds, const Gemm g, const Sched& S, const Epi& E) {
;     ...
;     PG8_WAIT_V(0);
;     if (wr == 0) PG8_BAR;
;     PG8_BAR;
.LBB0_527:
	s_waitcnt vmcnt(0)
	s_setprio 0
	s_cmpk_gt_u32 s2, 0xff
	v_readlane_b32 s58, v253, 45
	v_readlane_b32 s64, v253, 47
	v_readlane_b32 s48, v254, 53
	v_readlane_b32 s51, v254, 55
	v_readlane_b32 s53, v254, 57
	v_readlane_b32 s59, v253, 46
	s_cbranch_scc1 .LBB0_529

; #define PG8_STAGE(bufoff, gbase, voff) do { _Pragma("unroll") for (int _i = 0; _i < 2; ++_i) \
;         __builtin_amdgcn_global_load_lds((const unsigned*)((const char*)(gbase) + (voff)[_i]), (LAS unsigned*)(lds + (bufoff) + ldsw + _i * 8192), 16, 0, 0); } while (0)
; #define PG8_LDA(dst, b, h) do { _Pragma("unroll") for (int m = 0; m < 4; ++m) _Pragma("unroll") for (int k = 0; k < 2; ++k) dst[m][k] = *(const LAS bf16x8*)(lds + PG8_SA(b, h) + aoff + m * 2048 + k * 1024); } while (0)
; #define PG8_LDB(dst, b, h) do { _Pragma("unroll") for (int n = 0; n < 2; ++n) _Pragma("unroll") for (int k = 0; k < 2; ++k) dst[n][k] = *(const LAS bf16x8*)(lds + PG8_SB(b, h) + boff + n * 2048 + k * 1024); } while (0)
; #define PG8_MMA(ai, bj, At, Bt) do { __builtin_amdgcn_s_setprio(1); _Pragma("unroll") for (int m = 0; m < 4; ++m) _Pragma("unroll") for (int n = 0; n < 2; ++n) _Pragma("unroll") for (int k = 0; k < 2; ++k) \
;         acc[ai][bj][m][n] = __builtin_amdgcn_mfma_f32_16x16x32_bf16(Bt[n][k], At[m][k], acc[ai][bj][m][n], 0, 0, 0); __builtin_amdgcn_s_setprio(0); } while (0)
; #define PG8_WAIT_L(n) asm volatile("s_waitcnt lgkmcnt(" #n ")" ::: "memory")
; #define PG8_BAR __builtin_amdgcn_s_barrier()
; #define PG8_SCHED __builtin_amdgcn_sched_barrier(0)
; template <class Epi>
; __device__ __forceinline__ void gemm_phase(LAS unsigned char* lds, const Gemm g, const Sched& S, const Epi& E) {
;     ...
;         for (int t = 0; t < nt; t += 2) {
;             const bool last = (t == nt - 2);
;             const char* a1 = cA + (size_t)(t + 1) * kstep;
;             const char* a2 = last ? nA : cA + (size_t)(t + 2) * kstep; const char* b2 = last ? nB : cB + (size_t)(t + 2) * kstep;
;             const char* a3 = a2 + kstep; const char* b3 = b2 + kstep;
;             PG8_LDB(B0, 0, 0); PG8_SCHED; PG8_LDA(At, 0, 0); PG8_STAGE(PG8_SA(1, 1), a1 + hstepA, voffA);
;             PG8_WAIT_L(8); PG8_BAR; PG8_WAIT_L(0); PG8_MMA(0, 0, At, B0); PG8_BAR; PG8_SCHED;
;     ...
; #pragma unroll
;         for (int a = 0; a < 2; ++a)
; #pragma unroll
;             for (int b = 0; b < 2; ++b)
; #pragma unroll
;                 for (int m = 0; m < 4; ++m)
; #pragma unroll
;                     for (int n = 0; n < 2; ++n) acc[a][b][m][n] = (f32x4){0.f, 0.f, 0.f, 0.f};
;         cur = nxt; cA = nA; cB = nB; ++ui;
.LBB0_554:
	v_mov_b64_e32 v[2:3], s[26:27]
	v_readlane_b32 s8, v254, 11
	v_cmp_lt_i64_e32 vcc, s[86:87], v[2:3]
	v_readlane_b32 s9, v254, 12
	s_add_u32 s86, s8, s82
	s_addc_u32 s87, s9, s83
	s_and_b64 s[14:15], vcc, exec
	s_cselect_b32 s55, s87, s5
	s_cselect_b32 s57, s86, s4
	s_add_u32 s88, s10, s84
	s_addc_u32 s89, s11, s85
	s_and_b64 s[14:15], vcc, exec
	s_cselect_b32 s59, s89, s7
	s_cselect_b32 s95, s88, s6
	s_add_u32 s4, s4, 0x80
	s_addc_u32 s5, s5, 0
	s_add_u32 s34, s6, 0x100
	v_mov_b32_e32 v2, 0
	s_addc_u32 s35, s7, 0
	s_mov_b32 s6, 0
	v_mov_b32_e32 v3, v2
	v_mov_b32_e32 v4, v2
	v_mov_b32_e32 v5, v2
	v_mov_b32_e32 v6, v2
	v_mov_b32_e32 v7, v2
	v_mov_b32_e32 v8, v2
	v_mov_b32_e32 v9, v2
	v_mov_b32_e32 v18, v2
	v_mov_b32_e32 v19, v2
	v_mov_b32_e32 v20, v2
	v_mov_b32_e32 v21, v2
	v_mov_b32_e32 v22, v2
	v_mov_b32_e32 v23, v2
	v_mov_b32_e32 v24, v2
	v_mov_b32_e32 v25, v2
	v_mov_b32_e32 v34, v2
	v_mov_b32_e32 v35, v2
	v_mov_b32_e32 v36, v2
	v_mov_b32_e32 v37, v2
	v_mov_b32_e32 v38, v2
	v_mov_b32_e32 v39, v2
	v_mov_b32_e32 v40, v2
	v_mov_b32_e32 v41, v2
	v_mov_b32_e32 v50, v2
	v_mov_b32_e32 v51, v2
	v_mov_b32_e32 v52, v2
	v_mov_b32_e32 v53, v2
	v_mov_b32_e32 v54, v2
	v_mov_b32_e32 v55, v2
	v_mov_b32_e32 v56, v2
	v_mov_b32_e32 v57, v2
	v_mov_b32_e32 v10, v2
	v_mov_b32_e32 v11, v2
	v_mov_b32_e32 v12, v2
	v_mov_b32_e32 v13, v2
	v_mov_b32_e32 v14, v2
	v_mov_b32_e32 v15, v2
	v_mov_b32_e32 v16, v2
	v_mov_b32_e32 v17, v2
	v_mov_b32_e32 v26, v2
	v_mov_b32_e32 v27, v2
	v_mov_b32_e32 v28, v2
	v_mov_b32_e32 v29, v2
	v_mov_b32_e32 v30, v2
	v_mov_b32_e32 v31, v2
	v_mov_b32_e32 v32, v2
	v_mov_b32_e32 v33, v2
	v_mov_b32_e32 v42, v2
	v_mov_b32_e32 v43, v2
	v_mov_b32_e32 v44, v2
	v_mov_b32_e32 v45, v2
	v_mov_b32_e32 v46, v2
	s_waitcnt lgkmcnt(0)
	v_mov_b32_e32 v47, v2
	v_mov_b32_e32 v48, v2
	v_mov_b32_e32 v49, v2
	v_mov_b32_e32 v58, v2
	v_mov_b32_e32 v59, v2
	v_mov_b32_e32 v60, v2
	v_mov_b32_e32 v61, v2
	v_mov_b32_e32 v62, v2
	v_mov_b32_e32 v63, v2
	v_mov_b32_e32 v64, v2
	v_mov_b32_e32 v65, v2
	v_mov_b32_e32 v66, v2
	v_mov_b32_e32 v67, v2
	v_mov_b32_e32 v68, v2
	v_mov_b32_e32 v69, v2
	v_mov_b32_e32 v70, v2
	v_mov_b32_e32 v71, v2
	v_mov_b32_e32 v72, v2
	v_mov_b32_e32 v73, v2
	v_mov_b32_e32 v82, v2
	v_mov_b32_e32 v83, v2
	v_mov_b32_e32 v84, v2
	v_mov_b32_e32 v85, v2
	v_mov_b32_e32 v86, v2
	v_mov_b32_e32 v87, v2
	v_mov_b32_e32 v88, v2
	v_mov_b32_e32 v89, v2
	v_mov_b32_e32 v98, v2
	v_mov_b32_e32 v99, v2
	v_mov_b32_e32 v100, v2
	v_mov_b32_e32 v101, v2
	v_mov_b32_e32 v102, v2
	v_mov_b32_e32 v103, v2
	v_mov_b32_e32 v104, v2
	v_mov_b32_e32 v105, v2
	v_mov_b32_e32 v114, v2
	v_mov_b32_e32 v115, v2
	v_mov_b32_e32 v116, v2
	v_mov_b32_e32 v117, v2
	v_mov_b32_e32 v118, v2
	v_mov_b32_e32 v119, v2
	v_mov_b32_e32 v120, v2
	v_mov_b32_e32 v121, v2
	v_mov_b32_e32 v74, v2
	v_mov_b32_e32 v75, v2
	v_mov_b32_e32 v76, v2
	v_mov_b32_e32 v77, v2
	v_mov_b32_e32 v78, v2
	v_mov_b32_e32 v79, v2
	v_mov_b32_e32 v80, v2
	v_mov_b32_e32 v81, v2
	v_mov_b32_e32 v90, v2
	v_mov_b32_e32 v91, v2
	v_mov_b32_e32 v92, v2
	v_mov_b32_e32 v93, v2
	v_mov_b32_e32 v94, v2
	v_mov_b32_e32 v95, v2
	v_mov_b32_e32 v96, v2
	v_mov_b32_e32 v97, v2
	v_mov_b32_e32 v106, v2
	v_mov_b32_e32 v107, v2
	v_mov_b32_e32 v108, v2
	v_mov_b32_e32 v109, v2
	v_mov_b32_e32 v110, v2
	v_mov_b32_e32 v111, v2
	v_mov_b32_e32 v112, v2
	v_mov_b32_e32 v113, v2
	v_mov_b32_e32 v122, v2
	v_mov_b32_e32 v123, v2
	v_mov_b32_e32 v124, v2
	v_mov_b32_e32 v125, v2
	v_mov_b32_e32 v126, v2
	v_mov_b32_e32 v127, v2
	v_mov_b32_e32 v128, v2
	v_mov_b32_e32 v129, v2
	v_readfirstlane_b32 s98, v219
	s_nop 1
	s_bitcmp1_b32 s98, 8
	s_cbranch_scc0 .Lresync_y_555
	s_setprio 0
	s_barrier
.Lresync_y_555:
.LBB0_555:
	s_add_i32 s14, s6, 2
	s_add_u32 s8, s4, 0x80
	s_addc_u32 s7, s5, 0
	s_add_i32 s9, 0, 0x10000
	v_add_u32_e32 v160, s9, v156
	ds_read_b128 v[142:145], v160
	ds_read_b128 v[146:149], v160 offset:1024
	ds_read_b128 v[150:153], v160 offset:2048
	ds_read_b128 v[160:163], v160 offset:3072
	s_cmp_eq_u32 s43, s6
	s_cselect_b32 s6, s57, s8
	s_cselect_b32 s7, s55, s7
	s_cselect_b32 s91, s59, s35
	s_cselect_b32 s90, s95, s34
	v_lshl_add_u64 v[192:193], s[4:5], 0, v[136:137]
	s_add_i32 m0, s33, 0xc000
	ds_read_b128 v[164:167], v159
	ds_read_b128 v[168:171], v159 offset:1024
	ds_read_b128 v[172:175], v159 offset:2048
	ds_read_b128 v[176:179], v159 offset:3072
	ds_read_b128 v[180:183], v159 offset:4096
	ds_read_b128 v[184:187], v159 offset:5120
	ds_read_b128 v[188:191], v159 offset:6144
	ds_read_b128 v[196:199], v159 offset:7168
	global_load_lds_dwordx4 v[192:193], off
	v_lshl_add_u64 v[192:193], s[4:5], 0, v[138:139]
	s_add_i32 m0, s33, 0xe000
	s_nop 0
	global_load_lds_dwordx4 v[192:193], off
	s_add_i32 s8, 0, 0x14000
	v_add_u32_e32 v192, s8, v156
	ds_read_b128 v[200:203], v192
	ds_read_b128 v[204:207], v192 offset:1024
	ds_read_b128 v[208:211], v192 offset:2048
	ds_read_b128 v[212:215], v192 offset:3072
	s_waitcnt vmcnt(8)
	s_waitcnt lgkmcnt(0)
	v_mfma_f32_16x16x32_bf16 v[126:129], v[142:145], v[164:167], v[126:129]
	v_mfma_f32_16x16x32_bf16 v[122:125], v[150:153], v[164:167], v[122:125]
	v_mfma_f32_16x16x32_bf16 v[110:113], v[142:145], v[172:175], v[110:113]
	v_mfma_f32_16x16x32_bf16 v[106:109], v[150:153], v[172:175], v[106:109]
	s_barrier
; #define PG8_STAGE(bufoff, gbase, voff) do { _Pragma("unroll") for (int _i = 0; _i < 2; ++_i) \
;         __builtin_amdgcn_global_load_lds((const unsigned*)((const char*)(gbase) + (voff)[_i]), (LAS unsigned*)(lds + (bufoff) + ldsw + _i * 8192), 16, 0, 0); } while (0)
; #define PG8_LDA(dst, b, h) do { _Pragma("unroll") for (int m = 0; m < 4; ++m) _Pragma("unroll") for (int k = 0; k < 2; ++k) dst[m][k] = *(const LAS bf16x8*)(lds + PG8_SA(b, h) + aoff + m * 2048 + k * 1024); } while (0)
; #define PG8_LDB(dst, b, h) do { _Pragma("unroll") for (int n = 0; n < 2; ++n) _Pragma("unroll") for (int k = 0; k < 2; ++k) dst[n][k] = *(const LAS bf16x8*)(lds + PG8_SB(b, h) + boff + n * 2048 + k * 1024); } while (0)
; #define PG8_MMA(ai, bj, At, Bt) do { __builtin_amdgcn_s_setprio(1); _Pragma("unroll") for (int m = 0; m < 4; ++m) _Pragma("unroll") for (int n = 0; n < 2; ++n) _Pragma("unroll") for (int k = 0; k < 2; ++k) \
;         acc[ai][bj][m][n] = __builtin_amdgcn_mfma_f32_16x16x32_bf16(Bt[n][k], At[m][k], acc[ai][bj][m][n], 0, 0, 0); __builtin_amdgcn_s_setprio(0); } while (0)
; #define PG8_WAIT_V(n) asm volatile("s_waitcnt vmcnt(" #n ")" ::: "memory")
; #define PG8_WAIT_L(n) asm volatile("s_waitcnt lgkmcnt(" #n ")" ::: "memory")
; #define PG8_BAR __builtin_amdgcn_s_barrier()
; #define PG8_SCHED __builtin_amdgcn_sched_barrier(0)
; template <class Epi>
; __device__ __forceinline__ void gemm_phase(LAS unsigned char* lds, const Gemm g, const Sched& S, const Epi& E) {
;     ...
;             PG8_LDB(B0, 0, 0); PG8_SCHED; PG8_LDA(At, 0, 0); PG8_STAGE(PG8_SA(1, 1), a1 + hstepA, voffA);
;             PG8_WAIT_L(8); PG8_BAR; PG8_WAIT_L(0); PG8_MMA(0, 0, At, B0); PG8_BAR; PG8_SCHED;
;             PG8_LDB(B1, 0, 1); PG8_STAGE(PG8_SB(0, 0), b2, voffB);
;             PG8_BAR; PG8_WAIT_L(0); PG8_MMA(0, 1, At, B1); PG8_BAR;
;             PG8_LDA(At, 0, 1); PG8_STAGE(PG8_SA(0, 0), a2, voffA);
;             PG8_BAR; PG8_WAIT_L(0); PG8_MMA(1, 0, At, B0); PG8_BAR; PG8_SCHED;
;             PG8_STAGE(PG8_SB(0, 1), b2 + hstepB, voffB);
;             PG8_WAIT_V(6); PG8_BAR; PG8_MMA(1, 1, At, B1); PG8_BAR;
	s_setprio 1
	v_mfma_f32_16x16x32_bf16 v[94:97], v[142:145], v[180:183], v[94:97]
	v_mfma_f32_16x16x32_bf16 v[90:93], v[150:153], v[180:183], v[90:93]
	v_mfma_f32_16x16x32_bf16 v[78:81], v[142:145], v[188:191], v[78:81]
	v_mfma_f32_16x16x32_bf16 v[74:77], v[150:153], v[188:191], v[74:77]
	v_mfma_f32_16x16x32_bf16 v[126:129], v[146:149], v[168:171], v[126:129]
	v_mfma_f32_16x16x32_bf16 v[122:125], v[160:163], v[168:171], v[122:125]
	v_mfma_f32_16x16x32_bf16 v[110:113], v[146:149], v[176:179], v[110:113]
	v_mfma_f32_16x16x32_bf16 v[106:109], v[160:163], v[176:179], v[106:109]
	v_mfma_f32_16x16x32_bf16 v[94:97], v[146:149], v[184:187], v[94:97]
	v_mfma_f32_16x16x32_bf16 v[90:93], v[160:163], v[184:187], v[90:93]
	v_mfma_f32_16x16x32_bf16 v[78:81], v[146:149], v[196:199], v[78:81]
	v_mfma_f32_16x16x32_bf16 v[74:77], v[160:163], v[196:199], v[74:77]
	v_mfma_f32_16x16x32_bf16 v[118:121], v[200:203], v[164:167], v[118:121]
	v_mfma_f32_16x16x32_bf16 v[114:117], v[208:211], v[164:167], v[114:117]
	v_mfma_f32_16x16x32_bf16 v[102:105], v[200:203], v[172:175], v[102:105]
	v_mfma_f32_16x16x32_bf16 v[98:101], v[208:211], v[172:175], v[98:101]
	v_mfma_f32_16x16x32_bf16 v[86:89], v[200:203], v[180:183], v[86:89]
	v_mfma_f32_16x16x32_bf16 v[82:85], v[208:211], v[180:183], v[82:85]
	v_mfma_f32_16x16x32_bf16 v[70:73], v[200:203], v[188:191], v[70:73]
	v_mfma_f32_16x16x32_bf16 v[66:69], v[208:211], v[188:191], v[66:69]
	v_mfma_f32_16x16x32_bf16 v[118:121], v[204:207], v[168:171], v[118:121]
	v_mfma_f32_16x16x32_bf16 v[114:117], v[212:215], v[168:171], v[114:117]
	v_mfma_f32_16x16x32_bf16 v[102:105], v[204:207], v[176:179], v[102:105]
	v_mfma_f32_16x16x32_bf16 v[98:101], v[212:215], v[176:179], v[98:101]
	v_mfma_f32_16x16x32_bf16 v[86:89], v[204:207], v[184:187], v[86:89]
	v_mfma_f32_16x16x32_bf16 v[82:85], v[212:215], v[184:187], v[82:85]
	v_mfma_f32_16x16x32_bf16 v[70:73], v[204:207], v[196:199], v[70:73]
	v_mfma_f32_16x16x32_bf16 v[66:69], v[212:215], v[196:199], v[66:69]
	s_setprio 0
	s_barrier
	s_add_i32 s9, s9, s3
	v_lshl_add_u64 v[192:193], s[90:91], 0, v[0:1]
	s_mov_b32 m0, s9
	v_lshl_add_u64 v[194:195], s[90:91], 0, v[134:135]
	global_load_lds_dwordx4 v[192:193], off
	s_add_i32 m0, s9, 0x2000
	s_nop 0
	global_load_lds_dwordx4 v[194:195], off
	s_mov_b32 m0, s33
	v_lshl_add_u64 v[216:217], s[6:7], 0, v[130:131]
	ds_read_b128 v[164:167], v159 offset:16384
	ds_read_b128 v[168:171], v159 offset:17408
	ds_read_b128 v[172:175], v159 offset:18432
	ds_read_b128 v[176:179], v159 offset:19456
	ds_read_b128 v[180:183], v159 offset:20480
	ds_read_b128 v[184:187], v159 offset:21504
	ds_read_b128 v[188:191], v159 offset:22528
	ds_read_b128 v[196:199], v159 offset:23552
	global_load_lds_dwordx4 v[216:217], off
	v_lshl_add_u64 v[222:223], s[6:7], 0, v[132:133]
	s_mov_b32 m0, s38
	s_nop 0
	global_load_lds_dwordx4 v[222:223], off
	s_add_u32 s90, s90, s76
	s_addc_u32 s91, s91, s77
	s_add_i32 s8, s8, s3
	v_lshl_add_u64 v[224:225], s[90:91], 0, v[0:1]
	s_mov_b32 m0, s8
	v_lshl_add_u64 v[226:227], s[90:91], 0, v[134:135]
	global_load_lds_dwordx4 v[224:225], off
	s_add_i32 m0, s8, 0x2000
	s_nop 0
	global_load_lds_dwordx4 v[226:227], off
	s_waitcnt vmcnt(8)
	s_waitcnt lgkmcnt(0)
	v_mfma_f32_16x16x32_bf16 v[62:65], v[142:145], v[164:167], v[62:65]
	v_mfma_f32_16x16x32_bf16 v[58:61], v[150:153], v[164:167], v[58:61]
	v_mfma_f32_16x16x32_bf16 v[46:49], v[142:145], v[172:175], v[46:49]
	v_mfma_f32_16x16x32_bf16 v[42:45], v[150:153], v[172:175], v[42:45]
	s_barrier
	s_setprio 1
	v_mfma_f32_16x16x32_bf16 v[30:33], v[142:145], v[180:183], v[30:33]
	v_mfma_f32_16x16x32_bf16 v[26:29], v[150:153], v[180:183], v[26:29]
	v_mfma_f32_16x16x32_bf16 v[14:17], v[142:145], v[188:191], v[14:17]
	v_mfma_f32_16x16x32_bf16 v[10:13], v[150:153], v[188:191], v[10:13]
	v_mfma_f32_16x16x32_bf16 v[62:65], v[146:149], v[168:171], v[62:65]
	v_mfma_f32_16x16x32_bf16 v[58:61], v[160:163], v[168:171], v[58:61]
	v_mfma_f32_16x16x32_bf16 v[46:49], v[146:149], v[176:179], v[46:49]
	v_mfma_f32_16x16x32_bf16 v[42:45], v[160:163], v[176:179], v[42:45]
	v_mfma_f32_16x16x32_bf16 v[30:33], v[146:149], v[184:187], v[30:33]
	v_mfma_f32_16x16x32_bf16 v[26:29], v[160:163], v[184:187], v[26:29]
	v_mfma_f32_16x16x32_bf16 v[14:17], v[146:149], v[196:199], v[14:17]
	v_mfma_f32_16x16x32_bf16 v[10:13], v[160:163], v[196:199], v[10:13]
	v_mfma_f32_16x16x32_bf16 v[54:57], v[200:203], v[164:167], v[54:57]
	v_mfma_f32_16x16x32_bf16 v[50:53], v[208:211], v[164:167], v[50:53]
	v_mfma_f32_16x16x32_bf16 v[38:41], v[200:203], v[172:175], v[38:41]
	v_mfma_f32_16x16x32_bf16 v[34:37], v[208:211], v[172:175], v[34:37]
	v_mfma_f32_16x16x32_bf16 v[22:25], v[200:203], v[180:183], v[22:25]
	v_mfma_f32_16x16x32_bf16 v[18:21], v[208:211], v[180:183], v[18:21]
	v_mfma_f32_16x16x32_bf16 v[6:9], v[200:203], v[188:191], v[6:9]
	v_mfma_f32_16x16x32_bf16 v[2:5], v[208:211], v[188:191], v[2:5]
	v_mfma_f32_16x16x32_bf16 v[54:57], v[204:207], v[168:171], v[54:57]
	v_mfma_f32_16x16x32_bf16 v[50:53], v[212:215], v[168:171], v[50:53]
	v_mfma_f32_16x16x32_bf16 v[38:41], v[204:207], v[176:179], v[38:41]
	v_mfma_f32_16x16x32_bf16 v[34:37], v[212:215], v[176:179], v[34:37]
	v_mfma_f32_16x16x32_bf16 v[22:25], v[204:207], v[184:187], v[22:25]
	v_mfma_f32_16x16x32_bf16 v[18:21], v[212:215], v[184:187], v[18:21]
	v_mfma_f32_16x16x32_bf16 v[6:9], v[204:207], v[196:199], v[6:9]
	v_mfma_f32_16x16x32_bf16 v[2:5], v[212:215], v[196:199], v[2:5]
	s_setprio 0
	s_barrier
; #define PG8_STAGE(bufoff, gbase, voff) do { _Pragma("unroll") for (int _i = 0; _i < 2; ++_i) \
;         __builtin_amdgcn_global_load_lds((const unsigned*)((const char*)(gbase) + (voff)[_i]), (LAS unsigned*)(lds + (bufoff) + ldsw + _i * 8192), 16, 0, 0); } while (0)
; #define PG8_LDA(dst, b, h) do { _Pragma("unroll") for (int m = 0; m < 4; ++m) _Pragma("unroll") for (int k = 0; k < 2; ++k) dst[m][k] = *(const LAS bf16x8*)(lds + PG8_SA(b, h) + aoff + m * 2048 + k * 1024); } while (0)
; #define PG8_LDB(dst, b, h) do { _Pragma("unroll") for (int n = 0; n < 2; ++n) _Pragma("unroll") for (int k = 0; k < 2; ++k) dst[n][k] = *(const LAS bf16x8*)(lds + PG8_SB(b, h) + boff + n * 2048 + k * 1024); } while (0)
; #define PG8_MMA(ai, bj, At, Bt) do { __builtin_amdgcn_s_setprio(1); _Pragma("unroll") for (int m = 0; m < 4; ++m) _Pragma("unroll") for (int n = 0; n < 2; ++n) _Pragma("unroll") for (int k = 0; k < 2; ++k) \
;         acc[ai][bj][m][n] = __builtin_amdgcn_mfma_f32_16x16x32_bf16(Bt[n][k], At[m][k], acc[ai][bj][m][n], 0, 0, 0); __builtin_amdgcn_s_setprio(0); } while (0)
; #define PG8_WAIT_L(n) asm volatile("s_waitcnt lgkmcnt(" #n ")" ::: "memory")
; #define PG8_BAR __builtin_amdgcn_s_barrier()
; #define PG8_SCHED __builtin_amdgcn_sched_barrier(0)
; template <class Epi>
; __device__ __forceinline__ void gemm_phase(LAS unsigned char* lds, const Gemm g, const Sched& S, const Epi& E) {
;     ...
;             PG8_LDB(B0, 1, 0); PG8_SCHED; PG8_LDA(At, 1, 0); PG8_STAGE(PG8_SA(0, 1), a2 + hstepA, voffA);
;             PG8_WAIT_L(8); PG8_BAR; PG8_WAIT_L(0); PG8_MMA(0, 0, At, B0); PG8_BAR; PG8_SCHED;
;             PG8_LDB(B1, 1, 1); PG8_STAGE(PG8_SB(1, 0), b3, voffB);
;             PG8_BAR; PG8_WAIT_L(0); PG8_MMA(0, 1, At, B1); PG8_BAR;
;             PG8_LDA(At, 1, 1); PG8_STAGE(PG8_SA(1, 0), a3, voffA);
;             PG8_BAR; PG8_WAIT_L(0); PG8_MMA(1, 0, At, B0); PG8_BAR; PG8_SCHED;
	s_add_i32 s8, 0, 0x18000
	v_add_u32_e32 v160, s8, v156
	ds_read_b128 v[142:145], v160
	ds_read_b128 v[146:149], v160 offset:1024
	ds_read_b128 v[150:153], v160 offset:2048
	ds_read_b128 v[160:163], v160 offset:3072
	s_add_u32 s6, s6, s36
	s_addc_u32 s7, s7, s37
	s_mov_b32 m0, s39
	v_lshl_add_u64 v[200:201], s[6:7], 0, v[130:131]
	ds_read_b128 v[164:167], v159 offset:32768
	ds_read_b128 v[168:171], v159 offset:33792
	ds_read_b128 v[172:175], v159 offset:34816
	ds_read_b128 v[176:179], v159 offset:35840
	ds_read_b128 v[180:183], v159 offset:36864
	ds_read_b128 v[184:187], v159 offset:37888
	ds_read_b128 v[188:191], v159 offset:38912
	ds_read_b128 v[196:199], v159 offset:39936
	global_load_lds_dwordx4 v[200:201], off
	v_lshl_add_u64 v[200:201], s[6:7], 0, v[132:133]
	s_mov_b32 m0, s40
	s_nop 0
	global_load_lds_dwordx4 v[200:201], off
	s_add_i32 s6, 0, 0x1c000
	v_add_u32_e32 v212, s6, v156
	ds_read_b128 v[200:203], v212
	ds_read_b128 v[204:207], v212 offset:1024
	ds_read_b128 v[208:211], v212 offset:2048
	ds_read_b128 v[212:215], v212 offset:3072
	s_waitcnt vmcnt(8)
	s_waitcnt lgkmcnt(0)
	v_mfma_f32_16x16x32_bf16 v[126:129], v[142:145], v[164:167], v[126:129]
	v_mfma_f32_16x16x32_bf16 v[122:125], v[150:153], v[164:167], v[122:125]
	v_mfma_f32_16x16x32_bf16 v[110:113], v[142:145], v[172:175], v[110:113]
	v_mfma_f32_16x16x32_bf16 v[106:109], v[150:153], v[172:175], v[106:109]
	s_barrier
	s_setprio 1
	v_mfma_f32_16x16x32_bf16 v[94:97], v[142:145], v[180:183], v[94:97]
	v_mfma_f32_16x16x32_bf16 v[90:93], v[150:153], v[180:183], v[90:93]
	v_mfma_f32_16x16x32_bf16 v[78:81], v[142:145], v[188:191], v[78:81]
	v_mfma_f32_16x16x32_bf16 v[74:77], v[150:153], v[188:191], v[74:77]
	v_mfma_f32_16x16x32_bf16 v[126:129], v[146:149], v[168:171], v[126:129]
	v_mfma_f32_16x16x32_bf16 v[122:125], v[160:163], v[168:171], v[122:125]
	v_mfma_f32_16x16x32_bf16 v[110:113], v[146:149], v[176:179], v[110:113]
	v_mfma_f32_16x16x32_bf16 v[106:109], v[160:163], v[176:179], v[106:109]
	v_mfma_f32_16x16x32_bf16 v[94:97], v[146:149], v[184:187], v[94:97]
	v_mfma_f32_16x16x32_bf16 v[90:93], v[160:163], v[184:187], v[90:93]
	v_mfma_f32_16x16x32_bf16 v[78:81], v[146:149], v[196:199], v[78:81]
	v_mfma_f32_16x16x32_bf16 v[74:77], v[160:163], v[196:199], v[74:77]
	v_mfma_f32_16x16x32_bf16 v[118:121], v[200:203], v[164:167], v[118:121]
	v_mfma_f32_16x16x32_bf16 v[114:117], v[208:211], v[164:167], v[114:117]
	v_mfma_f32_16x16x32_bf16 v[102:105], v[200:203], v[172:175], v[102:105]
	v_mfma_f32_16x16x32_bf16 v[98:101], v[208:211], v[172:175], v[98:101]
	v_mfma_f32_16x16x32_bf16 v[86:89], v[200:203], v[180:183], v[86:89]
	v_mfma_f32_16x16x32_bf16 v[82:85], v[208:211], v[180:183], v[82:85]
	v_mfma_f32_16x16x32_bf16 v[70:73], v[200:203], v[188:191], v[70:73]
	v_mfma_f32_16x16x32_bf16 v[66:69], v[208:211], v[188:191], v[66:69]
	v_mfma_f32_16x16x32_bf16 v[118:121], v[204:207], v[168:171], v[118:121]
	v_mfma_f32_16x16x32_bf16 v[114:117], v[212:215], v[168:171], v[114:117]
	v_mfma_f32_16x16x32_bf16 v[102:105], v[204:207], v[176:179], v[102:105]
	v_mfma_f32_16x16x32_bf16 v[98:101], v[212:215], v[176:179], v[98:101]
	v_mfma_f32_16x16x32_bf16 v[86:89], v[204:207], v[184:187], v[86:89]
	v_mfma_f32_16x16x32_bf16 v[82:85], v[212:215], v[184:187], v[82:85]
	v_mfma_f32_16x16x32_bf16 v[70:73], v[204:207], v[196:199], v[70:73]
	v_mfma_f32_16x16x32_bf16 v[66:69], v[212:215], v[196:199], v[66:69]
	s_setprio 0
	s_barrier
; #define PG8_STAGE(bufoff, gbase, voff) do { _Pragma("unroll") for (int _i = 0; _i < 2; ++_i) \
;         __builtin_amdgcn_global_load_lds((const unsigned*)((const char*)(gbase) + (voff)[_i]), (LAS unsigned*)(lds + (bufoff) + ldsw + _i * 8192), 16, 0, 0); } while (0)
; #define PG8_LDA(dst, b, h) do { _Pragma("unroll") for (int m = 0; m < 4; ++m) _Pragma("unroll") for (int k = 0; k < 2; ++k) dst[m][k] = *(const LAS bf16x8*)(lds + PG8_SA(b, h) + aoff + m * 2048 + k * 1024); } while (0)
; #define PG8_MMA(ai, bj, At, Bt) do { __builtin_amdgcn_s_setprio(1); _Pragma("unroll") for (int m = 0; m < 4; ++m) _Pragma("unroll") for (int n = 0; n < 2; ++n) _Pragma("unroll") for (int k = 0; k < 2; ++k) \
;         acc[ai][bj][m][n] = __builtin_amdgcn_mfma_f32_16x16x32_bf16(Bt[n][k], At[m][k], acc[ai][bj][m][n], 0, 0, 0); __builtin_amdgcn_s_setprio(0); } while (0)
; #define PG8_WAIT_V(n) asm volatile("s_waitcnt vmcnt(" #n ")" ::: "memory")
; #define PG8_WAIT_L(n) asm volatile("s_waitcnt lgkmcnt(" #n ")" ::: "memory")
; #define PG8_BAR __builtin_amdgcn_s_barrier()
; #define PG8_SCHED __builtin_amdgcn_sched_barrier(0)
; template <class Epi>
; __device__ __forceinline__ void gemm_phase(LAS unsigned char* lds, const Gemm g, const Sched& S, const Epi& E) {
;     ...
;             PG8_LDA(At, 1, 1); PG8_STAGE(PG8_SA(1, 0), a3, voffA);
;             PG8_BAR; PG8_WAIT_L(0); PG8_MMA(1, 0, At, B0); PG8_BAR; PG8_SCHED;
;             PG8_STAGE(PG8_SB(1, 1), b3 + hstepB, voffB);
;             PG8_WAIT_V(6); PG8_BAR; PG8_MMA(1, 1, At, B1); PG8_BAR;
;         }
;         E(acc, cur, wr, wc, fr, fq, pre);
;         if (!has_next) break;
	s_add_i32 s7, s8, s3
	v_lshl_add_u64 v[192:193], v[192:193], 0, s[60:61]
	s_mov_b32 m0, s7
	s_nop 0
	global_load_lds_dwordx4 v[192:193], off
	v_lshl_add_u64 v[192:193], v[194:195], 0, s[60:61]
	s_add_i32 m0, s7, 0x2000
	s_nop 0
	global_load_lds_dwordx4 v[192:193], off
	s_mov_b32 m0, s41
	v_lshl_add_u64 v[192:193], v[216:217], 0, s[60:61]
	ds_read_b128 v[164:167], v159 offset:49152
	ds_read_b128 v[168:171], v159 offset:50176
	ds_read_b128 v[172:175], v159 offset:51200
	ds_read_b128 v[176:179], v159 offset:52224
	ds_read_b128 v[180:183], v159 offset:53248
	ds_read_b128 v[184:187], v159 offset:54272
	ds_read_b128 v[188:191], v159 offset:55296
	ds_read_b128 v[196:199], v159 offset:56320
	global_load_lds_dwordx4 v[192:193], off
	v_lshl_add_u64 v[192:193], v[222:223], 0, s[60:61]
	s_mov_b32 m0, s42
	s_nop 0
	global_load_lds_dwordx4 v[192:193], off
	s_add_i32 s6, s6, s3
	v_lshl_add_u64 v[192:193], v[224:225], 0, s[60:61]
	s_mov_b32 m0, s6
	s_nop 0
	global_load_lds_dwordx4 v[192:193], off
	v_lshl_add_u64 v[192:193], v[226:227], 0, s[60:61]
	s_add_i32 m0, s6, 0x2000
	s_nop 0
	global_load_lds_dwordx4 v[192:193], off
	s_waitcnt vmcnt(8)
	s_waitcnt lgkmcnt(0)
	v_mfma_f32_16x16x32_bf16 v[62:65], v[142:145], v[164:167], v[62:65]
	v_mfma_f32_16x16x32_bf16 v[58:61], v[150:153], v[164:167], v[58:61]
	v_mfma_f32_16x16x32_bf16 v[46:49], v[142:145], v[172:175], v[46:49]
	v_mfma_f32_16x16x32_bf16 v[42:45], v[150:153], v[172:175], v[42:45]
	s_barrier
	s_setprio 1
	v_mfma_f32_16x16x32_bf16 v[30:33], v[142:145], v[180:183], v[30:33]
	v_mfma_f32_16x16x32_bf16 v[26:29], v[150:153], v[180:183], v[26:29]
	v_mfma_f32_16x16x32_bf16 v[14:17], v[142:145], v[188:191], v[14:17]
	v_mfma_f32_16x16x32_bf16 v[10:13], v[150:153], v[188:191], v[10:13]
	v_mfma_f32_16x16x32_bf16 v[62:65], v[146:149], v[168:171], v[62:65]
	v_mfma_f32_16x16x32_bf16 v[58:61], v[160:163], v[168:171], v[58:61]
	v_mfma_f32_16x16x32_bf16 v[46:49], v[146:149], v[176:179], v[46:49]
	v_mfma_f32_16x16x32_bf16 v[42:45], v[160:163], v[176:179], v[42:45]
	v_mfma_f32_16x16x32_bf16 v[30:33], v[146:149], v[184:187], v[30:33]
	v_mfma_f32_16x16x32_bf16 v[26:29], v[160:163], v[184:187], v[26:29]
	v_mfma_f32_16x16x32_bf16 v[14:17], v[146:149], v[196:199], v[14:17]
	v_mfma_f32_16x16x32_bf16 v[10:13], v[160:163], v[196:199], v[10:13]
	v_mfma_f32_16x16x32_bf16 v[54:57], v[200:203], v[164:167], v[54:57]
	v_mfma_f32_16x16x32_bf16 v[50:53], v[208:211], v[164:167], v[50:53]
	v_mfma_f32_16x16x32_bf16 v[38:41], v[200:203], v[172:175], v[38:41]
	v_mfma_f32_16x16x32_bf16 v[34:37], v[208:211], v[172:175], v[34:37]
	v_mfma_f32_16x16x32_bf16 v[22:25], v[200:203], v[180:183], v[22:25]
	v_mfma_f32_16x16x32_bf16 v[18:21], v[208:211], v[180:183], v[18:21]
	v_mfma_f32_16x16x32_bf16 v[6:9], v[200:203], v[188:191], v[6:9]
	v_mfma_f32_16x16x32_bf16 v[2:5], v[208:211], v[188:191], v[2:5]
	v_mfma_f32_16x16x32_bf16 v[54:57], v[204:207], v[168:171], v[54:57]
	v_mfma_f32_16x16x32_bf16 v[50:53], v[212:215], v[168:171], v[50:53]
	v_mfma_f32_16x16x32_bf16 v[38:41], v[204:207], v[176:179], v[38:41]
	v_mfma_f32_16x16x32_bf16 v[34:37], v[212:215], v[176:179], v[34:37]
	v_mfma_f32_16x16x32_bf16 v[22:25], v[204:207], v[184:187], v[22:25]
	v_mfma_f32_16x16x32_bf16 v[18:21], v[212:215], v[184:187], v[18:21]
	v_mfma_f32_16x16x32_bf16 v[6:9], v[204:207], v[196:199], v[6:9]
	v_mfma_f32_16x16x32_bf16 v[2:5], v[212:215], v[196:199], v[2:5]
	s_setprio 0
	s_add_u32 s4, s4, 0x100
	s_addc_u32 s5, s5, 0
	s_add_u32 s34, s34, 0x100
	s_addc_u32 s35, s35, 0
	s_cmp_ge_u32 s14, s73
	s_mov_b32 s6, s14
	s_barrier
	s_cbranch_scc0 .LBB0_555
	v_readfirstlane_b32 s98, v219
	s_nop 1
	s_bitcmp1_b32 s98, 8
	s_cbranch_scc1 .Lresync_x_555_p
	s_barrier
	s_branch .Lresync_x_555

; #define PG8_WAIT_V(n) asm volatile("s_waitcnt vmcnt(" #n ")" ::: "memory")
; #define PG8_BAR __builtin_amdgcn_s_barrier()
; template <class Epi>
; __device__ __forceinline__ void gemm_phase(LAS unsigned char* lds, const Gemm g, const Sched& S, const Epi& E) {
;     ...
;     PG8_WAIT_V(0);
;     if (wr == 0) PG8_BAR;
;     PG8_BAR;
.LBB0_621:
	s_waitcnt vmcnt(0)
	v_readlane_b32 s0, v254, 35
	v_readlane_b32 s90, v254, 39
	v_readlane_b32 s84, v254, 49
	s_setprio 0
	s_cmpk_gt_u32 s0, 0xff
	v_readlane_b32 s58, v253, 45
	v_readlane_b32 s64, v253, 47
	v_readlane_b32 s91, v254, 40
	v_readlane_b32 s85, v254, 50
	v_readlane_b32 s59, v253, 46
	s_cbranch_scc1 .LBB0_623

; #define PG8_STAGE(bufoff, gbase, voff) do { _Pragma("unroll") for (int _i = 0; _i < 2; ++_i) \
;         __builtin_amdgcn_global_load_lds((const unsigned*)((const char*)(gbase) + (voff)[_i]), (LAS unsigned*)(lds + (bufoff) + ldsw + _i * 8192), 16, 0, 0); } while (0)
; #define PG8_LDA(dst, b, h) do { _Pragma("unroll") for (int m = 0; m < 4; ++m) _Pragma("unroll") for (int k = 0; k < 2; ++k) dst[m][k] = *(const LAS bf16x8*)(lds + PG8_SA(b, h) + aoff + m * 2048 + k * 1024); } while (0)
; #define PG8_LDB(dst, b, h) do { _Pragma("unroll") for (int n = 0; n < 2; ++n) _Pragma("unroll") for (int k = 0; k < 2; ++k) dst[n][k] = *(const LAS bf16x8*)(lds + PG8_SB(b, h) + boff + n * 2048 + k * 1024); } while (0)
; #define PG8_MMA(ai, bj, At, Bt) do { __builtin_amdgcn_s_setprio(1); _Pragma("unroll") for (int m = 0; m < 4; ++m) _Pragma("unroll") for (int n = 0; n < 2; ++n) _Pragma("unroll") for (int k = 0; k < 2; ++k) \
;         acc[ai][bj][m][n] = __builtin_amdgcn_mfma_f32_16x16x32_bf16(Bt[n][k], At[m][k], acc[ai][bj][m][n], 0, 0, 0); __builtin_amdgcn_s_setprio(0); } while (0)
; #define PG8_WAIT_L(n) asm volatile("s_waitcnt lgkmcnt(" #n ")" ::: "memory")
; #define PG8_BAR __builtin_amdgcn_s_barrier()
; #define PG8_SCHED __builtin_amdgcn_sched_barrier(0)
; template <class Epi>
; __device__ __forceinline__ void gemm_phase(LAS unsigned char* lds, const Gemm g, const Sched& S, const Epi& E) {
;     ...
;         for (int t = 0; t < nt; t += 2) {
;             const bool last = (t == nt - 2);
;             const char* a1 = cA + (size_t)(t + 1) * kstep;
;             const char* a2 = last ? nA : cA + (size_t)(t + 2) * kstep; const char* b2 = last ? nB : cB + (size_t)(t + 2) * kstep;
;             const char* a3 = a2 + kstep; const char* b3 = b2 + kstep;
;             PG8_LDB(B0, 0, 0); PG8_SCHED; PG8_LDA(At, 0, 0); PG8_STAGE(PG8_SA(1, 1), a1 + hstepA, voffA);
;             PG8_WAIT_L(8); PG8_BAR; PG8_WAIT_L(0); PG8_MMA(0, 0, At, B0); PG8_BAR; PG8_SCHED;
;     ...
; #pragma unroll
;         for (int a = 0; a < 2; ++a)
; #pragma unroll
;             for (int b = 0; b < 2; ++b)
; #pragma unroll
;                 for (int m = 0; m < 4; ++m)
; #pragma unroll
;                     for (int n = 0; n < 2; ++n) acc[a][b][m][n] = (f32x4){0.f, 0.f, 0.f, 0.f};
;         cur = nxt; cA = nA; cB = nB; ++ui;
.LBB0_648:
	v_mov_b64_e32 v[2:3], s[26:27]
	v_readlane_b32 s8, v254, 11
	v_cmp_lt_i64_e32 vcc, s[82:83], v[2:3]
	v_readlane_b32 s9, v254, 12
	s_add_u32 s82, s8, s38
	s_addc_u32 s83, s9, s39
	s_and_b64 s[14:15], vcc, exec
	s_cselect_b32 s33, s83, s1
	s_cselect_b32 s48, s82, s0
	s_add_u32 s84, s10, s80
	s_addc_u32 s85, s11, s81
	s_and_b64 s[14:15], vcc, exec
	s_cselect_b32 s51, s85, s5
	s_cselect_b32 s55, s84, s4
	s_add_u32 s0, s0, 0x80
	s_addc_u32 s1, s1, 0
	s_add_u32 s34, s4, 0x100
	v_mov_b32_e32 v2, 0
	s_addc_u32 s35, s5, 0
	s_mov_b32 s4, 0
	v_mov_b32_e32 v3, v2
	v_mov_b32_e32 v4, v2
	v_mov_b32_e32 v5, v2
	v_mov_b32_e32 v6, v2
	v_mov_b32_e32 v7, v2
	v_mov_b32_e32 v8, v2
	v_mov_b32_e32 v9, v2
	v_mov_b32_e32 v18, v2
	v_mov_b32_e32 v19, v2
	v_mov_b32_e32 v20, v2
	v_mov_b32_e32 v21, v2
	v_mov_b32_e32 v22, v2
	v_mov_b32_e32 v23, v2
	v_mov_b32_e32 v24, v2
	v_mov_b32_e32 v25, v2
	v_mov_b32_e32 v34, v2
	v_mov_b32_e32 v35, v2
	v_mov_b32_e32 v36, v2
	v_mov_b32_e32 v37, v2
	v_mov_b32_e32 v38, v2
	v_mov_b32_e32 v39, v2
	v_mov_b32_e32 v40, v2
	v_mov_b32_e32 v41, v2
	v_mov_b32_e32 v50, v2
	v_mov_b32_e32 v51, v2
	v_mov_b32_e32 v52, v2
	v_mov_b32_e32 v53, v2
	v_mov_b32_e32 v54, v2
	v_mov_b32_e32 v55, v2
	v_mov_b32_e32 v56, v2
	v_mov_b32_e32 v57, v2
	v_mov_b32_e32 v10, v2
	v_mov_b32_e32 v11, v2
	v_mov_b32_e32 v12, v2
	v_mov_b32_e32 v13, v2
	v_mov_b32_e32 v14, v2
	v_mov_b32_e32 v15, v2
	v_mov_b32_e32 v16, v2
	v_mov_b32_e32 v17, v2
	v_mov_b32_e32 v26, v2
	v_mov_b32_e32 v27, v2
	v_mov_b32_e32 v28, v2
	v_mov_b32_e32 v29, v2
	v_mov_b32_e32 v30, v2
	v_mov_b32_e32 v31, v2
	v_mov_b32_e32 v32, v2
	v_mov_b32_e32 v33, v2
	v_mov_b32_e32 v42, v2
	v_mov_b32_e32 v43, v2
	v_mov_b32_e32 v44, v2
	v_mov_b32_e32 v45, v2
	v_mov_b32_e32 v46, v2
	s_waitcnt lgkmcnt(0)
	v_mov_b32_e32 v47, v2
	v_mov_b32_e32 v48, v2
	v_mov_b32_e32 v49, v2
	v_mov_b32_e32 v58, v2
	v_mov_b32_e32 v59, v2
	v_mov_b32_e32 v60, v2
	v_mov_b32_e32 v61, v2
	v_mov_b32_e32 v62, v2
	v_mov_b32_e32 v63, v2
	v_mov_b32_e32 v64, v2
	v_mov_b32_e32 v65, v2
	v_mov_b32_e32 v66, v2
	v_mov_b32_e32 v67, v2
	v_mov_b32_e32 v68, v2
	v_mov_b32_e32 v69, v2
	v_mov_b32_e32 v70, v2
	v_mov_b32_e32 v71, v2
	v_mov_b32_e32 v72, v2
	v_mov_b32_e32 v73, v2
	v_mov_b32_e32 v82, v2
	v_mov_b32_e32 v83, v2
	v_mov_b32_e32 v84, v2
	v_mov_b32_e32 v85, v2
	v_mov_b32_e32 v86, v2
	v_mov_b32_e32 v87, v2
	v_mov_b32_e32 v88, v2
	v_mov_b32_e32 v89, v2
	v_mov_b32_e32 v98, v2
	v_mov_b32_e32 v99, v2
	v_mov_b32_e32 v100, v2
	v_mov_b32_e32 v101, v2
	v_mov_b32_e32 v102, v2
	v_mov_b32_e32 v103, v2
	v_mov_b32_e32 v104, v2
	v_mov_b32_e32 v105, v2
	v_mov_b32_e32 v114, v2
	v_mov_b32_e32 v115, v2
	v_mov_b32_e32 v116, v2
	v_mov_b32_e32 v117, v2
	v_mov_b32_e32 v118, v2
	v_mov_b32_e32 v119, v2
	v_mov_b32_e32 v120, v2
	v_mov_b32_e32 v121, v2
	v_mov_b32_e32 v74, v2
	v_mov_b32_e32 v75, v2
	v_mov_b32_e32 v76, v2
	v_mov_b32_e32 v77, v2
	v_mov_b32_e32 v78, v2
	v_mov_b32_e32 v79, v2
	v_mov_b32_e32 v80, v2
	v_mov_b32_e32 v81, v2
	v_mov_b32_e32 v90, v2
	v_mov_b32_e32 v91, v2
	v_mov_b32_e32 v92, v2
	v_mov_b32_e32 v93, v2
	v_mov_b32_e32 v94, v2
	v_mov_b32_e32 v95, v2
	v_mov_b32_e32 v96, v2
	v_mov_b32_e32 v97, v2
	v_mov_b32_e32 v106, v2
	v_mov_b32_e32 v107, v2
	v_mov_b32_e32 v108, v2
	v_mov_b32_e32 v109, v2
	v_mov_b32_e32 v110, v2
	v_mov_b32_e32 v111, v2
	v_mov_b32_e32 v112, v2
	v_mov_b32_e32 v113, v2
	v_mov_b32_e32 v122, v2
	v_mov_b32_e32 v123, v2
	v_mov_b32_e32 v124, v2
	v_mov_b32_e32 v125, v2
	v_mov_b32_e32 v126, v2
	v_mov_b32_e32 v127, v2
	v_mov_b32_e32 v128, v2
	v_mov_b32_e32 v129, v2
	v_readfirstlane_b32 s98, v219
	s_nop 1
	s_bitcmp1_b32 s98, 8
	s_cbranch_scc0 .Lresync_y_649
	s_setprio 0
	s_barrier
.Lresync_y_649:
.LBB0_649:
	s_add_i32 s14, s4, 2
	s_add_u32 s8, s0, 0x80
	s_addc_u32 s5, s1, 0
	s_add_i32 s9, 0, 0x10000
	v_add_u32_e32 v144, s9, v236
	ds_read_b128 v[132:135], v144
	ds_read_b128 v[136:139], v144 offset:1024
	ds_read_b128 v[140:143], v144 offset:2048
	ds_read_b128 v[144:147], v144 offset:3072
	s_cmp_eq_u32 s95, s4
	s_cselect_b32 s4, s48, s8
	s_cselect_b32 s5, s33, s5
	s_cselect_b32 s87, s51, s35
	s_cselect_b32 s86, s55, s34
	v_lshl_add_u64 v[176:177], s[0:1], 0, v[188:189]
	s_add_i32 m0, s89, 0xc000
	ds_read_b128 v[148:151], v239
	ds_read_b128 v[152:155], v239 offset:1024
	ds_read_b128 v[156:159], v239 offset:2048
	ds_read_b128 v[160:163], v239 offset:3072
	ds_read_b128 v[164:167], v239 offset:4096
	ds_read_b128 v[168:171], v239 offset:5120
	ds_read_b128 v[172:175], v239 offset:6144
	ds_read_b128 v[196:199], v239 offset:7168
	global_load_lds_dwordx4 v[176:177], off
	v_lshl_add_u64 v[176:177], s[0:1], 0, v[190:191]
	s_add_i32 m0, s89, 0xe000
	s_nop 0
	global_load_lds_dwordx4 v[176:177], off
	s_add_i32 s8, 0, 0x14000
	v_add_u32_e32 v176, s8, v236
	ds_read_b128 v[200:203], v176
	ds_read_b128 v[204:207], v176 offset:1024
	ds_read_b128 v[208:211], v176 offset:2048
	ds_read_b128 v[212:215], v176 offset:3072
	s_waitcnt vmcnt(8)
	s_waitcnt lgkmcnt(0)
	v_mfma_f32_16x16x32_bf16 v[126:129], v[132:135], v[148:151], v[126:129]
	v_mfma_f32_16x16x32_bf16 v[122:125], v[140:143], v[148:151], v[122:125]
	v_mfma_f32_16x16x32_bf16 v[110:113], v[132:135], v[156:159], v[110:113]
	v_mfma_f32_16x16x32_bf16 v[106:109], v[140:143], v[156:159], v[106:109]
	s_barrier
; #define PG8_STAGE(bufoff, gbase, voff) do { _Pragma("unroll") for (int _i = 0; _i < 2; ++_i) \
;         __builtin_amdgcn_global_load_lds((const unsigned*)((const char*)(gbase) + (voff)[_i]), (LAS unsigned*)(lds + (bufoff) + ldsw + _i * 8192), 16, 0, 0); } while (0)
; #define PG8_LDA(dst, b, h) do { _Pragma("unroll") for (int m = 0; m < 4; ++m) _Pragma("unroll") for (int k = 0; k < 2; ++k) dst[m][k] = *(const LAS bf16x8*)(lds + PG8_SA(b, h) + aoff + m * 2048 + k * 1024); } while (0)
; #define PG8_LDB(dst, b, h) do { _Pragma("unroll") for (int n = 0; n < 2; ++n) _Pragma("unroll") for (int k = 0; k < 2; ++k) dst[n][k] = *(const LAS bf16x8*)(lds + PG8_SB(b, h) + boff + n * 2048 + k * 1024); } while (0)
; #define PG8_MMA(ai, bj, At, Bt) do { __builtin_amdgcn_s_setprio(1); _Pragma("unroll") for (int m = 0; m < 4; ++m) _Pragma("unroll") for (int n = 0; n < 2; ++n) _Pragma("unroll") for (int k = 0; k < 2; ++k) \
;         acc[ai][bj][m][n] = __builtin_amdgcn_mfma_f32_16x16x32_bf16(Bt[n][k], At[m][k], acc[ai][bj][m][n], 0, 0, 0); __builtin_amdgcn_s_setprio(0); } while (0)
; #define PG8_WAIT_V(n) asm volatile("s_waitcnt vmcnt(" #n ")" ::: "memory")
; #define PG8_WAIT_L(n) asm volatile("s_waitcnt lgkmcnt(" #n ")" ::: "memory")
; #define PG8_BAR __builtin_amdgcn_s_barrier()
; #define PG8_SCHED __builtin_amdgcn_sched_barrier(0)
; template <class Epi>
; __device__ __forceinline__ void gemm_phase(LAS unsigned char* lds, const Gemm g, const Sched& S, const Epi& E) {
;     ...
;             PG8_LDB(B0, 0, 0); PG8_SCHED; PG8_LDA(At, 0, 0); PG8_STAGE(PG8_SA(1, 1), a1 + hstepA, voffA);
;             PG8_WAIT_L(8); PG8_BAR; PG8_WAIT_L(0); PG8_MMA(0, 0, At, B0); PG8_BAR; PG8_SCHED;
;             PG8_LDB(B1, 0, 1); PG8_STAGE(PG8_SB(0, 0), b2, voffB);
;             PG8_BAR; PG8_WAIT_L(0); PG8_MMA(0, 1, At, B1); PG8_BAR;
;             PG8_LDA(At, 0, 1); PG8_STAGE(PG8_SA(0, 0), a2, voffA);
;             PG8_BAR; PG8_WAIT_L(0); PG8_MMA(1, 0, At, B0); PG8_BAR; PG8_SCHED;
;             PG8_STAGE(PG8_SB(0, 1), b2 + hstepB, voffB);
;             PG8_WAIT_V(6); PG8_BAR; PG8_MMA(1, 1, At, B1); PG8_BAR;
	s_setprio 1
	v_mfma_f32_16x16x32_bf16 v[94:97], v[132:135], v[164:167], v[94:97]
	v_mfma_f32_16x16x32_bf16 v[90:93], v[140:143], v[164:167], v[90:93]
	v_mfma_f32_16x16x32_bf16 v[78:81], v[132:135], v[172:175], v[78:81]
	v_mfma_f32_16x16x32_bf16 v[74:77], v[140:143], v[172:175], v[74:77]
	v_mfma_f32_16x16x32_bf16 v[126:129], v[136:139], v[152:155], v[126:129]
	v_mfma_f32_16x16x32_bf16 v[122:125], v[144:147], v[152:155], v[122:125]
	v_mfma_f32_16x16x32_bf16 v[110:113], v[136:139], v[160:163], v[110:113]
	v_mfma_f32_16x16x32_bf16 v[106:109], v[144:147], v[160:163], v[106:109]
	v_mfma_f32_16x16x32_bf16 v[94:97], v[136:139], v[168:171], v[94:97]
	v_mfma_f32_16x16x32_bf16 v[90:93], v[144:147], v[168:171], v[90:93]
	v_mfma_f32_16x16x32_bf16 v[78:81], v[136:139], v[196:199], v[78:81]
	v_mfma_f32_16x16x32_bf16 v[74:77], v[144:147], v[196:199], v[74:77]
	v_mfma_f32_16x16x32_bf16 v[118:121], v[200:203], v[148:151], v[118:121]
	v_mfma_f32_16x16x32_bf16 v[114:117], v[208:211], v[148:151], v[114:117]
	v_mfma_f32_16x16x32_bf16 v[102:105], v[200:203], v[156:159], v[102:105]
	v_mfma_f32_16x16x32_bf16 v[98:101], v[208:211], v[156:159], v[98:101]
	v_mfma_f32_16x16x32_bf16 v[86:89], v[200:203], v[164:167], v[86:89]
	v_mfma_f32_16x16x32_bf16 v[82:85], v[208:211], v[164:167], v[82:85]
	v_mfma_f32_16x16x32_bf16 v[70:73], v[200:203], v[172:175], v[70:73]
	v_mfma_f32_16x16x32_bf16 v[66:69], v[208:211], v[172:175], v[66:69]
	v_mfma_f32_16x16x32_bf16 v[118:121], v[204:207], v[152:155], v[118:121]
	v_mfma_f32_16x16x32_bf16 v[114:117], v[212:215], v[152:155], v[114:117]
	v_mfma_f32_16x16x32_bf16 v[102:105], v[204:207], v[160:163], v[102:105]
	v_mfma_f32_16x16x32_bf16 v[98:101], v[212:215], v[160:163], v[98:101]
	v_mfma_f32_16x16x32_bf16 v[86:89], v[204:207], v[168:171], v[86:89]
	v_mfma_f32_16x16x32_bf16 v[82:85], v[212:215], v[168:171], v[82:85]
	v_mfma_f32_16x16x32_bf16 v[70:73], v[204:207], v[196:199], v[70:73]
	v_mfma_f32_16x16x32_bf16 v[66:69], v[212:215], v[196:199], v[66:69]
	s_setprio 0
	s_barrier
	s_add_i32 s9, s9, s88
	v_lshl_add_u64 v[176:177], s[86:87], 0, v[180:181]
	s_mov_b32 m0, s9
	v_lshl_add_u64 v[192:193], s[86:87], 0, v[184:185]
	global_load_lds_dwordx4 v[176:177], off
	s_add_i32 m0, s9, 0x2000
	s_nop 0
	global_load_lds_dwordx4 v[192:193], off
	s_mov_b32 m0, s89
	v_lshl_add_u64 v[194:195], s[4:5], 0, v[178:179]
	ds_read_b128 v[148:151], v239 offset:16384
	ds_read_b128 v[152:155], v239 offset:17408
	ds_read_b128 v[156:159], v239 offset:18432
	ds_read_b128 v[160:163], v239 offset:19456
	ds_read_b128 v[164:167], v239 offset:20480
	ds_read_b128 v[168:171], v239 offset:21504
	ds_read_b128 v[172:175], v239 offset:22528
	ds_read_b128 v[196:199], v239 offset:23552
	global_load_lds_dwordx4 v[194:195], off
	v_lshl_add_u64 v[216:217], s[4:5], 0, v[182:183]
	s_mov_b32 m0, s90
	s_nop 0
	global_load_lds_dwordx4 v[216:217], off
	s_add_u32 s56, s86, s36
	s_addc_u32 s57, s87, s37
	s_add_i32 s8, s8, s88
	v_lshl_add_u64 v[222:223], s[56:57], 0, v[180:181]
	s_mov_b32 m0, s8
	v_lshl_add_u64 v[224:225], s[56:57], 0, v[184:185]
	global_load_lds_dwordx4 v[222:223], off
	s_add_i32 m0, s8, 0x2000
	s_nop 0
	global_load_lds_dwordx4 v[224:225], off
	s_waitcnt vmcnt(8)
	s_waitcnt lgkmcnt(0)
	v_mfma_f32_16x16x32_bf16 v[62:65], v[132:135], v[148:151], v[62:65]
	v_mfma_f32_16x16x32_bf16 v[58:61], v[140:143], v[148:151], v[58:61]
	v_mfma_f32_16x16x32_bf16 v[46:49], v[132:135], v[156:159], v[46:49]
	v_mfma_f32_16x16x32_bf16 v[42:45], v[140:143], v[156:159], v[42:45]
	s_barrier
	s_setprio 1
	v_mfma_f32_16x16x32_bf16 v[30:33], v[132:135], v[164:167], v[30:33]
	v_mfma_f32_16x16x32_bf16 v[26:29], v[140:143], v[164:167], v[26:29]
	v_mfma_f32_16x16x32_bf16 v[14:17], v[132:135], v[172:175], v[14:17]
	v_mfma_f32_16x16x32_bf16 v[10:13], v[140:143], v[172:175], v[10:13]
	v_mfma_f32_16x16x32_bf16 v[62:65], v[136:139], v[152:155], v[62:65]
	v_mfma_f32_16x16x32_bf16 v[58:61], v[144:147], v[152:155], v[58:61]
	v_mfma_f32_16x16x32_bf16 v[46:49], v[136:139], v[160:163], v[46:49]
	v_mfma_f32_16x16x32_bf16 v[42:45], v[144:147], v[160:163], v[42:45]
	v_mfma_f32_16x16x32_bf16 v[30:33], v[136:139], v[168:171], v[30:33]
	v_mfma_f32_16x16x32_bf16 v[26:29], v[144:147], v[168:171], v[26:29]
	v_mfma_f32_16x16x32_bf16 v[14:17], v[136:139], v[196:199], v[14:17]
	v_mfma_f32_16x16x32_bf16 v[10:13], v[144:147], v[196:199], v[10:13]
	v_mfma_f32_16x16x32_bf16 v[54:57], v[200:203], v[148:151], v[54:57]
	v_mfma_f32_16x16x32_bf16 v[50:53], v[208:211], v[148:151], v[50:53]
	v_mfma_f32_16x16x32_bf16 v[38:41], v[200:203], v[156:159], v[38:41]
	v_mfma_f32_16x16x32_bf16 v[34:37], v[208:211], v[156:159], v[34:37]
	v_mfma_f32_16x16x32_bf16 v[22:25], v[200:203], v[164:167], v[22:25]
	v_mfma_f32_16x16x32_bf16 v[18:21], v[208:211], v[164:167], v[18:21]
	v_mfma_f32_16x16x32_bf16 v[6:9], v[200:203], v[172:175], v[6:9]
	v_mfma_f32_16x16x32_bf16 v[2:5], v[208:211], v[172:175], v[2:5]
	v_mfma_f32_16x16x32_bf16 v[54:57], v[204:207], v[152:155], v[54:57]
	v_mfma_f32_16x16x32_bf16 v[50:53], v[212:215], v[152:155], v[50:53]
	v_mfma_f32_16x16x32_bf16 v[38:41], v[204:207], v[160:163], v[38:41]
	v_mfma_f32_16x16x32_bf16 v[34:37], v[212:215], v[160:163], v[34:37]
	v_mfma_f32_16x16x32_bf16 v[22:25], v[204:207], v[168:171], v[22:25]
	v_mfma_f32_16x16x32_bf16 v[18:21], v[212:215], v[168:171], v[18:21]
	v_mfma_f32_16x16x32_bf16 v[6:9], v[204:207], v[196:199], v[6:9]
	v_mfma_f32_16x16x32_bf16 v[2:5], v[212:215], v[196:199], v[2:5]
	s_setprio 0
	s_barrier
; #define PG8_STAGE(bufoff, gbase, voff) do { _Pragma("unroll") for (int _i = 0; _i < 2; ++_i) \
;         __builtin_amdgcn_global_load_lds((const unsigned*)((const char*)(gbase) + (voff)[_i]), (LAS unsigned*)(lds + (bufoff) + ldsw + _i * 8192), 16, 0, 0); } while (0)
; #define PG8_LDA(dst, b, h) do { _Pragma("unroll") for (int m = 0; m < 4; ++m) _Pragma("unroll") for (int k = 0; k < 2; ++k) dst[m][k] = *(const LAS bf16x8*)(lds + PG8_SA(b, h) + aoff + m * 2048 + k * 1024); } while (0)
; #define PG8_LDB(dst, b, h) do { _Pragma("unroll") for (int n = 0; n < 2; ++n) _Pragma("unroll") for (int k = 0; k < 2; ++k) dst[n][k] = *(const LAS bf16x8*)(lds + PG8_SB(b, h) + boff + n * 2048 + k * 1024); } while (0)
; #define PG8_MMA(ai, bj, At, Bt) do { __builtin_amdgcn_s_setprio(1); _Pragma("unroll") for (int m = 0; m < 4; ++m) _Pragma("unroll") for (int n = 0; n < 2; ++n) _Pragma("unroll") for (int k = 0; k < 2; ++k) \
;         acc[ai][bj][m][n] = __builtin_amdgcn_mfma_f32_16x16x32_bf16(Bt[n][k], At[m][k], acc[ai][bj][m][n], 0, 0, 0); __builtin_amdgcn_s_setprio(0); } while (0)
; #define PG8_WAIT_L(n) asm volatile("s_waitcnt lgkmcnt(" #n ")" ::: "memory")
; #define PG8_BAR __builtin_amdgcn_s_barrier()
; #define PG8_SCHED __builtin_amdgcn_sched_barrier(0)
; template <class Epi>
; __device__ __forceinline__ void gemm_phase(LAS unsigned char* lds, const Gemm g, const Sched& S, const Epi& E) {
;     ...
;             PG8_LDB(B0, 1, 0); PG8_SCHED; PG8_LDA(At, 1, 0); PG8_STAGE(PG8_SA(0, 1), a2 + hstepA, voffA);
;             PG8_WAIT_L(8); PG8_BAR; PG8_WAIT_L(0); PG8_MMA(0, 0, At, B0); PG8_BAR; PG8_SCHED;
;             PG8_LDB(B1, 1, 1); PG8_STAGE(PG8_SB(1, 0), b3, voffB);
;             PG8_BAR; PG8_WAIT_L(0); PG8_MMA(0, 1, At, B1); PG8_BAR;
;             PG8_LDA(At, 1, 1); PG8_STAGE(PG8_SA(1, 0), a3, voffA);
;             PG8_BAR; PG8_WAIT_L(0); PG8_MMA(1, 0, At, B0); PG8_BAR; PG8_SCHED;
	s_add_i32 s8, 0, 0x18000
	v_add_u32_e32 v144, s8, v236
	ds_read_b128 v[132:135], v144
	ds_read_b128 v[136:139], v144 offset:1024
	ds_read_b128 v[140:143], v144 offset:2048
	ds_read_b128 v[144:147], v144 offset:3072
	s_add_u32 s4, s4, s6
	s_addc_u32 s5, s5, s7
	s_mov_b32 m0, s91
	v_lshl_add_u64 v[200:201], s[4:5], 0, v[178:179]
	ds_read_b128 v[148:151], v239 offset:32768
	ds_read_b128 v[152:155], v239 offset:33792
	ds_read_b128 v[156:159], v239 offset:34816
	ds_read_b128 v[160:163], v239 offset:35840
	ds_read_b128 v[164:167], v239 offset:36864
	ds_read_b128 v[168:171], v239 offset:37888
	ds_read_b128 v[172:175], v239 offset:38912
	ds_read_b128 v[196:199], v239 offset:39936
	global_load_lds_dwordx4 v[200:201], off
	v_lshl_add_u64 v[200:201], s[4:5], 0, v[182:183]
	s_mov_b32 m0, s92
	s_nop 0
	global_load_lds_dwordx4 v[200:201], off
	s_add_i32 s4, 0, 0x1c000
	v_add_u32_e32 v212, s4, v236
	ds_read_b128 v[200:203], v212
	ds_read_b128 v[204:207], v212 offset:1024
	ds_read_b128 v[208:211], v212 offset:2048
	ds_read_b128 v[212:215], v212 offset:3072
	s_waitcnt vmcnt(8)
	s_waitcnt lgkmcnt(0)
	v_mfma_f32_16x16x32_bf16 v[126:129], v[132:135], v[148:151], v[126:129]
	v_mfma_f32_16x16x32_bf16 v[122:125], v[140:143], v[148:151], v[122:125]
	v_mfma_f32_16x16x32_bf16 v[110:113], v[132:135], v[156:159], v[110:113]
	v_mfma_f32_16x16x32_bf16 v[106:109], v[140:143], v[156:159], v[106:109]
	s_barrier
	s_setprio 1
	v_mfma_f32_16x16x32_bf16 v[94:97], v[132:135], v[164:167], v[94:97]
	v_mfma_f32_16x16x32_bf16 v[90:93], v[140:143], v[164:167], v[90:93]
	v_mfma_f32_16x16x32_bf16 v[78:81], v[132:135], v[172:175], v[78:81]
	v_mfma_f32_16x16x32_bf16 v[74:77], v[140:143], v[172:175], v[74:77]
	v_mfma_f32_16x16x32_bf16 v[126:129], v[136:139], v[152:155], v[126:129]
	v_mfma_f32_16x16x32_bf16 v[122:125], v[144:147], v[152:155], v[122:125]
	v_mfma_f32_16x16x32_bf16 v[110:113], v[136:139], v[160:163], v[110:113]
	v_mfma_f32_16x16x32_bf16 v[106:109], v[144:147], v[160:163], v[106:109]
	v_mfma_f32_16x16x32_bf16 v[94:97], v[136:139], v[168:171], v[94:97]
	v_mfma_f32_16x16x32_bf16 v[90:93], v[144:147], v[168:171], v[90:93]
	v_mfma_f32_16x16x32_bf16 v[78:81], v[136:139], v[196:199], v[78:81]
	v_mfma_f32_16x16x32_bf16 v[74:77], v[144:147], v[196:199], v[74:77]
	v_mfma_f32_16x16x32_bf16 v[118:121], v[200:203], v[148:151], v[118:121]
	v_mfma_f32_16x16x32_bf16 v[114:117], v[208:211], v[148:151], v[114:117]
	v_mfma_f32_16x16x32_bf16 v[102:105], v[200:203], v[156:159], v[102:105]
	v_mfma_f32_16x16x32_bf16 v[98:101], v[208:211], v[156:159], v[98:101]
	v_mfma_f32_16x16x32_bf16 v[86:89], v[200:203], v[164:167], v[86:89]
	v_mfma_f32_16x16x32_bf16 v[82:85], v[208:211], v[164:167], v[82:85]
	v_mfma_f32_16x16x32_bf16 v[70:73], v[200:203], v[172:175], v[70:73]
	v_mfma_f32_16x16x32_bf16 v[66:69], v[208:211], v[172:175], v[66:69]
	v_mfma_f32_16x16x32_bf16 v[118:121], v[204:207], v[152:155], v[118:121]
	v_mfma_f32_16x16x32_bf16 v[114:117], v[212:215], v[152:155], v[114:117]
	v_mfma_f32_16x16x32_bf16 v[102:105], v[204:207], v[160:163], v[102:105]
	v_mfma_f32_16x16x32_bf16 v[98:101], v[212:215], v[160:163], v[98:101]
	v_mfma_f32_16x16x32_bf16 v[86:89], v[204:207], v[168:171], v[86:89]
	v_mfma_f32_16x16x32_bf16 v[82:85], v[212:215], v[168:171], v[82:85]
	v_mfma_f32_16x16x32_bf16 v[70:73], v[204:207], v[196:199], v[70:73]
	v_mfma_f32_16x16x32_bf16 v[66:69], v[212:215], v[196:199], v[66:69]
	s_setprio 0
	s_barrier
; #define PG8_STAGE(bufoff, gbase, voff) do { _Pragma("unroll") for (int _i = 0; _i < 2; ++_i) \
;         __builtin_amdgcn_global_load_lds((const unsigned*)((const char*)(gbase) + (voff)[_i]), (LAS unsigned*)(lds + (bufoff) + ldsw + _i * 8192), 16, 0, 0); } while (0)
; #define PG8_LDA(dst, b, h) do { _Pragma("unroll") for (int m = 0; m < 4; ++m) _Pragma("unroll") for (int k = 0; k < 2; ++k) dst[m][k] = *(const LAS bf16x8*)(lds + PG8_SA(b, h) + aoff + m * 2048 + k * 1024); } while (0)
; #define PG8_MMA(ai, bj, At, Bt) do { __builtin_amdgcn_s_setprio(1); _Pragma("unroll") for (int m = 0; m < 4; ++m) _Pragma("unroll") for (int n = 0; n < 2; ++n) _Pragma("unroll") for (int k = 0; k < 2; ++k) \
;         acc[ai][bj][m][n] = __builtin_amdgcn_mfma_f32_16x16x32_bf16(Bt[n][k], At[m][k], acc[ai][bj][m][n], 0, 0, 0); __builtin_amdgcn_s_setprio(0); } while (0)
; #define PG8_WAIT_V(n) asm volatile("s_waitcnt vmcnt(" #n ")" ::: "memory")
; #define PG8_WAIT_L(n) asm volatile("s_waitcnt lgkmcnt(" #n ")" ::: "memory")
; #define PG8_BAR __builtin_amdgcn_s_barrier()
; #define PG8_SCHED __builtin_amdgcn_sched_barrier(0)
; template <class Epi>
; __device__ __forceinline__ void gemm_phase(LAS unsigned char* lds, const Gemm g, const Sched& S, const Epi& E) {
;     ...
;             PG8_LDA(At, 1, 1); PG8_STAGE(PG8_SA(1, 0), a3, voffA);
;             PG8_BAR; PG8_WAIT_L(0); PG8_MMA(1, 0, At, B0); PG8_BAR; PG8_SCHED;
;             PG8_STAGE(PG8_SB(1, 1), b3 + hstepB, voffB);
;             PG8_WAIT_V(6); PG8_BAR; PG8_MMA(1, 1, At, B1); PG8_BAR;
;         }
;         E(acc, cur, wr, wc, fr, fq, pre);
;         if (!has_next) break;
	s_add_i32 s5, s8, s88
	v_lshl_add_u64 v[176:177], v[176:177], 0, s[60:61]
	s_mov_b32 m0, s5
	s_nop 0
	global_load_lds_dwordx4 v[176:177], off
	v_lshl_add_u64 v[176:177], v[192:193], 0, s[60:61]
	s_add_i32 m0, s5, 0x2000
	s_nop 0
	global_load_lds_dwordx4 v[176:177], off
	s_mov_b32 m0, s93
	v_lshl_add_u64 v[176:177], v[194:195], 0, s[60:61]
	ds_read_b128 v[148:151], v239 offset:49152
	ds_read_b128 v[152:155], v239 offset:50176
	ds_read_b128 v[156:159], v239 offset:51200
	ds_read_b128 v[160:163], v239 offset:52224
	ds_read_b128 v[164:167], v239 offset:53248
	ds_read_b128 v[168:171], v239 offset:54272
	ds_read_b128 v[172:175], v239 offset:55296
	ds_read_b128 v[196:199], v239 offset:56320
	global_load_lds_dwordx4 v[176:177], off
	v_lshl_add_u64 v[176:177], v[216:217], 0, s[60:61]
	s_mov_b32 m0, s94
	s_nop 0
	global_load_lds_dwordx4 v[176:177], off
	s_add_i32 s4, s4, s88
	v_lshl_add_u64 v[176:177], v[222:223], 0, s[60:61]
	s_mov_b32 m0, s4
	s_nop 0
	global_load_lds_dwordx4 v[176:177], off
	v_lshl_add_u64 v[176:177], v[224:225], 0, s[60:61]
	s_add_i32 m0, s4, 0x2000
	s_nop 0
	global_load_lds_dwordx4 v[176:177], off
	s_waitcnt vmcnt(8)
	s_waitcnt lgkmcnt(0)
	v_mfma_f32_16x16x32_bf16 v[62:65], v[132:135], v[148:151], v[62:65]
	v_mfma_f32_16x16x32_bf16 v[58:61], v[140:143], v[148:151], v[58:61]
	v_mfma_f32_16x16x32_bf16 v[46:49], v[132:135], v[156:159], v[46:49]
	v_mfma_f32_16x16x32_bf16 v[42:45], v[140:143], v[156:159], v[42:45]
	s_barrier
	s_setprio 1
	v_mfma_f32_16x16x32_bf16 v[30:33], v[132:135], v[164:167], v[30:33]
	v_mfma_f32_16x16x32_bf16 v[26:29], v[140:143], v[164:167], v[26:29]
	v_mfma_f32_16x16x32_bf16 v[14:17], v[132:135], v[172:175], v[14:17]
	v_mfma_f32_16x16x32_bf16 v[10:13], v[140:143], v[172:175], v[10:13]
	v_mfma_f32_16x16x32_bf16 v[62:65], v[136:139], v[152:155], v[62:65]
	v_mfma_f32_16x16x32_bf16 v[58:61], v[144:147], v[152:155], v[58:61]
	v_mfma_f32_16x16x32_bf16 v[46:49], v[136:139], v[160:163], v[46:49]
	v_mfma_f32_16x16x32_bf16 v[42:45], v[144:147], v[160:163], v[42:45]
	v_mfma_f32_16x16x32_bf16 v[30:33], v[136:139], v[168:171], v[30:33]
	v_mfma_f32_16x16x32_bf16 v[26:29], v[144:147], v[168:171], v[26:29]
	v_mfma_f32_16x16x32_bf16 v[14:17], v[136:139], v[196:199], v[14:17]
	v_mfma_f32_16x16x32_bf16 v[10:13], v[144:147], v[196:199], v[10:13]
	v_mfma_f32_16x16x32_bf16 v[54:57], v[200:203], v[148:151], v[54:57]
	v_mfma_f32_16x16x32_bf16 v[50:53], v[208:211], v[148:151], v[50:53]
	v_mfma_f32_16x16x32_bf16 v[38:41], v[200:203], v[156:159], v[38:41]
	v_mfma_f32_16x16x32_bf16 v[34:37], v[208:211], v[156:159], v[34:37]
	v_mfma_f32_16x16x32_bf16 v[22:25], v[200:203], v[164:167], v[22:25]
	v_mfma_f32_16x16x32_bf16 v[18:21], v[208:211], v[164:167], v[18:21]
	v_mfma_f32_16x16x32_bf16 v[6:9], v[200:203], v[172:175], v[6:9]
	v_mfma_f32_16x16x32_bf16 v[2:5], v[208:211], v[172:175], v[2:5]
	v_mfma_f32_16x16x32_bf16 v[54:57], v[204:207], v[152:155], v[54:57]
	v_mfma_f32_16x16x32_bf16 v[50:53], v[212:215], v[152:155], v[50:53]
	v_mfma_f32_16x16x32_bf16 v[38:41], v[204:207], v[160:163], v[38:41]
	v_mfma_f32_16x16x32_bf16 v[34:37], v[212:215], v[160:163], v[34:37]
	v_mfma_f32_16x16x32_bf16 v[22:25], v[204:207], v[168:171], v[22:25]
	v_mfma_f32_16x16x32_bf16 v[18:21], v[212:215], v[168:171], v[18:21]
	v_mfma_f32_16x16x32_bf16 v[6:9], v[204:207], v[196:199], v[6:9]
	v_mfma_f32_16x16x32_bf16 v[2:5], v[212:215], v[196:199], v[2:5]
	s_setprio 0
	s_add_u32 s0, s0, 0x100
	s_addc_u32 s1, s1, 0
	s_add_u32 s34, s34, 0x100
	s_addc_u32 s35, s35, 0
	s_cmp_ge_u32 s14, s73
	s_mov_b32 s4, s14
	s_barrier
	s_cbranch_scc0 .LBB0_649
	v_readfirstlane_b32 s98, v219
	s_nop 1
	s_bitcmp1_b32 s98, 8
	s_cbranch_scc1 .Lresync_x_649_p
	s_barrier
	s_branch .Lresync_x_649

; #define PG8_WAIT_V(n) asm volatile("s_waitcnt vmcnt(" #n ")" ::: "memory")
; #define PG8_BAR __builtin_amdgcn_s_barrier()
; template <class Epi>
; __device__ __forceinline__ void gemm_phase(LAS unsigned char* lds, const Gemm g, const Sched& S, const Epi& E) {
;     ...
;     PG8_WAIT_V(0);
;     if (wr == 0) PG8_BAR;
;     PG8_BAR;
.LBB0_691:
	s_waitcnt vmcnt(0)
	v_readlane_b32 s0, v254, 29
	v_readlane_b32 s90, v254, 39
	s_setprio 0
	s_cmpk_gt_u32 s0, 0xff
	v_readlane_b32 s96, v253, 48
	s_mov_b32 s97, 0x800000
	v_readlane_b32 s91, v254, 40
	s_cbranch_scc1 .LBB0_693

; #define PG8_STAGE(bufoff, gbase, voff) do { _Pragma("unroll") for (int _i = 0; _i < 2; ++_i) \
;         __builtin_amdgcn_global_load_lds((const unsigned*)((const char*)(gbase) + (voff)[_i]), (LAS unsigned*)(lds + (bufoff) + ldsw + _i * 8192), 16, 0, 0); } while (0)
; #define PG8_LDA(dst, b, h) do { _Pragma("unroll") for (int m = 0; m < 4; ++m) _Pragma("unroll") for (int k = 0; k < 2; ++k) dst[m][k] = *(const LAS bf16x8*)(lds + PG8_SA(b, h) + aoff + m * 2048 + k * 1024); } while (0)
; #define PG8_LDB(dst, b, h) do { _Pragma("unroll") for (int n = 0; n < 2; ++n) _Pragma("unroll") for (int k = 0; k < 2; ++k) dst[n][k] = *(const LAS bf16x8*)(lds + PG8_SB(b, h) + boff + n * 2048 + k * 1024); } while (0)
; #define PG8_MMA(ai, bj, At, Bt) do { __builtin_amdgcn_s_setprio(1); _Pragma("unroll") for (int m = 0; m < 4; ++m) _Pragma("unroll") for (int n = 0; n < 2; ++n) _Pragma("unroll") for (int k = 0; k < 2; ++k) \
;         acc[ai][bj][m][n] = __builtin_amdgcn_mfma_f32_16x16x32_bf16(Bt[n][k], At[m][k], acc[ai][bj][m][n], 0, 0, 0); __builtin_amdgcn_s_setprio(0); } while (0)
; #define PG8_WAIT_L(n) asm volatile("s_waitcnt lgkmcnt(" #n ")" ::: "memory")
; #define PG8_BAR __builtin_amdgcn_s_barrier()
; template <class Epi>
; __device__ __forceinline__ void gemm_phase(LAS unsigned char* lds, const Gemm g, const Sched& S, const Epi& E) {
;     ...
;         for (int t = 0; t < nt; t += 2) {
;             const bool last = (t == nt - 2);
;             const char* a1 = cA + (size_t)(t + 1) * kstep;
;             const char* a2 = last ? nA : cA + (size_t)(t + 2) * kstep; const char* b2 = last ? nB : cB + (size_t)(t + 2) * kstep;
;             const char* a3 = a2 + kstep; const char* b3 = b2 + kstep;
;             PG8_LDB(B0, 0, 0); PG8_SCHED; PG8_LDA(At, 0, 0); PG8_STAGE(PG8_SA(1, 1), a1 + hstepA, voffA);
;             PG8_WAIT_L(8); PG8_BAR; PG8_WAIT_L(0); PG8_MMA(0, 0, At, B0); PG8_BAR; PG8_SCHED;
;             PG8_LDB(B1, 0, 1); PG8_STAGE(PG8_SB(0, 0), b2, voffB);
;             PG8_BAR; PG8_WAIT_L(0); PG8_MMA(0, 1, At, B1); PG8_BAR;
;     ...
; #pragma unroll
;         for (int a = 0; a < 2; ++a)
; #pragma unroll
;             for (int b = 0; b < 2; ++b)
; #pragma unroll
;                 for (int m = 0; m < 4; ++m)
; #pragma unroll
;                     for (int n = 0; n < 2; ++n) acc[a][b][m][n] = (f32x4){0.f, 0.f, 0.f, 0.f};
;         cur = nxt; cA = nA; cB = nB; ++ui;
.LBB0_718:
	v_mov_b64_e32 v[2:3], s[26:27]
	v_readlane_b32 s8, v254, 11
	v_cmp_lt_i64_e32 vcc, s[90:91], v[2:3]
	v_readlane_b32 s9, v254, 12
	s_add_u32 s90, s8, s86
	s_addc_u32 s91, s9, s87
	s_and_b64 s[14:15], vcc, exec
	s_cselect_b32 s57, s91, s1
	s_cselect_b32 s59, s90, s0
	s_add_u32 s92, s10, s88
	s_addc_u32 s93, s11, s89
	s_and_b64 s[14:15], vcc, exec
	s_cselect_b32 vcc_lo, s93, s5
	s_cselect_b32 vcc_hi, s92, s4
	s_add_u32 s0, s0, 0x80
	s_addc_u32 s1, s1, 0
	s_add_u32 s34, s4, 0x100
	v_mov_b32_e32 v2, 0
	s_addc_u32 s35, s5, 0
	s_mov_b32 s4, 0
	v_mov_b32_e32 v3, v2
	v_mov_b32_e32 v4, v2
	v_mov_b32_e32 v5, v2
	v_mov_b32_e32 v6, v2
	v_mov_b32_e32 v7, v2
	v_mov_b32_e32 v8, v2
	v_mov_b32_e32 v9, v2
	v_mov_b32_e32 v18, v2
	v_mov_b32_e32 v19, v2
	v_mov_b32_e32 v20, v2
	v_mov_b32_e32 v21, v2
	v_mov_b32_e32 v22, v2
	v_mov_b32_e32 v23, v2
	v_mov_b32_e32 v24, v2
	v_mov_b32_e32 v25, v2
	v_mov_b32_e32 v34, v2
	v_mov_b32_e32 v35, v2
	v_mov_b32_e32 v36, v2
	v_mov_b32_e32 v37, v2
	v_mov_b32_e32 v38, v2
	v_mov_b32_e32 v39, v2
	v_mov_b32_e32 v40, v2
	v_mov_b32_e32 v41, v2
	v_mov_b32_e32 v50, v2
	v_mov_b32_e32 v51, v2
	v_mov_b32_e32 v52, v2
	v_mov_b32_e32 v53, v2
	v_mov_b32_e32 v54, v2
	v_mov_b32_e32 v55, v2
	v_mov_b32_e32 v56, v2
	v_mov_b32_e32 v57, v2
	v_mov_b32_e32 v10, v2
	v_mov_b32_e32 v11, v2
	v_mov_b32_e32 v12, v2
	v_mov_b32_e32 v13, v2
	v_mov_b32_e32 v14, v2
	v_mov_b32_e32 v15, v2
	v_mov_b32_e32 v16, v2
	v_mov_b32_e32 v17, v2
	v_mov_b32_e32 v26, v2
	v_mov_b32_e32 v27, v2
	v_mov_b32_e32 v28, v2
	v_mov_b32_e32 v29, v2
	v_mov_b32_e32 v30, v2
	v_mov_b32_e32 v31, v2
	v_mov_b32_e32 v32, v2
	v_mov_b32_e32 v33, v2
	v_mov_b32_e32 v42, v2
	v_mov_b32_e32 v43, v2
	v_mov_b32_e32 v44, v2
	v_mov_b32_e32 v45, v2
	v_mov_b32_e32 v46, v2
	v_mov_b32_e32 v47, v2
	v_mov_b32_e32 v48, v2
	v_mov_b32_e32 v49, v2
	v_mov_b32_e32 v58, v2
	v_mov_b32_e32 v59, v2
	v_mov_b32_e32 v60, v2
	v_mov_b32_e32 v61, v2
	v_mov_b32_e32 v62, v2
	v_mov_b32_e32 v63, v2
	v_mov_b32_e32 v64, v2
	v_mov_b32_e32 v65, v2
	v_mov_b32_e32 v66, v2
	v_mov_b32_e32 v67, v2
	v_mov_b32_e32 v68, v2
	v_mov_b32_e32 v69, v2
	v_mov_b32_e32 v70, v2
	v_mov_b32_e32 v71, v2
	v_mov_b32_e32 v72, v2
	v_mov_b32_e32 v73, v2
	v_mov_b32_e32 v82, v2
	v_mov_b32_e32 v83, v2
	v_mov_b32_e32 v84, v2
	v_mov_b32_e32 v85, v2
	v_mov_b32_e32 v86, v2
	v_mov_b32_e32 v87, v2
	v_mov_b32_e32 v88, v2
	v_mov_b32_e32 v89, v2
	v_mov_b32_e32 v98, v2
	v_mov_b32_e32 v99, v2
	v_mov_b32_e32 v100, v2
	v_mov_b32_e32 v101, v2
	v_mov_b32_e32 v102, v2
	v_mov_b32_e32 v103, v2
	v_mov_b32_e32 v104, v2
	v_mov_b32_e32 v105, v2
	v_mov_b32_e32 v178, v2
	v_mov_b32_e32 v179, v2
	v_mov_b32_e32 v180, v2
	v_mov_b32_e32 v181, v2
	v_mov_b32_e32 v182, v2
	v_mov_b32_e32 v183, v2
	v_mov_b32_e32 v184, v2
	v_mov_b32_e32 v185, v2
	v_mov_b32_e32 v74, v2
	v_mov_b32_e32 v75, v2
	v_mov_b32_e32 v76, v2
	v_mov_b32_e32 v77, v2
	v_mov_b32_e32 v78, v2
	v_mov_b32_e32 v79, v2
	v_mov_b32_e32 v80, v2
	v_mov_b32_e32 v81, v2
	v_mov_b32_e32 v90, v2
	v_mov_b32_e32 v91, v2
	v_mov_b32_e32 v92, v2
	v_mov_b32_e32 v93, v2
	v_mov_b32_e32 v94, v2
	v_mov_b32_e32 v95, v2
	v_mov_b32_e32 v96, v2
	v_mov_b32_e32 v97, v2
	v_mov_b32_e32 v162, v2
	v_mov_b32_e32 v163, v2
	v_mov_b32_e32 v164, v2
	v_mov_b32_e32 v165, v2
	v_mov_b32_e32 v174, v2
	v_mov_b32_e32 v175, v2
	v_mov_b32_e32 v176, v2
	v_mov_b32_e32 v177, v2
	v_mov_b32_e32 v186, v2
	v_mov_b32_e32 v187, v2
	v_mov_b32_e32 v188, v2
	v_mov_b32_e32 v189, v2
	v_mov_b32_e32 v190, v2
	v_mov_b32_e32 v191, v2
	v_mov_b32_e32 v192, v2
	v_mov_b32_e32 v193, v2
	v_readfirstlane_b32 s98, v219
	s_nop 1
	s_bitcmp1_b32 s98, 8
	s_cbranch_scc0 .Lresync_y_719
	s_setprio 0
	s_barrier
.Lresync_y_719:
.LBB0_719:
	s_add_i32 s14, s4, 2
	s_add_u32 s15, s0, 0x80
	s_addc_u32 s5, s1, 0
	s_add_i32 s8, 0, 0x10000
	v_add_u32_e32 v118, s8, v217
	ds_read_b128 v[106:109], v118
	ds_read_b128 v[110:113], v118 offset:1024
	ds_read_b128 v[114:117], v118 offset:2048
	ds_read_b128 v[118:121], v118 offset:3072
	s_cmp_eq_u32 s48, s4
	s_cselect_b32 s4, s59, s15
	s_cselect_b32 s5, s57, s5
	s_cselect_b32 s95, vcc_lo, s35
	s_cselect_b32 s94, vcc_hi, s34
	v_lshl_add_u64 v[154:155], s[0:1], 0, v[202:203]
	s_add_i32 m0, s52, 0xc000
	ds_read_b128 v[122:125], v235
	ds_read_b128 v[126:129], v235 offset:1024
	ds_read_b128 v[130:133], v235 offset:2048
	ds_read_b128 v[134:137], v235 offset:3072
	ds_read_b128 v[138:141], v235 offset:4096
	ds_read_b128 v[142:145], v235 offset:5120
	ds_read_b128 v[146:149], v235 offset:6144
	ds_read_b128 v[150:153], v235 offset:7168
	global_load_lds_dwordx4 v[154:155], off
	v_lshl_add_u64 v[154:155], s[0:1], 0, v[204:205]
	s_add_i32 m0, s52, 0xe000
	s_nop 0
	global_load_lds_dwordx4 v[154:155], off
	s_waitcnt lgkmcnt(8)
	s_waitcnt lgkmcnt(0)
	v_mfma_f32_16x16x32_bf16 v[162:165], v[114:117], v[130:133], v[162:165]
	v_mfma_f32_16x16x32_bf16 v[94:97], v[106:109], v[138:141], v[94:97]
	v_mfma_f32_16x16x32_bf16 v[90:93], v[114:117], v[138:141], v[90:93]
	v_mfma_f32_16x16x32_bf16 v[78:81], v[106:109], v[146:149], v[78:81]
	s_barrier
	s_waitcnt lgkmcnt(0)
	s_setprio 1
	s_waitcnt lgkmcnt(0)
	v_mfma_f32_16x16x32_bf16 v[74:77], v[114:117], v[146:149], v[74:77]
	v_mfma_f32_16x16x32_bf16 v[154:157], v[106:109], v[122:125], v[190:193]
	v_mfma_f32_16x16x32_bf16 v[158:161], v[114:117], v[122:125], v[186:189]
	v_mfma_f32_16x16x32_bf16 v[166:169], v[106:109], v[130:133], v[174:177]
	v_mfma_f32_16x16x32_bf16 v[162:165], v[118:121], v[134:137], v[162:165]
	v_mfma_f32_16x16x32_bf16 v[94:97], v[110:113], v[142:145], v[94:97]
	v_mfma_f32_16x16x32_bf16 v[90:93], v[118:121], v[142:145], v[90:93]
	v_mfma_f32_16x16x32_bf16 v[78:81], v[110:113], v[150:153], v[78:81]
	v_mfma_f32_16x16x32_bf16 v[74:77], v[118:121], v[150:153], v[74:77]
	v_mfma_f32_16x16x32_bf16 v[154:157], v[110:113], v[126:129], v[154:157]
	v_mfma_f32_16x16x32_bf16 v[158:161], v[118:121], v[126:129], v[158:161]
	v_mfma_f32_16x16x32_bf16 v[166:169], v[110:113], v[134:137], v[166:169]
	s_setprio 0
	s_barrier
; #define PG8_STAGE(bufoff, gbase, voff) do { _Pragma("unroll") for (int _i = 0; _i < 2; ++_i) \
;         __builtin_amdgcn_global_load_lds((const unsigned*)((const char*)(gbase) + (voff)[_i]), (LAS unsigned*)(lds + (bufoff) + ldsw + _i * 8192), 16, 0, 0); } while (0)
; #define PG8_LDA(dst, b, h) do { _Pragma("unroll") for (int m = 0; m < 4; ++m) _Pragma("unroll") for (int k = 0; k < 2; ++k) dst[m][k] = *(const LAS bf16x8*)(lds + PG8_SA(b, h) + aoff + m * 2048 + k * 1024); } while (0)
; #define PG8_LDB(dst, b, h) do { _Pragma("unroll") for (int n = 0; n < 2; ++n) _Pragma("unroll") for (int k = 0; k < 2; ++k) dst[n][k] = *(const LAS bf16x8*)(lds + PG8_SB(b, h) + boff + n * 2048 + k * 1024); } while (0)
; #define PG8_MMA(ai, bj, At, Bt) do { __builtin_amdgcn_s_setprio(1); _Pragma("unroll") for (int m = 0; m < 4; ++m) _Pragma("unroll") for (int n = 0; n < 2; ++n) _Pragma("unroll") for (int k = 0; k < 2; ++k) \
;         acc[ai][bj][m][n] = __builtin_amdgcn_mfma_f32_16x16x32_bf16(Bt[n][k], At[m][k], acc[ai][bj][m][n], 0, 0, 0); __builtin_amdgcn_s_setprio(0); } while (0)
; #define PG8_WAIT_V(n) asm volatile("s_waitcnt vmcnt(" #n ")" ::: "memory")
; #define PG8_WAIT_L(n) asm volatile("s_waitcnt lgkmcnt(" #n ")" ::: "memory")
; #define PG8_BAR __builtin_amdgcn_s_barrier()
; #define PG8_SCHED __builtin_amdgcn_sched_barrier(0)
; template <class Epi>
; __device__ __forceinline__ void gemm_phase(LAS unsigned char* lds, const Gemm g, const Sched& S, const Epi& E) {
;     ...
;             PG8_WAIT_L(8); PG8_BAR; PG8_WAIT_L(0); PG8_MMA(0, 0, At, B0); PG8_BAR; PG8_SCHED;
;             PG8_LDB(B1, 0, 1); PG8_STAGE(PG8_SB(0, 0), b2, voffB);
;             PG8_BAR; PG8_WAIT_L(0); PG8_MMA(0, 1, At, B1); PG8_BAR;
;             PG8_LDA(At, 0, 1); PG8_STAGE(PG8_SA(0, 0), a2, voffA);
;             PG8_BAR; PG8_WAIT_L(0); PG8_MMA(1, 0, At, B0); PG8_BAR; PG8_SCHED;
;             PG8_STAGE(PG8_SB(0, 1), b2 + hstepB, voffB);
;             PG8_WAIT_V(6); PG8_BAR; PG8_MMA(1, 1, At, B1); PG8_BAR;
;             PG8_LDB(B0, 1, 0); PG8_SCHED; PG8_LDA(At, 1, 0); PG8_STAGE(PG8_SA(0, 1), a2 + hstepA, voffA);
;             PG8_WAIT_L(8); PG8_BAR; PG8_WAIT_L(0); PG8_MMA(0, 0, At, B0); PG8_BAR; PG8_SCHED;
;             PG8_LDB(B1, 1, 1); PG8_STAGE(PG8_SB(1, 0), b3, voffB);
;             PG8_BAR; PG8_WAIT_L(0); PG8_MMA(0, 1, At, B1); PG8_BAR;
	s_add_i32 s9, 0, 0x14000
	s_add_i32 s8, s8, s43
	v_add_u32_e32 v190, s9, v217
	v_lshl_add_u64 v[210:211], s[94:95], 0, v[0:1]
	s_mov_b32 m0, s8
	ds_read_b128 v[170:173], v190
	ds_read_b128 v[174:177], v190 offset:1024
	ds_read_b128 v[186:189], v190 offset:2048
	ds_read_b128 v[190:193], v190 offset:3072
	global_load_lds_dwordx4 v[210:211], off
	v_lshl_add_u64 v[212:213], s[94:95], 0, v[200:201]
	s_add_i32 m0, s8, 0x2000
	s_nop 0
	global_load_lds_dwordx4 v[212:213], off
	s_waitcnt lgkmcnt(0)
	v_mfma_f32_16x16x32_bf16 v[182:185], v[170:173], v[122:125], v[182:185]
	v_mfma_f32_16x16x32_bf16 v[102:105], v[170:173], v[130:133], v[102:105]
	v_mfma_f32_16x16x32_bf16 v[98:101], v[186:189], v[130:133], v[98:101]
	v_mfma_f32_16x16x32_bf16 v[86:89], v[170:173], v[138:141], v[86:89]
	s_barrier
	s_waitcnt lgkmcnt(0)
	s_setprio 1
	s_waitcnt lgkmcnt(0)
	v_mfma_f32_16x16x32_bf16 v[82:85], v[186:189], v[138:141], v[82:85]
	v_mfma_f32_16x16x32_bf16 v[70:73], v[170:173], v[146:149], v[70:73]
	v_mfma_f32_16x16x32_bf16 v[66:69], v[186:189], v[146:149], v[66:69]
	v_mfma_f32_16x16x32_bf16 v[182:185], v[174:177], v[126:129], v[182:185]
	v_mfma_f32_16x16x32_bf16 v[122:125], v[186:189], v[122:125], v[178:181]
	v_mfma_f32_16x16x32_bf16 v[102:105], v[174:177], v[134:137], v[102:105]
	v_mfma_f32_16x16x32_bf16 v[98:101], v[190:193], v[134:137], v[98:101]
	v_mfma_f32_16x16x32_bf16 v[86:89], v[174:177], v[142:145], v[86:89]
	v_mfma_f32_16x16x32_bf16 v[82:85], v[190:193], v[142:145], v[82:85]
	v_mfma_f32_16x16x32_bf16 v[70:73], v[174:177], v[150:153], v[70:73]
	v_mfma_f32_16x16x32_bf16 v[66:69], v[190:193], v[150:153], v[66:69]
	v_mfma_f32_16x16x32_bf16 v[122:125], v[190:193], v[126:129], v[122:125]
	s_setprio 0
	s_mov_b32 m0, s52
	v_lshl_add_u64 v[214:215], s[4:5], 0, v[196:197]
	s_barrier
	ds_read_b128 v[126:129], v235 offset:16384
	ds_read_b128 v[130:133], v235 offset:17408
	ds_read_b128 v[134:137], v235 offset:18432
	ds_read_b128 v[138:141], v235 offset:19456
	ds_read_b128 v[142:145], v235 offset:20480
	ds_read_b128 v[146:149], v235 offset:21504
	ds_read_b128 v[150:153], v235 offset:22528
	ds_read_b128 v[178:181], v235 offset:23552
	global_load_lds_dwordx4 v[214:215], off
	v_lshl_add_u64 v[222:223], s[4:5], 0, v[198:199]
	s_mov_b32 m0, s53
	s_nop 0
	global_load_lds_dwordx4 v[222:223], off
	s_add_u32 s94, s94, s76
	s_addc_u32 s95, s95, s77
	s_add_i32 s8, s9, s43
	v_lshl_add_u64 v[224:225], s[94:95], 0, v[0:1]
	s_mov_b32 m0, s8
	v_lshl_add_u64 v[226:227], s[94:95], 0, v[200:201]
	global_load_lds_dwordx4 v[224:225], off
	s_add_i32 m0, s8, 0x2000
	s_nop 0
	global_load_lds_dwordx4 v[226:227], off
	s_waitcnt vmcnt(6)
	s_waitcnt lgkmcnt(0)
	v_mfma_f32_16x16x32_bf16 v[62:65], v[106:109], v[126:129], v[62:65]
	v_mfma_f32_16x16x32_bf16 v[58:61], v[114:117], v[126:129], v[58:61]
	v_mfma_f32_16x16x32_bf16 v[46:49], v[106:109], v[134:137], v[46:49]
	v_mfma_f32_16x16x32_bf16 v[42:45], v[114:117], v[134:137], v[42:45]
	s_barrier
	s_setprio 1
	v_mfma_f32_16x16x32_bf16 v[30:33], v[106:109], v[142:145], v[30:33]
	v_mfma_f32_16x16x32_bf16 v[26:29], v[114:117], v[142:145], v[26:29]
	v_mfma_f32_16x16x32_bf16 v[14:17], v[106:109], v[150:153], v[14:17]
	v_mfma_f32_16x16x32_bf16 v[10:13], v[114:117], v[150:153], v[10:13]
	v_mfma_f32_16x16x32_bf16 v[62:65], v[110:113], v[130:133], v[62:65]
	v_mfma_f32_16x16x32_bf16 v[58:61], v[118:121], v[130:133], v[58:61]
	v_mfma_f32_16x16x32_bf16 v[46:49], v[110:113], v[138:141], v[46:49]
	v_mfma_f32_16x16x32_bf16 v[42:45], v[118:121], v[138:141], v[42:45]
	v_mfma_f32_16x16x32_bf16 v[30:33], v[110:113], v[146:149], v[30:33]
	v_mfma_f32_16x16x32_bf16 v[26:29], v[118:121], v[146:149], v[26:29]
	v_mfma_f32_16x16x32_bf16 v[14:17], v[110:113], v[178:181], v[14:17]
	v_mfma_f32_16x16x32_bf16 v[10:13], v[118:121], v[178:181], v[10:13]
	v_mfma_f32_16x16x32_bf16 v[54:57], v[170:173], v[126:129], v[54:57]
	v_mfma_f32_16x16x32_bf16 v[50:53], v[186:189], v[126:129], v[50:53]
	v_mfma_f32_16x16x32_bf16 v[38:41], v[170:173], v[134:137], v[38:41]
	v_mfma_f32_16x16x32_bf16 v[34:37], v[186:189], v[134:137], v[34:37]
	v_mfma_f32_16x16x32_bf16 v[22:25], v[170:173], v[142:145], v[22:25]
	v_mfma_f32_16x16x32_bf16 v[18:21], v[186:189], v[142:145], v[18:21]
	v_mfma_f32_16x16x32_bf16 v[6:9], v[170:173], v[150:153], v[6:9]
	v_mfma_f32_16x16x32_bf16 v[2:5], v[186:189], v[150:153], v[2:5]
	v_mfma_f32_16x16x32_bf16 v[54:57], v[174:177], v[130:133], v[54:57]
	v_mfma_f32_16x16x32_bf16 v[50:53], v[190:193], v[130:133], v[50:53]
	v_mfma_f32_16x16x32_bf16 v[38:41], v[174:177], v[138:141], v[38:41]
	v_mfma_f32_16x16x32_bf16 v[34:37], v[190:193], v[138:141], v[34:37]
	v_mfma_f32_16x16x32_bf16 v[22:25], v[174:177], v[146:149], v[22:25]
	v_mfma_f32_16x16x32_bf16 v[18:21], v[190:193], v[146:149], v[18:21]
	v_mfma_f32_16x16x32_bf16 v[6:9], v[174:177], v[178:181], v[6:9]
	v_mfma_f32_16x16x32_bf16 v[2:5], v[190:193], v[178:181], v[2:5]
	s_setprio 0
	s_add_i32 s8, 0, 0x18000
	v_add_u32_e32 v118, s8, v217
	s_barrier
	ds_read_b128 v[106:109], v118
	ds_read_b128 v[110:113], v118 offset:1024
	ds_read_b128 v[114:117], v118 offset:2048
	ds_read_b128 v[118:121], v118 offset:3072
	s_add_u32 s4, s4, s40
	s_addc_u32 s5, s5, s41
	s_mov_b32 m0, s56
	v_lshl_add_u64 v[174:175], s[4:5], 0, v[196:197]
	ds_read_b128 v[126:129], v235 offset:32768
	ds_read_b128 v[130:133], v235 offset:33792
	ds_read_b128 v[134:137], v235 offset:34816
	ds_read_b128 v[138:141], v235 offset:35840
	ds_read_b128 v[142:145], v235 offset:36864
	ds_read_b128 v[146:149], v235 offset:37888
	ds_read_b128 v[150:153], v235 offset:38912
	ds_read_b128 v[170:173], v235 offset:39936
	global_load_lds_dwordx4 v[174:175], off
	v_lshl_add_u64 v[174:175], s[4:5], 0, v[198:199]
	s_mov_b32 m0, s67
	s_nop 0
	global_load_lds_dwordx4 v[174:175], off
	s_waitcnt lgkmcnt(8)
	s_waitcnt lgkmcnt(0)
	v_mfma_f32_16x16x32_bf16 v[154:157], v[106:109], v[126:129], v[154:157]
	v_mfma_f32_16x16x32_bf16 v[190:193], v[110:113], v[130:133], v[154:157]
	v_mfma_f32_16x16x32_bf16 v[154:157], v[114:117], v[126:129], v[158:161]
	v_mfma_f32_16x16x32_bf16 v[186:189], v[118:121], v[130:133], v[154:157]
	s_barrier
; #define PG8_STAGE(bufoff, gbase, voff) do { _Pragma("unroll") for (int _i = 0; _i < 2; ++_i) \
;         __builtin_amdgcn_global_load_lds((const unsigned*)((const char*)(gbase) + (voff)[_i]), (LAS unsigned*)(lds + (bufoff) + ldsw + _i * 8192), 16, 0, 0); } while (0)
; #define PG8_LDA(dst, b, h) do { _Pragma("unroll") for (int m = 0; m < 4; ++m) _Pragma("unroll") for (int k = 0; k < 2; ++k) dst[m][k] = *(const LAS bf16x8*)(lds + PG8_SA(b, h) + aoff + m * 2048 + k * 1024); } while (0)
; #define PG8_LDB(dst, b, h) do { _Pragma("unroll") for (int n = 0; n < 2; ++n) _Pragma("unroll") for (int k = 0; k < 2; ++k) dst[n][k] = *(const LAS bf16x8*)(lds + PG8_SB(b, h) + boff + n * 2048 + k * 1024); } while (0)
; #define PG8_MMA(ai, bj, At, Bt) do { __builtin_amdgcn_s_setprio(1); _Pragma("unroll") for (int m = 0; m < 4; ++m) _Pragma("unroll") for (int n = 0; n < 2; ++n) _Pragma("unroll") for (int k = 0; k < 2; ++k) \
;         acc[ai][bj][m][n] = __builtin_amdgcn_mfma_f32_16x16x32_bf16(Bt[n][k], At[m][k], acc[ai][bj][m][n], 0, 0, 0); __builtin_amdgcn_s_setprio(0); } while (0)
; #define PG8_WAIT_V(n) asm volatile("s_waitcnt vmcnt(" #n ")" ::: "memory")
; #define PG8_WAIT_L(n) asm volatile("s_waitcnt lgkmcnt(" #n ")" ::: "memory")
; #define PG8_BAR __builtin_amdgcn_s_barrier()
; #define PG8_SCHED __builtin_amdgcn_sched_barrier(0)
; template <class Epi>
; __device__ __forceinline__ void gemm_phase(LAS unsigned char* lds, const Gemm g, const Sched& S, const Epi& E) {
;     ...
;             PG8_LDB(B1, 1, 1); PG8_STAGE(PG8_SB(1, 0), b3, voffB);
;             PG8_BAR; PG8_WAIT_L(0); PG8_MMA(0, 1, At, B1); PG8_BAR;
;             PG8_LDA(At, 1, 1); PG8_STAGE(PG8_SA(1, 0), a3, voffA);
;             PG8_BAR; PG8_WAIT_L(0); PG8_MMA(1, 0, At, B0); PG8_BAR; PG8_SCHED;
;             PG8_STAGE(PG8_SB(1, 1), b3 + hstepB, voffB);
;             PG8_WAIT_V(6); PG8_BAR; PG8_MMA(1, 1, At, B1); PG8_BAR;
;         }
;         E(acc, cur, wr, wc, fr, fq, pre);
;         if (!has_next) break;
	s_waitcnt lgkmcnt(0)
	s_setprio 1
	s_waitcnt lgkmcnt(0)
	v_mfma_f32_16x16x32_bf16 v[154:157], v[106:109], v[134:137], v[166:169]
	v_mfma_f32_16x16x32_bf16 v[174:177], v[110:113], v[138:141], v[154:157]
	v_mfma_f32_16x16x32_bf16 v[154:157], v[114:117], v[134:137], v[162:165]
	v_mfma_f32_16x16x32_bf16 v[94:97], v[106:109], v[142:145], v[94:97]
	v_mfma_f32_16x16x32_bf16 v[90:93], v[114:117], v[142:145], v[90:93]
	v_mfma_f32_16x16x32_bf16 v[78:81], v[106:109], v[150:153], v[78:81]
	v_mfma_f32_16x16x32_bf16 v[74:77], v[114:117], v[150:153], v[74:77]
	v_mfma_f32_16x16x32_bf16 v[162:165], v[118:121], v[138:141], v[154:157]
	v_mfma_f32_16x16x32_bf16 v[94:97], v[110:113], v[146:149], v[94:97]
	v_mfma_f32_16x16x32_bf16 v[90:93], v[118:121], v[146:149], v[90:93]
	v_mfma_f32_16x16x32_bf16 v[78:81], v[110:113], v[170:173], v[78:81]
	v_mfma_f32_16x16x32_bf16 v[74:77], v[118:121], v[170:173], v[74:77]
	s_setprio 0
	s_barrier
	s_add_i32 s4, 0, 0x1c000
	v_add_u32_e32 v178, s4, v217
	s_add_i32 s5, s8, s43
	ds_read_b128 v[154:157], v178
	ds_read_b128 v[158:161], v178 offset:1024
	ds_read_b128 v[166:169], v178 offset:2048
	ds_read_b128 v[206:209], v178 offset:3072
	v_lshl_add_u64 v[178:179], v[210:211], 0, s[60:61]
	s_mov_b32 m0, s5
	s_nop 0
	global_load_lds_dwordx4 v[178:179], off
	v_lshl_add_u64 v[178:179], v[212:213], 0, s[60:61]
	s_add_i32 m0, s5, 0x2000
	s_nop 0
	global_load_lds_dwordx4 v[178:179], off
	s_waitcnt lgkmcnt(0)
	v_mfma_f32_16x16x32_bf16 v[178:181], v[154:157], v[126:129], v[182:185]
	v_mfma_f32_16x16x32_bf16 v[122:125], v[166:169], v[126:129], v[122:125]
	v_mfma_f32_16x16x32_bf16 v[102:105], v[154:157], v[134:137], v[102:105]
	v_mfma_f32_16x16x32_bf16 v[98:101], v[166:169], v[134:137], v[98:101]
	s_barrier
	s_waitcnt lgkmcnt(0)
	s_setprio 1
	s_waitcnt lgkmcnt(0)
	v_mfma_f32_16x16x32_bf16 v[86:89], v[154:157], v[142:145], v[86:89]
	v_mfma_f32_16x16x32_bf16 v[82:85], v[166:169], v[142:145], v[82:85]
	v_mfma_f32_16x16x32_bf16 v[70:73], v[154:157], v[150:153], v[70:73]
	v_mfma_f32_16x16x32_bf16 v[66:69], v[166:169], v[150:153], v[66:69]
	v_mfma_f32_16x16x32_bf16 v[182:185], v[158:161], v[130:133], v[178:181]
	v_mfma_f32_16x16x32_bf16 v[178:181], v[206:209], v[130:133], v[122:125]
	v_mfma_f32_16x16x32_bf16 v[102:105], v[158:161], v[138:141], v[102:105]
	v_mfma_f32_16x16x32_bf16 v[98:101], v[206:209], v[138:141], v[98:101]
	v_mfma_f32_16x16x32_bf16 v[86:89], v[158:161], v[146:149], v[86:89]
	v_mfma_f32_16x16x32_bf16 v[82:85], v[206:209], v[146:149], v[82:85]
	v_mfma_f32_16x16x32_bf16 v[70:73], v[158:161], v[170:173], v[70:73]
	v_mfma_f32_16x16x32_bf16 v[66:69], v[206:209], v[170:173], v[66:69]
	s_setprio 0
	s_mov_b32 m0, s51
	v_lshl_add_u64 v[170:171], v[214:215], 0, s[60:61]
	s_barrier
	ds_read_b128 v[122:125], v235 offset:49152
	ds_read_b128 v[126:129], v235 offset:50176
	ds_read_b128 v[130:133], v235 offset:51200
	ds_read_b128 v[134:137], v235 offset:52224
	ds_read_b128 v[138:141], v235 offset:53248
	ds_read_b128 v[142:145], v235 offset:54272
	ds_read_b128 v[146:149], v235 offset:55296
	ds_read_b128 v[150:153], v235 offset:56320
	global_load_lds_dwordx4 v[170:171], off
	v_lshl_add_u64 v[170:171], v[222:223], 0, s[60:61]
	s_mov_b32 m0, s2
	s_nop 0
	global_load_lds_dwordx4 v[170:171], off
	s_add_i32 s4, s4, s43
	v_lshl_add_u64 v[170:171], v[224:225], 0, s[60:61]
	s_mov_b32 m0, s4
	s_nop 0
	global_load_lds_dwordx4 v[170:171], off
	v_lshl_add_u64 v[170:171], v[226:227], 0, s[60:61]
	s_add_i32 m0, s4, 0x2000
	s_nop 0
	global_load_lds_dwordx4 v[170:171], off
	s_waitcnt vmcnt(6)
	s_waitcnt lgkmcnt(0)
	v_mfma_f32_16x16x32_bf16 v[62:65], v[106:109], v[122:125], v[62:65]
	v_mfma_f32_16x16x32_bf16 v[58:61], v[114:117], v[122:125], v[58:61]
	v_mfma_f32_16x16x32_bf16 v[46:49], v[106:109], v[130:133], v[46:49]
	v_mfma_f32_16x16x32_bf16 v[42:45], v[114:117], v[130:133], v[42:45]
	s_barrier
	s_setprio 1
	v_mfma_f32_16x16x32_bf16 v[30:33], v[106:109], v[138:141], v[30:33]
	v_mfma_f32_16x16x32_bf16 v[26:29], v[114:117], v[138:141], v[26:29]
	v_mfma_f32_16x16x32_bf16 v[14:17], v[106:109], v[146:149], v[14:17]
	v_mfma_f32_16x16x32_bf16 v[10:13], v[114:117], v[146:149], v[10:13]
	v_mfma_f32_16x16x32_bf16 v[62:65], v[110:113], v[126:129], v[62:65]
	v_mfma_f32_16x16x32_bf16 v[58:61], v[118:121], v[126:129], v[58:61]
	v_mfma_f32_16x16x32_bf16 v[46:49], v[110:113], v[134:137], v[46:49]
	v_mfma_f32_16x16x32_bf16 v[42:45], v[118:121], v[134:137], v[42:45]
	v_mfma_f32_16x16x32_bf16 v[30:33], v[110:113], v[142:145], v[30:33]
	v_mfma_f32_16x16x32_bf16 v[26:29], v[118:121], v[142:145], v[26:29]
	v_mfma_f32_16x16x32_bf16 v[14:17], v[110:113], v[150:153], v[14:17]
	v_mfma_f32_16x16x32_bf16 v[10:13], v[118:121], v[150:153], v[10:13]
	v_mfma_f32_16x16x32_bf16 v[54:57], v[154:157], v[122:125], v[54:57]
	v_mfma_f32_16x16x32_bf16 v[50:53], v[166:169], v[122:125], v[50:53]
	v_mfma_f32_16x16x32_bf16 v[38:41], v[154:157], v[130:133], v[38:41]
	v_mfma_f32_16x16x32_bf16 v[34:37], v[166:169], v[130:133], v[34:37]
	v_mfma_f32_16x16x32_bf16 v[22:25], v[154:157], v[138:141], v[22:25]
	v_mfma_f32_16x16x32_bf16 v[18:21], v[166:169], v[138:141], v[18:21]
	v_mfma_f32_16x16x32_bf16 v[6:9], v[154:157], v[146:149], v[6:9]
	v_mfma_f32_16x16x32_bf16 v[2:5], v[166:169], v[146:149], v[2:5]
	v_mfma_f32_16x16x32_bf16 v[54:57], v[158:161], v[126:129], v[54:57]
	v_mfma_f32_16x16x32_bf16 v[50:53], v[206:209], v[126:129], v[50:53]
	v_mfma_f32_16x16x32_bf16 v[38:41], v[158:161], v[134:137], v[38:41]
	v_mfma_f32_16x16x32_bf16 v[34:37], v[206:209], v[134:137], v[34:37]
	v_mfma_f32_16x16x32_bf16 v[22:25], v[158:161], v[142:145], v[22:25]
	v_mfma_f32_16x16x32_bf16 v[18:21], v[206:209], v[142:145], v[18:21]
	v_mfma_f32_16x16x32_bf16 v[6:9], v[158:161], v[150:153], v[6:9]
	v_mfma_f32_16x16x32_bf16 v[2:5], v[206:209], v[150:153], v[2:5]
	s_setprio 0
	s_add_u32 s0, s0, 0x100
	s_addc_u32 s1, s1, 0
	s_add_u32 s34, s34, 0x100
	s_addc_u32 s35, s35, 0
	s_cmp_ge_u32 s14, s73
	s_mov_b32 s4, s14
	s_barrier
	s_cbranch_scc0 .LBB0_719
	v_readfirstlane_b32 s98, v219
	s_nop 1
	s_bitcmp1_b32 s98, 8
	s_cbranch_scc1 .Lresync_x_719_p
	s_barrier
	s_branch .Lresync_x_719

; #define PG8_WAIT_V(n) asm volatile("s_waitcnt vmcnt(" #n ")" ::: "memory")
; #define PG8_BAR __builtin_amdgcn_s_barrier()
; template <class Epi>
; __device__ __forceinline__ void gemm_phase(LAS unsigned char* lds, const Gemm g, const Sched& S, const Epi& E) {
;     ...
;     PG8_WAIT_V(0);
;     if (wr == 0) PG8_BAR;
;     PG8_BAR;
.LBB0_800:
	s_waitcnt vmcnt(0)
	v_readlane_b32 s0, v254, 35
	v_readlane_b32 s90, v254, 39
	s_setprio 0
	s_cmpk_gt_u32 s0, 0xff
	v_readlane_b32 s58, v253, 45
	v_readlane_b32 s64, v253, 47
	v_readlane_b32 s72, v254, 41
	v_readlane_b32 s91, v254, 40
	v_readlane_b32 s59, v253, 46
	s_cbranch_scc1 .LBB0_802

; #define PG8_STAGE(bufoff, gbase, voff) do { _Pragma("unroll") for (int _i = 0; _i < 2; ++_i) \
;         __builtin_amdgcn_global_load_lds((const unsigned*)((const char*)(gbase) + (voff)[_i]), (LAS unsigned*)(lds + (bufoff) + ldsw + _i * 8192), 16, 0, 0); } while (0)
; #define PG8_LDA(dst, b, h) do { _Pragma("unroll") for (int m = 0; m < 4; ++m) _Pragma("unroll") for (int k = 0; k < 2; ++k) dst[m][k] = *(const LAS bf16x8*)(lds + PG8_SA(b, h) + aoff + m * 2048 + k * 1024); } while (0)
; #define PG8_LDB(dst, b, h) do { _Pragma("unroll") for (int n = 0; n < 2; ++n) _Pragma("unroll") for (int k = 0; k < 2; ++k) dst[n][k] = *(const LAS bf16x8*)(lds + PG8_SB(b, h) + boff + n * 2048 + k * 1024); } while (0)
; #define PG8_MMA(ai, bj, At, Bt) do { __builtin_amdgcn_s_setprio(1); _Pragma("unroll") for (int m = 0; m < 4; ++m) _Pragma("unroll") for (int n = 0; n < 2; ++n) _Pragma("unroll") for (int k = 0; k < 2; ++k) \
;         acc[ai][bj][m][n] = __builtin_amdgcn_mfma_f32_16x16x32_bf16(Bt[n][k], At[m][k], acc[ai][bj][m][n], 0, 0, 0); __builtin_amdgcn_s_setprio(0); } while (0)
; #define PG8_WAIT_L(n) asm volatile("s_waitcnt lgkmcnt(" #n ")" ::: "memory")
; #define PG8_BAR __builtin_amdgcn_s_barrier()
; #define PG8_SCHED __builtin_amdgcn_sched_barrier(0)
; template <class Epi>
; __device__ __forceinline__ void gemm_phase(LAS unsigned char* lds, const Gemm g, const Sched& S, const Epi& E) {
;     ...
;         for (int t = 0; t < nt; t += 2) {
;             const bool last = (t == nt - 2);
;             const char* a1 = cA + (size_t)(t + 1) * kstep;
;             const char* a2 = last ? nA : cA + (size_t)(t + 2) * kstep; const char* b2 = last ? nB : cB + (size_t)(t + 2) * kstep;
;             const char* a3 = a2 + kstep; const char* b3 = b2 + kstep;
;             PG8_LDB(B0, 0, 0); PG8_SCHED; PG8_LDA(At, 0, 0); PG8_STAGE(PG8_SA(1, 1), a1 + hstepA, voffA);
;             PG8_WAIT_L(8); PG8_BAR; PG8_WAIT_L(0); PG8_MMA(0, 0, At, B0); PG8_BAR; PG8_SCHED;
;     ...
; #pragma unroll
;         for (int a = 0; a < 2; ++a)
; #pragma unroll
;             for (int b = 0; b < 2; ++b)
; #pragma unroll
;                 for (int m = 0; m < 4; ++m)
; #pragma unroll
;                     for (int n = 0; n < 2; ++n) acc[a][b][m][n] = (f32x4){0.f, 0.f, 0.f, 0.f};
;         cur = nxt; cA = nA; cB = nB; ++ui;
.LBB0_824:
	v_mov_b64_e32 v[2:3], s[26:27]
	v_cmp_lt_i64_e32 vcc, s[64:65], v[2:3]
	v_readlane_b32 s64, v254, 11
	v_readlane_b32 s65, v254, 12
	s_add_u32 s64, s64, s38
	s_addc_u32 s65, s65, s39
	s_and_b64 s[66:67], vcc, exec
	s_cselect_b32 s57, s65, s5
	s_cselect_b32 s59, s64, s4
	s_add_u32 s66, s10, s40
	s_addc_u32 s67, s11, s41
	s_and_b64 s[70:71], vcc, exec
	s_cselect_b32 s82, s67, s69
	s_cselect_b32 s83, s66, s68
	s_add_u32 s4, s4, 0x80
	s_addc_u32 s5, s5, 0
	s_add_u32 s84, s68, 0x100
	v_mov_b32_e32 v2, 0
	s_addc_u32 s85, s69, 0
	s_mov_b32 s68, 0
	v_mov_b32_e32 v3, v2
	v_mov_b32_e32 v4, v2
	v_mov_b32_e32 v5, v2
	v_mov_b32_e32 v6, v2
	v_mov_b32_e32 v7, v2
	v_mov_b32_e32 v8, v2
	v_mov_b32_e32 v9, v2
	v_mov_b32_e32 v18, v2
	v_mov_b32_e32 v19, v2
	v_mov_b32_e32 v20, v2
	v_mov_b32_e32 v21, v2
	v_mov_b32_e32 v22, v2
	v_mov_b32_e32 v23, v2
	v_mov_b32_e32 v24, v2
	v_mov_b32_e32 v25, v2
	v_mov_b32_e32 v34, v2
	v_mov_b32_e32 v35, v2
	v_mov_b32_e32 v36, v2
	v_mov_b32_e32 v37, v2
	v_mov_b32_e32 v38, v2
	v_mov_b32_e32 v39, v2
	v_mov_b32_e32 v40, v2
	v_mov_b32_e32 v41, v2
	v_mov_b32_e32 v50, v2
	v_mov_b32_e32 v51, v2
	v_mov_b32_e32 v52, v2
	v_mov_b32_e32 v53, v2
	v_mov_b32_e32 v54, v2
	v_mov_b32_e32 v55, v2
	v_mov_b32_e32 v56, v2
	v_mov_b32_e32 v57, v2
	v_mov_b32_e32 v10, v2
	v_mov_b32_e32 v11, v2
	v_mov_b32_e32 v12, v2
	v_mov_b32_e32 v13, v2
	v_mov_b32_e32 v14, v2
	v_mov_b32_e32 v15, v2
	v_mov_b32_e32 v16, v2
	v_mov_b32_e32 v17, v2
	v_mov_b32_e32 v26, v2
	v_mov_b32_e32 v27, v2
	v_mov_b32_e32 v28, v2
	v_mov_b32_e32 v29, v2
	v_mov_b32_e32 v30, v2
	v_mov_b32_e32 v31, v2
	v_mov_b32_e32 v32, v2
	v_mov_b32_e32 v33, v2
	v_mov_b32_e32 v42, v2
	v_mov_b32_e32 v43, v2
	v_mov_b32_e32 v44, v2
	v_mov_b32_e32 v45, v2
	v_mov_b32_e32 v46, v2
	v_mov_b32_e32 v47, v2
	v_mov_b32_e32 v48, v2
	v_mov_b32_e32 v49, v2
	v_mov_b32_e32 v58, v2
	v_mov_b32_e32 v59, v2
	v_mov_b32_e32 v60, v2
	v_mov_b32_e32 v61, v2
	v_mov_b32_e32 v62, v2
	v_mov_b32_e32 v63, v2
	v_mov_b32_e32 v64, v2
	v_mov_b32_e32 v65, v2
	v_mov_b32_e32 v66, v2
	v_mov_b32_e32 v67, v2
	v_mov_b32_e32 v68, v2
	v_mov_b32_e32 v69, v2
	v_mov_b32_e32 v70, v2
	v_mov_b32_e32 v71, v2
	v_mov_b32_e32 v72, v2
	v_mov_b32_e32 v73, v2
	v_mov_b32_e32 v82, v2
	v_mov_b32_e32 v83, v2
	v_mov_b32_e32 v84, v2
	v_mov_b32_e32 v85, v2
	v_mov_b32_e32 v86, v2
	v_mov_b32_e32 v87, v2
	v_mov_b32_e32 v88, v2
	v_mov_b32_e32 v89, v2
	v_mov_b32_e32 v98, v2
	v_mov_b32_e32 v99, v2
	v_mov_b32_e32 v100, v2
	v_mov_b32_e32 v101, v2
	v_mov_b32_e32 v102, v2
	v_mov_b32_e32 v103, v2
	v_mov_b32_e32 v104, v2
	v_mov_b32_e32 v105, v2
	v_mov_b32_e32 v114, v2
	v_mov_b32_e32 v115, v2
	v_mov_b32_e32 v116, v2
	v_mov_b32_e32 v117, v2
	v_mov_b32_e32 v118, v2
	v_mov_b32_e32 v119, v2
	v_mov_b32_e32 v120, v2
	v_mov_b32_e32 v121, v2
	v_mov_b32_e32 v74, v2
	v_mov_b32_e32 v75, v2
	v_mov_b32_e32 v76, v2
	v_mov_b32_e32 v77, v2
	v_mov_b32_e32 v78, v2
	v_mov_b32_e32 v79, v2
	v_mov_b32_e32 v80, v2
	v_mov_b32_e32 v81, v2
	v_mov_b32_e32 v90, v2
	v_mov_b32_e32 v91, v2
	v_mov_b32_e32 v92, v2
	v_mov_b32_e32 v93, v2
	v_mov_b32_e32 v94, v2
	v_mov_b32_e32 v95, v2
	v_mov_b32_e32 v96, v2
	v_mov_b32_e32 v97, v2
	v_mov_b32_e32 v106, v2
	v_mov_b32_e32 v107, v2
	v_mov_b32_e32 v108, v2
	v_mov_b32_e32 v109, v2
	v_mov_b32_e32 v110, v2
	v_mov_b32_e32 v111, v2
	v_mov_b32_e32 v112, v2
	v_mov_b32_e32 v113, v2
	v_mov_b32_e32 v122, v2
	v_mov_b32_e32 v123, v2
	v_mov_b32_e32 v124, v2
	v_mov_b32_e32 v125, v2
	v_mov_b32_e32 v126, v2
	v_mov_b32_e32 v127, v2
	v_mov_b32_e32 v128, v2
	v_mov_b32_e32 v129, v2
	v_readfirstlane_b32 s98, v219
	s_nop 1
	s_bitcmp1_b32 s98, 8
	s_cbranch_scc0 .Lresync_y_825
	s_setprio 0
	s_barrier
.Lresync_y_825:
.LBB0_825:
	s_add_i32 s86, s68, 2
	s_add_u32 s70, s4, 0x80
	s_addc_u32 s69, s5, 0
	s_add_i32 s87, 0, 0x10000
	v_add_u32_e32 v144, s87, v145
	ds_read_b128 v[152:155], v144
	ds_read_b128 v[156:159], v144 offset:1024
	ds_read_b128 v[160:163], v144 offset:2048
	ds_read_b128 v[164:167], v144 offset:3072
	s_cmp_eq_u32 s77, s68
	s_cselect_b32 s68, s59, s70
	s_cselect_b32 s69, s57, s69
	s_cselect_b32 s71, s82, s85
	s_cselect_b32 s70, s83, s84
	v_lshl_add_u64 v[192:193], s[4:5], 0, v[136:137]
	s_add_i32 m0, s33, 0xc000
	ds_read_b128 v[168:171], v151
	ds_read_b128 v[172:175], v151 offset:1024
	ds_read_b128 v[176:179], v151 offset:2048
	ds_read_b128 v[180:183], v151 offset:3072
	ds_read_b128 v[184:187], v151 offset:4096
	ds_read_b128 v[188:191], v151 offset:5120
	ds_read_b128 v[196:199], v151 offset:6144
	ds_read_b128 v[200:203], v151 offset:7168
	global_load_lds_dwordx4 v[192:193], off
	v_lshl_add_u64 v[192:193], s[4:5], 0, v[138:139]
	s_add_i32 m0, s33, 0xe000
	s_nop 0
	global_load_lds_dwordx4 v[192:193], off
	s_add_i32 s88, 0, 0x14000
	v_add_u32_e32 v144, s88, v145
	ds_read_b128 v[204:207], v144
	ds_read_b128 v[208:211], v144 offset:1024
	ds_read_b128 v[212:215], v144 offset:2048
	ds_read_b128 v[234:237], v144 offset:3072
	s_waitcnt vmcnt(8)
	s_waitcnt lgkmcnt(0)
	v_mfma_f32_16x16x32_bf16 v[126:129], v[152:155], v[168:171], v[126:129]
	v_mfma_f32_16x16x32_bf16 v[122:125], v[160:163], v[168:171], v[122:125]
	v_mfma_f32_16x16x32_bf16 v[110:113], v[152:155], v[176:179], v[110:113]
	v_mfma_f32_16x16x32_bf16 v[106:109], v[160:163], v[176:179], v[106:109]
	s_barrier
; #define PG8_STAGE(bufoff, gbase, voff) do { _Pragma("unroll") for (int _i = 0; _i < 2; ++_i) \
;         __builtin_amdgcn_global_load_lds((const unsigned*)((const char*)(gbase) + (voff)[_i]), (LAS unsigned*)(lds + (bufoff) + ldsw + _i * 8192), 16, 0, 0); } while (0)
; #define PG8_LDA(dst, b, h) do { _Pragma("unroll") for (int m = 0; m < 4; ++m) _Pragma("unroll") for (int k = 0; k < 2; ++k) dst[m][k] = *(const LAS bf16x8*)(lds + PG8_SA(b, h) + aoff + m * 2048 + k * 1024); } while (0)
; #define PG8_LDB(dst, b, h) do { _Pragma("unroll") for (int n = 0; n < 2; ++n) _Pragma("unroll") for (int k = 0; k < 2; ++k) dst[n][k] = *(const LAS bf16x8*)(lds + PG8_SB(b, h) + boff + n * 2048 + k * 1024); } while (0)
; #define PG8_MMA(ai, bj, At, Bt) do { __builtin_amdgcn_s_setprio(1); _Pragma("unroll") for (int m = 0; m < 4; ++m) _Pragma("unroll") for (int n = 0; n < 2; ++n) _Pragma("unroll") for (int k = 0; k < 2; ++k) \
;         acc[ai][bj][m][n] = __builtin_amdgcn_mfma_f32_16x16x32_bf16(Bt[n][k], At[m][k], acc[ai][bj][m][n], 0, 0, 0); __builtin_amdgcn_s_setprio(0); } while (0)
; #define PG8_WAIT_V(n) asm volatile("s_waitcnt vmcnt(" #n ")" ::: "memory")
; #define PG8_WAIT_L(n) asm volatile("s_waitcnt lgkmcnt(" #n ")" ::: "memory")
; #define PG8_BAR __builtin_amdgcn_s_barrier()
; #define PG8_SCHED __builtin_amdgcn_sched_barrier(0)
; template <class Epi>
; __device__ __forceinline__ void gemm_phase(LAS unsigned char* lds, const Gemm g, const Sched& S, const Epi& E) {
;     ...
;             PG8_LDB(B0, 0, 0); PG8_SCHED; PG8_LDA(At, 0, 0); PG8_STAGE(PG8_SA(1, 1), a1 + hstepA, voffA);
;             PG8_WAIT_L(8); PG8_BAR; PG8_WAIT_L(0); PG8_MMA(0, 0, At, B0); PG8_BAR; PG8_SCHED;
;             PG8_LDB(B1, 0, 1); PG8_STAGE(PG8_SB(0, 0), b2, voffB);
;             PG8_BAR; PG8_WAIT_L(0); PG8_MMA(0, 1, At, B1); PG8_BAR;
;             PG8_LDA(At, 0, 1); PG8_STAGE(PG8_SA(0, 0), a2, voffA);
;             PG8_BAR; PG8_WAIT_L(0); PG8_MMA(1, 0, At, B0); PG8_BAR; PG8_SCHED;
;             PG8_STAGE(PG8_SB(0, 1), b2 + hstepB, voffB);
;             PG8_WAIT_V(6); PG8_BAR; PG8_MMA(1, 1, At, B1); PG8_BAR;
	s_setprio 1
	v_mfma_f32_16x16x32_bf16 v[94:97], v[152:155], v[184:187], v[94:97]
	v_mfma_f32_16x16x32_bf16 v[90:93], v[160:163], v[184:187], v[90:93]
	v_mfma_f32_16x16x32_bf16 v[78:81], v[152:155], v[196:199], v[78:81]
	v_mfma_f32_16x16x32_bf16 v[74:77], v[160:163], v[196:199], v[74:77]
	v_mfma_f32_16x16x32_bf16 v[126:129], v[156:159], v[172:175], v[126:129]
	v_mfma_f32_16x16x32_bf16 v[122:125], v[164:167], v[172:175], v[122:125]
	v_mfma_f32_16x16x32_bf16 v[110:113], v[156:159], v[180:183], v[110:113]
	v_mfma_f32_16x16x32_bf16 v[106:109], v[164:167], v[180:183], v[106:109]
	v_mfma_f32_16x16x32_bf16 v[94:97], v[156:159], v[188:191], v[94:97]
	v_mfma_f32_16x16x32_bf16 v[90:93], v[164:167], v[188:191], v[90:93]
	v_mfma_f32_16x16x32_bf16 v[78:81], v[156:159], v[200:203], v[78:81]
	v_mfma_f32_16x16x32_bf16 v[74:77], v[164:167], v[200:203], v[74:77]
	v_mfma_f32_16x16x32_bf16 v[118:121], v[204:207], v[168:171], v[118:121]
	v_mfma_f32_16x16x32_bf16 v[114:117], v[212:215], v[168:171], v[114:117]
	v_mfma_f32_16x16x32_bf16 v[102:105], v[204:207], v[176:179], v[102:105]
	v_mfma_f32_16x16x32_bf16 v[98:101], v[212:215], v[176:179], v[98:101]
	v_mfma_f32_16x16x32_bf16 v[86:89], v[204:207], v[184:187], v[86:89]
	v_mfma_f32_16x16x32_bf16 v[82:85], v[212:215], v[184:187], v[82:85]
	v_mfma_f32_16x16x32_bf16 v[70:73], v[204:207], v[196:199], v[70:73]
	v_mfma_f32_16x16x32_bf16 v[66:69], v[212:215], v[196:199], v[66:69]
	v_mfma_f32_16x16x32_bf16 v[118:121], v[208:211], v[172:175], v[118:121]
	v_mfma_f32_16x16x32_bf16 v[114:117], v[234:237], v[172:175], v[114:117]
	v_mfma_f32_16x16x32_bf16 v[102:105], v[208:211], v[180:183], v[102:105]
	v_mfma_f32_16x16x32_bf16 v[98:101], v[234:237], v[180:183], v[98:101]
	v_mfma_f32_16x16x32_bf16 v[86:89], v[208:211], v[188:191], v[86:89]
	v_mfma_f32_16x16x32_bf16 v[82:85], v[234:237], v[188:191], v[82:85]
	v_mfma_f32_16x16x32_bf16 v[70:73], v[208:211], v[200:203], v[70:73]
	v_mfma_f32_16x16x32_bf16 v[66:69], v[234:237], v[200:203], v[66:69]
	s_setprio 0
	s_barrier
	s_add_i32 s87, s87, s51
	v_lshl_add_u64 v[192:193], s[70:71], 0, v[0:1]
	s_mov_b32 m0, s87
	s_nop 0
	global_load_lds_dwordx4 v[192:193], off
	v_lshl_add_u64 v[216:217], s[70:71], 0, v[134:135]
	s_add_i32 m0, s87, 0x2000
	s_nop 0
	global_load_lds_dwordx4 v[216:217], off
	s_mov_b32 m0, s33
	v_lshl_add_u64 v[222:223], s[68:69], 0, v[130:131]
	ds_read_b128 v[168:171], v151 offset:16384
	ds_read_b128 v[172:175], v151 offset:17408
	ds_read_b128 v[176:179], v151 offset:18432
	ds_read_b128 v[180:183], v151 offset:19456
	ds_read_b128 v[184:187], v151 offset:20480
	ds_read_b128 v[188:191], v151 offset:21504
	ds_read_b128 v[196:199], v151 offset:22528
	ds_read_b128 v[200:203], v151 offset:23552
	global_load_lds_dwordx4 v[222:223], off
	v_lshl_add_u64 v[224:225], s[68:69], 0, v[132:133]
	s_mov_b32 m0, s48
	s_nop 0
	global_load_lds_dwordx4 v[224:225], off
	s_add_u32 s70, s70, s14
	s_addc_u32 s71, s71, s15
	s_add_i32 s87, s88, s51
	v_lshl_add_u64 v[226:227], s[70:71], 0, v[0:1]
	s_mov_b32 m0, s87
	v_lshl_add_u64 v[228:229], s[70:71], 0, v[134:135]
	global_load_lds_dwordx4 v[226:227], off
	s_add_i32 m0, s87, 0x2000
	s_nop 0
	global_load_lds_dwordx4 v[228:229], off
	s_waitcnt vmcnt(8)
	s_waitcnt lgkmcnt(0)
	v_mfma_f32_16x16x32_bf16 v[62:65], v[152:155], v[168:171], v[62:65]
	v_mfma_f32_16x16x32_bf16 v[58:61], v[160:163], v[168:171], v[58:61]
	v_mfma_f32_16x16x32_bf16 v[46:49], v[152:155], v[176:179], v[46:49]
	v_mfma_f32_16x16x32_bf16 v[42:45], v[160:163], v[176:179], v[42:45]
	s_barrier
	s_setprio 1
	v_mfma_f32_16x16x32_bf16 v[30:33], v[152:155], v[184:187], v[30:33]
	v_mfma_f32_16x16x32_bf16 v[26:29], v[160:163], v[184:187], v[26:29]
	v_mfma_f32_16x16x32_bf16 v[14:17], v[152:155], v[196:199], v[14:17]
	v_mfma_f32_16x16x32_bf16 v[10:13], v[160:163], v[196:199], v[10:13]
	v_mfma_f32_16x16x32_bf16 v[62:65], v[156:159], v[172:175], v[62:65]
	v_mfma_f32_16x16x32_bf16 v[58:61], v[164:167], v[172:175], v[58:61]
	v_mfma_f32_16x16x32_bf16 v[46:49], v[156:159], v[180:183], v[46:49]
	v_mfma_f32_16x16x32_bf16 v[42:45], v[164:167], v[180:183], v[42:45]
	v_mfma_f32_16x16x32_bf16 v[30:33], v[156:159], v[188:191], v[30:33]
	v_mfma_f32_16x16x32_bf16 v[26:29], v[164:167], v[188:191], v[26:29]
	v_mfma_f32_16x16x32_bf16 v[14:17], v[156:159], v[200:203], v[14:17]
	v_mfma_f32_16x16x32_bf16 v[10:13], v[164:167], v[200:203], v[10:13]
	v_mfma_f32_16x16x32_bf16 v[54:57], v[204:207], v[168:171], v[54:57]
	v_mfma_f32_16x16x32_bf16 v[50:53], v[212:215], v[168:171], v[50:53]
	v_mfma_f32_16x16x32_bf16 v[38:41], v[204:207], v[176:179], v[38:41]
	v_mfma_f32_16x16x32_bf16 v[34:37], v[212:215], v[176:179], v[34:37]
	v_mfma_f32_16x16x32_bf16 v[22:25], v[204:207], v[184:187], v[22:25]
	v_mfma_f32_16x16x32_bf16 v[18:21], v[212:215], v[184:187], v[18:21]
	v_mfma_f32_16x16x32_bf16 v[6:9], v[204:207], v[196:199], v[6:9]
	v_mfma_f32_16x16x32_bf16 v[2:5], v[212:215], v[196:199], v[2:5]
	v_mfma_f32_16x16x32_bf16 v[54:57], v[208:211], v[172:175], v[54:57]
	v_mfma_f32_16x16x32_bf16 v[50:53], v[234:237], v[172:175], v[50:53]
	v_mfma_f32_16x16x32_bf16 v[38:41], v[208:211], v[180:183], v[38:41]
	v_mfma_f32_16x16x32_bf16 v[34:37], v[234:237], v[180:183], v[34:37]
	v_mfma_f32_16x16x32_bf16 v[22:25], v[208:211], v[188:191], v[22:25]
	v_mfma_f32_16x16x32_bf16 v[18:21], v[234:237], v[188:191], v[18:21]
	v_mfma_f32_16x16x32_bf16 v[6:9], v[208:211], v[200:203], v[6:9]
	v_mfma_f32_16x16x32_bf16 v[2:5], v[234:237], v[200:203], v[2:5]
	s_setprio 0
	s_barrier
; #define PG8_STAGE(bufoff, gbase, voff) do { _Pragma("unroll") for (int _i = 0; _i < 2; ++_i) \
;         __builtin_amdgcn_global_load_lds((const unsigned*)((const char*)(gbase) + (voff)[_i]), (LAS unsigned*)(lds + (bufoff) + ldsw + _i * 8192), 16, 0, 0); } while (0)
; #define PG8_LDA(dst, b, h) do { _Pragma("unroll") for (int m = 0; m < 4; ++m) _Pragma("unroll") for (int k = 0; k < 2; ++k) dst[m][k] = *(const LAS bf16x8*)(lds + PG8_SA(b, h) + aoff + m * 2048 + k * 1024); } while (0)
; #define PG8_LDB(dst, b, h) do { _Pragma("unroll") for (int n = 0; n < 2; ++n) _Pragma("unroll") for (int k = 0; k < 2; ++k) dst[n][k] = *(const LAS bf16x8*)(lds + PG8_SB(b, h) + boff + n * 2048 + k * 1024); } while (0)
; #define PG8_MMA(ai, bj, At, Bt) do { __builtin_amdgcn_s_setprio(1); _Pragma("unroll") for (int m = 0; m < 4; ++m) _Pragma("unroll") for (int n = 0; n < 2; ++n) _Pragma("unroll") for (int k = 0; k < 2; ++k) \
;         acc[ai][bj][m][n] = __builtin_amdgcn_mfma_f32_16x16x32_bf16(Bt[n][k], At[m][k], acc[ai][bj][m][n], 0, 0, 0); __builtin_amdgcn_s_setprio(0); } while (0)
; #define PG8_WAIT_L(n) asm volatile("s_waitcnt lgkmcnt(" #n ")" ::: "memory")
; #define PG8_BAR __builtin_amdgcn_s_barrier()
; #define PG8_SCHED __builtin_amdgcn_sched_barrier(0)
; template <class Epi>
; __device__ __forceinline__ void gemm_phase(LAS unsigned char* lds, const Gemm g, const Sched& S, const Epi& E) {
;     ...
;             PG8_LDB(B0, 1, 0); PG8_SCHED; PG8_LDA(At, 1, 0); PG8_STAGE(PG8_SA(0, 1), a2 + hstepA, voffA);
;             PG8_WAIT_L(8); PG8_BAR; PG8_WAIT_L(0); PG8_MMA(0, 0, At, B0); PG8_BAR; PG8_SCHED;
;             PG8_LDB(B1, 1, 1); PG8_STAGE(PG8_SB(1, 0), b3, voffB);
;             PG8_BAR; PG8_WAIT_L(0); PG8_MMA(0, 1, At, B1); PG8_BAR;
	s_add_i32 s70, 0, 0x18000
	v_add_u32_e32 v144, s70, v145
	ds_read_b128 v[152:155], v144
	ds_read_b128 v[156:159], v144 offset:1024
	ds_read_b128 v[160:163], v144 offset:2048
	ds_read_b128 v[164:167], v144 offset:3072
	s_add_u32 s68, s68, s6
	s_addc_u32 s69, s69, s7
	s_mov_b32 m0, s58
	v_lshl_add_u64 v[204:205], s[68:69], 0, v[130:131]
	ds_read_b128 v[168:171], v151 offset:32768
	ds_read_b128 v[172:175], v151 offset:33792
	ds_read_b128 v[176:179], v151 offset:34816
	ds_read_b128 v[180:183], v151 offset:35840
	ds_read_b128 v[184:187], v151 offset:36864
	ds_read_b128 v[188:191], v151 offset:37888
	ds_read_b128 v[196:199], v151 offset:38912
	ds_read_b128 v[200:203], v151 offset:39936
	global_load_lds_dwordx4 v[204:205], off
	v_lshl_add_u64 v[204:205], s[68:69], 0, v[132:133]
	s_mov_b32 m0, s72
	s_nop 0
	global_load_lds_dwordx4 v[204:205], off
	s_add_i32 s68, 0, 0x1c000
	v_add_u32_e32 v144, s68, v145
	ds_read_b128 v[204:207], v144
	ds_read_b128 v[208:211], v144 offset:1024
	ds_read_b128 v[212:215], v144 offset:2048
	ds_read_b128 v[234:237], v144 offset:3072
	s_waitcnt vmcnt(8)
	s_waitcnt lgkmcnt(0)
	v_mfma_f32_16x16x32_bf16 v[126:129], v[152:155], v[168:171], v[126:129]
	v_mfma_f32_16x16x32_bf16 v[122:125], v[160:163], v[168:171], v[122:125]
	v_mfma_f32_16x16x32_bf16 v[110:113], v[152:155], v[176:179], v[110:113]
	v_mfma_f32_16x16x32_bf16 v[106:109], v[160:163], v[176:179], v[106:109]
	s_barrier
	s_setprio 1
	v_mfma_f32_16x16x32_bf16 v[94:97], v[152:155], v[184:187], v[94:97]
	v_mfma_f32_16x16x32_bf16 v[90:93], v[160:163], v[184:187], v[90:93]
	v_mfma_f32_16x16x32_bf16 v[78:81], v[152:155], v[196:199], v[78:81]
	v_mfma_f32_16x16x32_bf16 v[74:77], v[160:163], v[196:199], v[74:77]
	v_mfma_f32_16x16x32_bf16 v[126:129], v[156:159], v[172:175], v[126:129]
	v_mfma_f32_16x16x32_bf16 v[122:125], v[164:167], v[172:175], v[122:125]
	v_mfma_f32_16x16x32_bf16 v[110:113], v[156:159], v[180:183], v[110:113]
	v_mfma_f32_16x16x32_bf16 v[106:109], v[164:167], v[180:183], v[106:109]
	v_mfma_f32_16x16x32_bf16 v[94:97], v[156:159], v[188:191], v[94:97]
	v_mfma_f32_16x16x32_bf16 v[90:93], v[164:167], v[188:191], v[90:93]
	v_mfma_f32_16x16x32_bf16 v[78:81], v[156:159], v[200:203], v[78:81]
	v_mfma_f32_16x16x32_bf16 v[74:77], v[164:167], v[200:203], v[74:77]
	v_mfma_f32_16x16x32_bf16 v[118:121], v[204:207], v[168:171], v[118:121]
	v_mfma_f32_16x16x32_bf16 v[114:117], v[212:215], v[168:171], v[114:117]
	v_mfma_f32_16x16x32_bf16 v[102:105], v[204:207], v[176:179], v[102:105]
	v_mfma_f32_16x16x32_bf16 v[98:101], v[212:215], v[176:179], v[98:101]
	v_mfma_f32_16x16x32_bf16 v[86:89], v[204:207], v[184:187], v[86:89]
	v_mfma_f32_16x16x32_bf16 v[82:85], v[212:215], v[184:187], v[82:85]
	v_mfma_f32_16x16x32_bf16 v[70:73], v[204:207], v[196:199], v[70:73]
	v_mfma_f32_16x16x32_bf16 v[66:69], v[212:215], v[196:199], v[66:69]
	v_mfma_f32_16x16x32_bf16 v[118:121], v[208:211], v[172:175], v[118:121]
	v_mfma_f32_16x16x32_bf16 v[114:117], v[234:237], v[172:175], v[114:117]
	v_mfma_f32_16x16x32_bf16 v[102:105], v[208:211], v[180:183], v[102:105]
	v_mfma_f32_16x16x32_bf16 v[98:101], v[234:237], v[180:183], v[98:101]
	v_mfma_f32_16x16x32_bf16 v[86:89], v[208:211], v[188:191], v[86:89]
	v_mfma_f32_16x16x32_bf16 v[82:85], v[234:237], v[188:191], v[82:85]
	v_mfma_f32_16x16x32_bf16 v[70:73], v[208:211], v[200:203], v[70:73]
	v_mfma_f32_16x16x32_bf16 v[66:69], v[234:237], v[200:203], v[66:69]
	s_setprio 0
	s_barrier
; #define PG8_STAGE(bufoff, gbase, voff) do { _Pragma("unroll") for (int _i = 0; _i < 2; ++_i) \
;         __builtin_amdgcn_global_load_lds((const unsigned*)((const char*)(gbase) + (voff)[_i]), (LAS unsigned*)(lds + (bufoff) + ldsw + _i * 8192), 16, 0, 0); } while (0)
; #define PG8_LDA(dst, b, h) do { _Pragma("unroll") for (int m = 0; m < 4; ++m) _Pragma("unroll") for (int k = 0; k < 2; ++k) dst[m][k] = *(const LAS bf16x8*)(lds + PG8_SA(b, h) + aoff + m * 2048 + k * 1024); } while (0)
; #define PG8_MMA(ai, bj, At, Bt) do { __builtin_amdgcn_s_setprio(1); _Pragma("unroll") for (int m = 0; m < 4; ++m) _Pragma("unroll") for (int n = 0; n < 2; ++n) _Pragma("unroll") for (int k = 0; k < 2; ++k) \
;         acc[ai][bj][m][n] = __builtin_amdgcn_mfma_f32_16x16x32_bf16(Bt[n][k], At[m][k], acc[ai][bj][m][n], 0, 0, 0); __builtin_amdgcn_s_setprio(0); } while (0)
; #define PG8_WAIT_V(n) asm volatile("s_waitcnt vmcnt(" #n ")" ::: "memory")
; #define PG8_WAIT_L(n) asm volatile("s_waitcnt lgkmcnt(" #n ")" ::: "memory")
; #define PG8_BAR __builtin_amdgcn_s_barrier()
; #define PG8_SCHED __builtin_amdgcn_sched_barrier(0)
; template <class Epi>
; __device__ __forceinline__ void gemm_phase(LAS unsigned char* lds, const Gemm g, const Sched& S, const Epi& E) {
;     ...
;             PG8_LDA(At, 1, 1); PG8_STAGE(PG8_SA(1, 0), a3, voffA);
;             PG8_BAR; PG8_WAIT_L(0); PG8_MMA(1, 0, At, B0); PG8_BAR; PG8_SCHED;
;             PG8_STAGE(PG8_SB(1, 1), b3 + hstepB, voffB);
;             PG8_WAIT_V(6); PG8_BAR; PG8_MMA(1, 1, At, B1); PG8_BAR;
;         }
;         E(acc, cur, wr, wc, fr, fq, pre);
;         if (!has_next) break;
	s_add_i32 s69, s70, s51
	v_lshl_add_u64 v[192:193], v[192:193], 0, s[60:61]
	s_mov_b32 m0, s69
	s_nop 0
	global_load_lds_dwordx4 v[192:193], off
	v_lshl_add_u64 v[192:193], v[216:217], 0, s[60:61]
	s_add_i32 m0, s69, 0x2000
	s_nop 0
	global_load_lds_dwordx4 v[192:193], off
	s_mov_b32 m0, s75
	v_lshl_add_u64 v[192:193], v[222:223], 0, s[60:61]
	ds_read_b128 v[168:171], v151 offset:49152
	ds_read_b128 v[172:175], v151 offset:50176
	ds_read_b128 v[176:179], v151 offset:51200
	ds_read_b128 v[180:183], v151 offset:52224
	ds_read_b128 v[184:187], v151 offset:53248
	ds_read_b128 v[188:191], v151 offset:54272
	ds_read_b128 v[196:199], v151 offset:55296
	ds_read_b128 v[200:203], v151 offset:56320
	global_load_lds_dwordx4 v[192:193], off
	v_lshl_add_u64 v[192:193], v[224:225], 0, s[60:61]
	s_mov_b32 m0, s76
	s_nop 0
	global_load_lds_dwordx4 v[192:193], off
	s_add_i32 s68, s68, s51
	v_lshl_add_u64 v[192:193], v[226:227], 0, s[60:61]
	s_mov_b32 m0, s68
	s_nop 0
	global_load_lds_dwordx4 v[192:193], off
	v_lshl_add_u64 v[192:193], v[228:229], 0, s[60:61]
	s_add_i32 m0, s68, 0x2000
	s_nop 0
	global_load_lds_dwordx4 v[192:193], off
	s_waitcnt vmcnt(8)
	s_waitcnt lgkmcnt(0)
	v_mfma_f32_16x16x32_bf16 v[62:65], v[152:155], v[168:171], v[62:65]
	v_mfma_f32_16x16x32_bf16 v[58:61], v[160:163], v[168:171], v[58:61]
	v_mfma_f32_16x16x32_bf16 v[46:49], v[152:155], v[176:179], v[46:49]
	v_mfma_f32_16x16x32_bf16 v[42:45], v[160:163], v[176:179], v[42:45]
	s_barrier
	s_setprio 1
	v_mfma_f32_16x16x32_bf16 v[30:33], v[152:155], v[184:187], v[30:33]
	v_mfma_f32_16x16x32_bf16 v[26:29], v[160:163], v[184:187], v[26:29]
	v_mfma_f32_16x16x32_bf16 v[14:17], v[152:155], v[196:199], v[14:17]
	v_mfma_f32_16x16x32_bf16 v[10:13], v[160:163], v[196:199], v[10:13]
	v_mfma_f32_16x16x32_bf16 v[62:65], v[156:159], v[172:175], v[62:65]
	v_mfma_f32_16x16x32_bf16 v[58:61], v[164:167], v[172:175], v[58:61]
	v_mfma_f32_16x16x32_bf16 v[46:49], v[156:159], v[180:183], v[46:49]
	v_mfma_f32_16x16x32_bf16 v[42:45], v[164:167], v[180:183], v[42:45]
	v_mfma_f32_16x16x32_bf16 v[30:33], v[156:159], v[188:191], v[30:33]
	v_mfma_f32_16x16x32_bf16 v[26:29], v[164:167], v[188:191], v[26:29]
	v_mfma_f32_16x16x32_bf16 v[14:17], v[156:159], v[200:203], v[14:17]
	v_mfma_f32_16x16x32_bf16 v[10:13], v[164:167], v[200:203], v[10:13]
	v_mfma_f32_16x16x32_bf16 v[54:57], v[204:207], v[168:171], v[54:57]
	v_mfma_f32_16x16x32_bf16 v[50:53], v[212:215], v[168:171], v[50:53]
	v_mfma_f32_16x16x32_bf16 v[38:41], v[204:207], v[176:179], v[38:41]
	v_mfma_f32_16x16x32_bf16 v[34:37], v[212:215], v[176:179], v[34:37]
	v_mfma_f32_16x16x32_bf16 v[22:25], v[204:207], v[184:187], v[22:25]
	v_mfma_f32_16x16x32_bf16 v[18:21], v[212:215], v[184:187], v[18:21]
	v_mfma_f32_16x16x32_bf16 v[6:9], v[204:207], v[196:199], v[6:9]
	v_mfma_f32_16x16x32_bf16 v[2:5], v[212:215], v[196:199], v[2:5]
	v_mfma_f32_16x16x32_bf16 v[54:57], v[208:211], v[172:175], v[54:57]
	v_mfma_f32_16x16x32_bf16 v[50:53], v[234:237], v[172:175], v[50:53]
	v_mfma_f32_16x16x32_bf16 v[38:41], v[208:211], v[180:183], v[38:41]
	v_mfma_f32_16x16x32_bf16 v[34:37], v[234:237], v[180:183], v[34:37]
	v_mfma_f32_16x16x32_bf16 v[22:25], v[208:211], v[188:191], v[22:25]
	v_mfma_f32_16x16x32_bf16 v[18:21], v[234:237], v[188:191], v[18:21]
	v_mfma_f32_16x16x32_bf16 v[6:9], v[208:211], v[200:203], v[6:9]
	v_mfma_f32_16x16x32_bf16 v[2:5], v[234:237], v[200:203], v[2:5]
	s_setprio 0
	s_add_u32 s4, s4, 0x100
	s_addc_u32 s5, s5, 0
	s_add_u32 s84, s84, 0x100
	s_addc_u32 s85, s85, 0
	s_cmp_ge_u32 s86, s73
	s_mov_b32 s68, s86
	s_barrier
	s_cbranch_scc0 .LBB0_825
	v_readfirstlane_b32 s98, v219
	s_nop 1
	s_bitcmp1_b32 s98, 8
	s_cbranch_scc1 .Lresync_x_825_p
	s_barrier
	s_branch .Lresync_x_825

; #define PG8_WAIT_V(n) asm volatile("s_waitcnt vmcnt(" #n ")" ::: "memory")
; #define PG8_BAR __builtin_amdgcn_s_barrier()
; template <class Epi>
; __device__ __forceinline__ void gemm_phase(LAS unsigned char* lds, const Gemm g, const Sched& S, const Epi& E) {
;     ...
;     PG8_WAIT_V(0);
;     if (wr == 0) PG8_BAR;
;     PG8_BAR;
.LBB0_828:
	s_waitcnt vmcnt(0)
	s_setprio 0
	s_cmpk_gt_u32 s2, 0xff
	s_cbranch_scc1 .LBB0_830
